# GEMM loops: mid-block s_setprio 0/1 pairs removed (32 MFMAs under one priority raise)
# speedup vs baseline: 1.0038x; 1.0038x over previous
; #define PG8_STAGE(bufoff, gbase, voff) do { _Pragma("unroll") for (int _i = 0; _i < 2; ++_i) \
;         __builtin_amdgcn_global_load_lds((const unsigned*)((const char*)(gbase) + (voff)[_i]), (PG8_LAS unsigned*)(lds + (bufoff) + ldsw + _i * 8192), 16, 0, 0); } while (0)
; #define PG8_LDA(dst, b, h) do { _Pragma("unroll") for (int m = 0; m < 4; ++m) _Pragma("unroll") for (int k = 0; k < 2; ++k) dst[m][k] = *(const PG8_LAS bf16x8*)(lds + PG8_SA(b, h) + aoff + m * 2048 + k * 1024); } while (0)
; #define PG8_LDB(dst, b, h) do { _Pragma("unroll") for (int n = 0; n < 2; ++n) _Pragma("unroll") for (int k = 0; k < 2; ++k) dst[n][k] = *(const PG8_LAS bf16x8*)(lds + PG8_SB(b, h) + boff + n * 2048 + k * 1024); } while (0)
; #define PG8_MMA(ai, bj, At, Bt) do { __builtin_amdgcn_s_setprio(1); _Pragma("unroll") for (int m = 0; m < 4; ++m) _Pragma("unroll") for (int n = 0; n < 2; ++n) _Pragma("unroll") for (int k = 0; k < 2; ++k) \
;         acc[ai][bj][m][n] = __builtin_amdgcn_mfma_f32_16x16x32_bf16(Bt[n][k], At[m][k], acc[ai][bj][m][n], 0, 0, 0); __builtin_amdgcn_s_setprio(0); } while (0)
; #define PG8_WAIT_V(n) asm volatile("s_waitcnt vmcnt(" #n ")" ::: "memory")
; #define PG8_WAIT_L(n) asm volatile("s_waitcnt lgkmcnt(" #n ")" ::: "memory")
; template <class Epi, class Sched, bool ALIGN_EPI = false, bool SP2 = false>
; __device__ __forceinline__ void gemm_phase(PG8_LAS unsigned char* lds, const Gemm g, const Sched& S, const Epi& E) {
;     ...
;             const bool last = (t == nt - 2);
;             const char* a1 = cA + (size_t)(t + 1) * kstep;
;             const char* a2 = last ? nA : cA + (size_t)(t + 2) * kstep; const char* b2 = last ? nB : cB + (size_t)(t + 2) * kstep;
;             const char* a3 = a2 + kstep; const char* b3 = b2 + kstep;
;             if (last && has_next) S.a_ready(nxt);
;             if constexpr (SP2) {
;             PG8_LDB(B0, 0, 0); PG8_LDB(B1, 0, 1); PG8_SCHED; PG8_LDA(At, 0, 0); PG8_STAGE(PG8_SA(1, 1), a1 + hstep, voffA);
;             PG8_WAIT_V(8); PG8_WAIT_L(0); PG8_BAR; PG8_MMA(0, 0, At, B0); PG8_MMA(0, 1, At, B1); PG8_BAR; PG8_SCHED;
;             PG8_LDA(At, 0, 1); PG8_STAGE(PG8_SB(0, 0), b2, voffB); PG8_STAGE(PG8_SB(0, 1), b2 + hstep, voffB); PG8_STAGE(PG8_SA(0, 0), a2, voffA);
;             PG8_WAIT_V(8); PG8_WAIT_L(0); PG8_BAR; PG8_MMA(1, 0, At, B0); PG8_MMA(1, 1, At, B1); PG8_BAR; PG8_SCHED;
.LBB0_452:
	ds_read_b128 v[144:147], v153
	ds_read_b128 v[158:161], v153 offset:1024
	ds_read_b128 v[162:165], v153 offset:2048
	ds_read_b128 v[166:169], v153 offset:3072
	ds_read_b128 v[170:173], v154
	ds_read_b128 v[174:177], v154 offset:1024
	ds_read_b128 v[178:181], v154 offset:2048
	ds_read_b128 v[182:185], v154 offset:3072
	s_add_u32 s22, s20, 0xfffc0080
	s_addc_u32 s23, s21, -1
	s_cmp_eq_u32 s45, 12
	s_cselect_b32 s25, s15, s23
	s_cselect_b32 s24, s41, s22
	s_cselect_b32 s23, s13, s44
	s_cselect_b32 s22, s42, s43
	v_lshl_add_u64 v[148:149], s[20:21], 0, v[136:137]
	s_add_i32 m0, s28, 0xc000
	ds_read_b128 v[186:189], v155
	ds_read_b128 v[190:193], v155 offset:1024
	ds_read_b128 v[194:197], v155 offset:2048
	ds_read_b128 v[202:205], v155 offset:3072
	ds_read_b128 v[206:209], v155 offset:4096
	ds_read_b128 v[210:213], v155 offset:5120
	ds_read_b128 v[214:217], v155 offset:6144
	ds_read_b128 v[218:221], v155 offset:7168
	global_load_lds_dwordx4 v[148:149], off
	v_lshl_add_u64 v[148:149], s[20:21], 0, v[138:139]
	s_add_i32 m0, s28, 0xe000
	s_nop 0
	global_load_lds_dwordx4 v[148:149], off
	s_waitcnt vmcnt(8)
	s_waitcnt lgkmcnt(0)
	s_barrier
	s_setprio 1
	s_waitcnt lgkmcnt(0)
	v_mfma_f32_16x16x32_bf16 v[124:127], v[144:147], v[186:189], v[124:127]
	v_mfma_f32_16x16x32_bf16 v[120:123], v[162:165], v[186:189], v[120:123]
	v_mfma_f32_16x16x32_bf16 v[116:119], v[144:147], v[194:197], v[116:119]
	v_mfma_f32_16x16x32_bf16 v[104:107], v[162:165], v[194:197], v[104:107]
	v_mfma_f32_16x16x32_bf16 v[92:95], v[144:147], v[206:209], v[92:95]
	v_mfma_f32_16x16x32_bf16 v[88:91], v[162:165], v[206:209], v[88:91]
	v_mfma_f32_16x16x32_bf16 v[76:79], v[144:147], v[214:217], v[76:79]
	v_mfma_f32_16x16x32_bf16 v[72:75], v[162:165], v[214:217], v[72:75]
	v_mfma_f32_16x16x32_bf16 v[124:127], v[158:161], v[190:193], v[124:127]
	v_mfma_f32_16x16x32_bf16 v[120:123], v[166:169], v[190:193], v[120:123]
	v_mfma_f32_16x16x32_bf16 v[116:119], v[158:161], v[202:205], v[116:119]
	v_mfma_f32_16x16x32_bf16 v[104:107], v[166:169], v[202:205], v[104:107]
	v_mfma_f32_16x16x32_bf16 v[92:95], v[158:161], v[210:213], v[92:95]
	v_mfma_f32_16x16x32_bf16 v[88:91], v[166:169], v[210:213], v[88:91]
	v_mfma_f32_16x16x32_bf16 v[76:79], v[158:161], v[218:221], v[76:79]
	v_mfma_f32_16x16x32_bf16 v[72:75], v[166:169], v[218:221], v[72:75]
	v_mfma_f32_16x16x32_bf16 v[112:115], v[170:173], v[186:189], v[112:115]
	v_mfma_f32_16x16x32_bf16 v[108:111], v[178:181], v[186:189], v[108:111]
	v_mfma_f32_16x16x32_bf16 v[100:103], v[170:173], v[194:197], v[100:103]
	v_mfma_f32_16x16x32_bf16 v[96:99], v[178:181], v[194:197], v[96:99]
	v_mfma_f32_16x16x32_bf16 v[84:87], v[170:173], v[206:209], v[84:87]
	v_mfma_f32_16x16x32_bf16 v[80:83], v[178:181], v[206:209], v[80:83]
	v_mfma_f32_16x16x32_bf16 v[68:71], v[170:173], v[214:217], v[68:71]
	v_mfma_f32_16x16x32_bf16 v[64:67], v[178:181], v[214:217], v[64:67]
	v_mfma_f32_16x16x32_bf16 v[112:115], v[174:177], v[190:193], v[112:115]
	v_mfma_f32_16x16x32_bf16 v[108:111], v[182:185], v[190:193], v[108:111]
	v_mfma_f32_16x16x32_bf16 v[100:103], v[174:177], v[202:205], v[100:103]
	v_mfma_f32_16x16x32_bf16 v[96:99], v[182:185], v[202:205], v[96:99]
	v_mfma_f32_16x16x32_bf16 v[84:87], v[174:177], v[210:213], v[84:87]
	v_mfma_f32_16x16x32_bf16 v[80:83], v[182:185], v[210:213], v[80:83]
	v_mfma_f32_16x16x32_bf16 v[68:71], v[174:177], v[218:221], v[68:71]
	v_mfma_f32_16x16x32_bf16 v[64:67], v[182:185], v[218:221], v[64:67]
	s_setprio 0
	s_barrier
	s_add_i32 s46, s37, s26
	v_lshl_add_u64 v[148:149], s[22:23], 0, v[132:133]
	s_mov_b32 m0, s46
	ds_read_b128 v[186:189], v155 offset:16384
	ds_read_b128 v[190:193], v155 offset:17408
	ds_read_b128 v[194:197], v155 offset:18432
	ds_read_b128 v[202:205], v155 offset:19456
	ds_read_b128 v[206:209], v155 offset:20480
	ds_read_b128 v[210:213], v155 offset:21504
	ds_read_b128 v[214:217], v155 offset:22528
	ds_read_b128 v[218:221], v155 offset:23552
	global_load_lds_dwordx4 v[148:149], off
	s_add_i32 m0, s46, 0x2000
	s_add_u32 s46, s22, 0x40000
	v_lshl_add_u64 v[198:199], s[22:23], 0, v[128:129]
	s_addc_u32 s47, s23, 0
	s_add_i32 s48, s38, s26
	global_load_lds_dwordx4 v[198:199], off
	v_lshl_add_u64 v[222:223], s[46:47], 0, v[132:133]
	s_mov_b32 m0, s48
	v_lshl_add_u64 v[224:225], s[24:25], 0, v[130:131]
	global_load_lds_dwordx4 v[222:223], off
	v_lshl_add_u64 v[222:223], s[46:47], 0, v[128:129]
	s_add_i32 m0, s48, 0x2000
	s_nop 0
	global_load_lds_dwordx4 v[222:223], off
	v_lshl_add_u64 v[222:223], s[24:25], 0, v[134:135]
	s_mov_b32 m0, s28
	s_nop 0
	global_load_lds_dwordx4 v[222:223], off
	s_mov_b32 m0, s29
	s_nop 0
	global_load_lds_dwordx4 v[224:225], off
	s_waitcnt vmcnt(8)
	s_waitcnt lgkmcnt(0)
	s_barrier
; #define PG8_STAGE(bufoff, gbase, voff) do { _Pragma("unroll") for (int _i = 0; _i < 2; ++_i) \
;         __builtin_amdgcn_global_load_lds((const unsigned*)((const char*)(gbase) + (voff)[_i]), (PG8_LAS unsigned*)(lds + (bufoff) + ldsw + _i * 8192), 16, 0, 0); } while (0)
; #define PG8_LDA(dst, b, h) do { _Pragma("unroll") for (int m = 0; m < 4; ++m) _Pragma("unroll") for (int k = 0; k < 2; ++k) dst[m][k] = *(const PG8_LAS bf16x8*)(lds + PG8_SA(b, h) + aoff + m * 2048 + k * 1024); } while (0)
; #define PG8_LDB(dst, b, h) do { _Pragma("unroll") for (int n = 0; n < 2; ++n) _Pragma("unroll") for (int k = 0; k < 2; ++k) dst[n][k] = *(const PG8_LAS bf16x8*)(lds + PG8_SB(b, h) + boff + n * 2048 + k * 1024); } while (0)
; #define PG8_MMA(ai, bj, At, Bt) do { __builtin_amdgcn_s_setprio(1); _Pragma("unroll") for (int m = 0; m < 4; ++m) _Pragma("unroll") for (int n = 0; n < 2; ++n) _Pragma("unroll") for (int k = 0; k < 2; ++k) \
;         acc[ai][bj][m][n] = __builtin_amdgcn_mfma_f32_16x16x32_bf16(Bt[n][k], At[m][k], acc[ai][bj][m][n], 0, 0, 0); __builtin_amdgcn_s_setprio(0); } while (0)
; #define PG8_WAIT_V(n) asm volatile("s_waitcnt vmcnt(" #n ")" ::: "memory")
; #define PG8_WAIT_L(n) asm volatile("s_waitcnt lgkmcnt(" #n ")" ::: "memory")
; #define PG8_BAR __builtin_amdgcn_s_barrier()
; #define PG8_SCHED __builtin_amdgcn_sched_barrier(0)
; template <class Epi, class Sched, bool ALIGN_EPI = false, bool SP2 = false>
; __device__ __forceinline__ void gemm_phase(PG8_LAS unsigned char* lds, const Gemm g, const Sched& S, const Epi& E) {
;     ...
;             PG8_LDA(At, 0, 1); PG8_STAGE(PG8_SB(0, 0), b2, voffB); PG8_STAGE(PG8_SB(0, 1), b2 + hstep, voffB); PG8_STAGE(PG8_SA(0, 0), a2, voffA);
;             PG8_WAIT_V(8); PG8_WAIT_L(0); PG8_BAR; PG8_MMA(1, 0, At, B0); PG8_MMA(1, 1, At, B1); PG8_BAR; PG8_SCHED;
;             PG8_LDB(B0, 1, 0); PG8_LDB(B1, 1, 1); PG8_SCHED; PG8_LDA(At, 1, 0); PG8_STAGE(PG8_SA(0, 1), a2 + hstep, voffA);
;             PG8_WAIT_V(8); PG8_WAIT_L(0); PG8_BAR; PG8_MMA(0, 0, At, B0); PG8_MMA(0, 1, At, B1); PG8_BAR; PG8_SCHED;
	s_setprio 1
	s_waitcnt lgkmcnt(0)
	v_mfma_f32_16x16x32_bf16 v[60:63], v[144:147], v[186:189], v[60:63]
	v_mfma_f32_16x16x32_bf16 v[56:59], v[162:165], v[186:189], v[56:59]
	v_mfma_f32_16x16x32_bf16 v[44:47], v[144:147], v[194:197], v[44:47]
	v_mfma_f32_16x16x32_bf16 v[40:43], v[162:165], v[194:197], v[40:43]
	v_mfma_f32_16x16x32_bf16 v[28:31], v[144:147], v[206:209], v[28:31]
	v_mfma_f32_16x16x32_bf16 v[24:27], v[162:165], v[206:209], v[24:27]
	v_mfma_f32_16x16x32_bf16 v[12:15], v[144:147], v[214:217], v[12:15]
	v_mfma_f32_16x16x32_bf16 v[8:11], v[162:165], v[214:217], v[8:11]
	v_mfma_f32_16x16x32_bf16 v[60:63], v[158:161], v[190:193], v[60:63]
	v_mfma_f32_16x16x32_bf16 v[56:59], v[166:169], v[190:193], v[56:59]
	v_mfma_f32_16x16x32_bf16 v[44:47], v[158:161], v[202:205], v[44:47]
	v_mfma_f32_16x16x32_bf16 v[40:43], v[166:169], v[202:205], v[40:43]
	v_mfma_f32_16x16x32_bf16 v[28:31], v[158:161], v[210:213], v[28:31]
	v_mfma_f32_16x16x32_bf16 v[24:27], v[166:169], v[210:213], v[24:27]
	v_mfma_f32_16x16x32_bf16 v[12:15], v[158:161], v[218:221], v[12:15]
	v_mfma_f32_16x16x32_bf16 v[8:11], v[166:169], v[218:221], v[8:11]
	v_mfma_f32_16x16x32_bf16 v[52:55], v[170:173], v[186:189], v[52:55]
	v_mfma_f32_16x16x32_bf16 v[48:51], v[178:181], v[186:189], v[48:51]
	v_mfma_f32_16x16x32_bf16 v[36:39], v[170:173], v[194:197], v[36:39]
	v_mfma_f32_16x16x32_bf16 v[32:35], v[178:181], v[194:197], v[32:35]
	v_mfma_f32_16x16x32_bf16 v[20:23], v[170:173], v[206:209], v[20:23]
	v_mfma_f32_16x16x32_bf16 v[16:19], v[178:181], v[206:209], v[16:19]
	v_mfma_f32_16x16x32_bf16 v[4:7], v[170:173], v[214:217], v[4:7]
	v_mfma_f32_16x16x32_bf16 v[0:3], v[178:181], v[214:217], v[0:3]
	v_mfma_f32_16x16x32_bf16 v[52:55], v[174:177], v[190:193], v[52:55]
	v_mfma_f32_16x16x32_bf16 v[48:51], v[182:185], v[190:193], v[48:51]
	v_mfma_f32_16x16x32_bf16 v[36:39], v[174:177], v[202:205], v[36:39]
	v_mfma_f32_16x16x32_bf16 v[32:35], v[182:185], v[202:205], v[32:35]
	v_mfma_f32_16x16x32_bf16 v[20:23], v[174:177], v[210:213], v[20:23]
	v_mfma_f32_16x16x32_bf16 v[16:19], v[182:185], v[210:213], v[16:19]
	v_mfma_f32_16x16x32_bf16 v[4:7], v[174:177], v[218:221], v[4:7]
	v_mfma_f32_16x16x32_bf16 v[0:3], v[182:185], v[218:221], v[0:3]
	s_setprio 0
	s_barrier
	s_add_i32 s46, 0, 0x18000
	v_add_u32_e32 v157, s46, v151
	s_add_i32 s47, 0, 0x1c000
	ds_read_b128 v[144:147], v157
	ds_read_b128 v[158:161], v157 offset:1024
	ds_read_b128 v[162:165], v157 offset:2048
	ds_read_b128 v[166:169], v157 offset:3072
	v_add_u32_e32 v157, s47, v151
	ds_read_b128 v[170:173], v157
	ds_read_b128 v[174:177], v157 offset:1024
	ds_read_b128 v[178:181], v157 offset:2048
	ds_read_b128 v[182:185], v157 offset:3072
	s_add_u32 s24, s24, 0x40000
	s_addc_u32 s25, s25, 0
	s_mov_b32 m0, s30
	v_lshl_add_u64 v[226:227], s[24:25], 0, v[134:135]
	ds_read_b128 v[186:189], v155 offset:32768
	ds_read_b128 v[190:193], v155 offset:33792
	ds_read_b128 v[194:197], v155 offset:34816
	ds_read_b128 v[202:205], v155 offset:35840
	ds_read_b128 v[206:209], v155 offset:36864
	ds_read_b128 v[210:213], v155 offset:37888
	ds_read_b128 v[214:217], v155 offset:38912
	ds_read_b128 v[218:221], v155 offset:39936
	global_load_lds_dwordx4 v[226:227], off
	v_lshl_add_u64 v[226:227], s[24:25], 0, v[130:131]
	s_mov_b32 m0, s31
	s_nop 0
	global_load_lds_dwordx4 v[226:227], off
	s_waitcnt vmcnt(8)
	s_waitcnt lgkmcnt(0)
	s_barrier
	s_setprio 1
	s_waitcnt lgkmcnt(0)
	v_mfma_f32_16x16x32_bf16 v[124:127], v[144:147], v[186:189], v[124:127]
	v_mfma_f32_16x16x32_bf16 v[120:123], v[162:165], v[186:189], v[120:123]
	v_mfma_f32_16x16x32_bf16 v[116:119], v[144:147], v[194:197], v[116:119]
	v_mfma_f32_16x16x32_bf16 v[104:107], v[162:165], v[194:197], v[104:107]
	v_mfma_f32_16x16x32_bf16 v[92:95], v[144:147], v[206:209], v[92:95]
	v_mfma_f32_16x16x32_bf16 v[88:91], v[162:165], v[206:209], v[88:91]
	v_mfma_f32_16x16x32_bf16 v[76:79], v[144:147], v[214:217], v[76:79]
	v_mfma_f32_16x16x32_bf16 v[72:75], v[162:165], v[214:217], v[72:75]
	v_mfma_f32_16x16x32_bf16 v[124:127], v[158:161], v[190:193], v[124:127]
	v_mfma_f32_16x16x32_bf16 v[120:123], v[166:169], v[190:193], v[120:123]
	v_mfma_f32_16x16x32_bf16 v[116:119], v[158:161], v[202:205], v[116:119]
	v_mfma_f32_16x16x32_bf16 v[104:107], v[166:169], v[202:205], v[104:107]
	v_mfma_f32_16x16x32_bf16 v[92:95], v[158:161], v[210:213], v[92:95]
	v_mfma_f32_16x16x32_bf16 v[88:91], v[166:169], v[210:213], v[88:91]
	v_mfma_f32_16x16x32_bf16 v[76:79], v[158:161], v[218:221], v[76:79]
	v_mfma_f32_16x16x32_bf16 v[72:75], v[166:169], v[218:221], v[72:75]
	v_mfma_f32_16x16x32_bf16 v[112:115], v[170:173], v[186:189], v[112:115]
	v_mfma_f32_16x16x32_bf16 v[108:111], v[178:181], v[186:189], v[108:111]
	v_mfma_f32_16x16x32_bf16 v[100:103], v[170:173], v[194:197], v[100:103]
	v_mfma_f32_16x16x32_bf16 v[96:99], v[178:181], v[194:197], v[96:99]
	v_mfma_f32_16x16x32_bf16 v[84:87], v[170:173], v[206:209], v[84:87]
	v_mfma_f32_16x16x32_bf16 v[80:83], v[178:181], v[206:209], v[80:83]
	v_mfma_f32_16x16x32_bf16 v[68:71], v[170:173], v[214:217], v[68:71]
	v_mfma_f32_16x16x32_bf16 v[64:67], v[178:181], v[214:217], v[64:67]
	v_mfma_f32_16x16x32_bf16 v[112:115], v[174:177], v[190:193], v[112:115]
	v_mfma_f32_16x16x32_bf16 v[108:111], v[182:185], v[190:193], v[108:111]
	v_mfma_f32_16x16x32_bf16 v[100:103], v[174:177], v[202:205], v[100:103]
	v_mfma_f32_16x16x32_bf16 v[96:99], v[182:185], v[202:205], v[96:99]
	v_mfma_f32_16x16x32_bf16 v[84:87], v[174:177], v[210:213], v[84:87]
	v_mfma_f32_16x16x32_bf16 v[80:83], v[182:185], v[210:213], v[80:83]
	v_mfma_f32_16x16x32_bf16 v[68:71], v[174:177], v[218:221], v[68:71]
	v_mfma_f32_16x16x32_bf16 v[64:67], v[182:185], v[218:221], v[64:67]
	s_setprio 0
	s_barrier
; #define PG8_STAGE(bufoff, gbase, voff) do { _Pragma("unroll") for (int _i = 0; _i < 2; ++_i) \
;         __builtin_amdgcn_global_load_lds((const unsigned*)((const char*)(gbase) + (voff)[_i]), (PG8_LAS unsigned*)(lds + (bufoff) + ldsw + _i * 8192), 16, 0, 0); } while (0)
; #define PG8_LDA(dst, b, h) do { _Pragma("unroll") for (int m = 0; m < 4; ++m) _Pragma("unroll") for (int k = 0; k < 2; ++k) dst[m][k] = *(const PG8_LAS bf16x8*)(lds + PG8_SA(b, h) + aoff + m * 2048 + k * 1024); } while (0)
; #define PG8_MMA(ai, bj, At, Bt) do { __builtin_amdgcn_s_setprio(1); _Pragma("unroll") for (int m = 0; m < 4; ++m) _Pragma("unroll") for (int n = 0; n < 2; ++n) _Pragma("unroll") for (int k = 0; k < 2; ++k) \
;         acc[ai][bj][m][n] = __builtin_amdgcn_mfma_f32_16x16x32_bf16(Bt[n][k], At[m][k], acc[ai][bj][m][n], 0, 0, 0); __builtin_amdgcn_s_setprio(0); } while (0)
; #define PG8_WAIT_V(n) asm volatile("s_waitcnt vmcnt(" #n ")" ::: "memory")
; #define PG8_WAIT_L(n) asm volatile("s_waitcnt lgkmcnt(" #n ")" ::: "memory")
; #define PG8_BAR __builtin_amdgcn_s_barrier()
; #define PG8_SCHED __builtin_amdgcn_sched_barrier(0)
; template <class Epi, class Sched, bool ALIGN_EPI = false, bool SP2 = false>
; __device__ __forceinline__ void gemm_phase(PG8_LAS unsigned char* lds, const Gemm g, const Sched& S, const Epi& E) {
;     ...
;             PG8_LDA(At, 1, 1); PG8_STAGE(PG8_SB(1, 0), b3, voffB); PG8_STAGE(PG8_SB(1, 1), b3 + hstep, voffB); PG8_STAGE(PG8_SA(1, 0), a3, voffA);
;             PG8_WAIT_V(8); PG8_WAIT_L(0); PG8_BAR; PG8_MMA(1, 0, At, B0); PG8_MMA(1, 1, At, B1); PG8_BAR; PG8_SCHED;
;     ...
;         }
;         if constexpr (ALIGN_EPI) { if (wr == 0) PG8_BAR; }
	s_add_i32 s24, s46, s26
	v_lshl_add_u64 v[148:149], v[148:149], 0, s[4:5]
	s_mov_b32 m0, s24
	ds_read_b128 v[186:189], v155 offset:49152
	ds_read_b128 v[190:193], v155 offset:50176
	ds_read_b128 v[194:197], v155 offset:51200
	ds_read_b128 v[202:205], v155 offset:52224
	ds_read_b128 v[206:209], v155 offset:53248
	ds_read_b128 v[210:213], v155 offset:54272
	ds_read_b128 v[214:217], v155 offset:55296
	ds_read_b128 v[218:221], v155 offset:56320
	global_load_lds_dwordx4 v[148:149], off
	s_add_i32 m0, s24, 0x2000
	s_add_u32 s22, s22, 0x40080
	v_lshl_add_u64 v[148:149], v[198:199], 0, s[4:5]
	s_addc_u32 s23, s23, 0
	s_add_i32 s24, s47, s26
	global_load_lds_dwordx4 v[148:149], off
	v_lshl_add_u64 v[148:149], s[22:23], 0, v[132:133]
	s_mov_b32 m0, s24
	s_nop 0
	global_load_lds_dwordx4 v[148:149], off
	v_lshl_add_u64 v[148:149], s[22:23], 0, v[128:129]
	s_add_i32 m0, s24, 0x2000
	s_nop 0
	global_load_lds_dwordx4 v[148:149], off
	v_lshl_add_u64 v[148:149], v[222:223], 0, s[4:5]
	s_mov_b32 m0, s35
	s_nop 0
	global_load_lds_dwordx4 v[148:149], off
	v_lshl_add_u64 v[148:149], v[224:225], 0, s[4:5]
	s_mov_b32 m0, s36
	s_nop 0
	global_load_lds_dwordx4 v[148:149], off
	s_waitcnt vmcnt(8)
	s_waitcnt lgkmcnt(0)
	s_barrier
	s_setprio 1
	s_waitcnt lgkmcnt(0)
	v_mfma_f32_16x16x32_bf16 v[60:63], v[144:147], v[186:189], v[60:63]
	v_mfma_f32_16x16x32_bf16 v[56:59], v[162:165], v[186:189], v[56:59]
	v_mfma_f32_16x16x32_bf16 v[44:47], v[144:147], v[194:197], v[44:47]
	v_mfma_f32_16x16x32_bf16 v[40:43], v[162:165], v[194:197], v[40:43]
	v_mfma_f32_16x16x32_bf16 v[28:31], v[144:147], v[206:209], v[28:31]
	v_mfma_f32_16x16x32_bf16 v[24:27], v[162:165], v[206:209], v[24:27]
	v_mfma_f32_16x16x32_bf16 v[12:15], v[144:147], v[214:217], v[12:15]
	v_mfma_f32_16x16x32_bf16 v[8:11], v[162:165], v[214:217], v[8:11]
	v_mfma_f32_16x16x32_bf16 v[60:63], v[158:161], v[190:193], v[60:63]
	v_mfma_f32_16x16x32_bf16 v[56:59], v[166:169], v[190:193], v[56:59]
	v_mfma_f32_16x16x32_bf16 v[44:47], v[158:161], v[202:205], v[44:47]
	v_mfma_f32_16x16x32_bf16 v[40:43], v[166:169], v[202:205], v[40:43]
	v_mfma_f32_16x16x32_bf16 v[28:31], v[158:161], v[210:213], v[28:31]
	v_mfma_f32_16x16x32_bf16 v[24:27], v[166:169], v[210:213], v[24:27]
	v_mfma_f32_16x16x32_bf16 v[12:15], v[158:161], v[218:221], v[12:15]
	v_mfma_f32_16x16x32_bf16 v[8:11], v[166:169], v[218:221], v[8:11]
	v_mfma_f32_16x16x32_bf16 v[52:55], v[170:173], v[186:189], v[52:55]
	v_mfma_f32_16x16x32_bf16 v[48:51], v[178:181], v[186:189], v[48:51]
	v_mfma_f32_16x16x32_bf16 v[36:39], v[170:173], v[194:197], v[36:39]
	v_mfma_f32_16x16x32_bf16 v[32:35], v[178:181], v[194:197], v[32:35]
	v_mfma_f32_16x16x32_bf16 v[20:23], v[170:173], v[206:209], v[20:23]
	v_mfma_f32_16x16x32_bf16 v[16:19], v[178:181], v[206:209], v[16:19]
	v_mfma_f32_16x16x32_bf16 v[4:7], v[170:173], v[214:217], v[4:7]
	v_mfma_f32_16x16x32_bf16 v[0:3], v[178:181], v[214:217], v[0:3]
	v_mfma_f32_16x16x32_bf16 v[52:55], v[174:177], v[190:193], v[52:55]
	v_mfma_f32_16x16x32_bf16 v[48:51], v[182:185], v[190:193], v[48:51]
	v_mfma_f32_16x16x32_bf16 v[36:39], v[174:177], v[202:205], v[36:39]
	v_mfma_f32_16x16x32_bf16 v[32:35], v[182:185], v[202:205], v[32:35]
	v_mfma_f32_16x16x32_bf16 v[20:23], v[174:177], v[210:213], v[20:23]
	v_mfma_f32_16x16x32_bf16 v[16:19], v[182:185], v[210:213], v[16:19]
	v_mfma_f32_16x16x32_bf16 v[4:7], v[174:177], v[218:221], v[4:7]
	v_mfma_f32_16x16x32_bf16 v[0:3], v[182:185], v[218:221], v[0:3]
	s_setprio 0
	s_barrier
	s_add_i32 s45, s45, 2
	s_add_u32 s20, s20, 0x100
	s_addc_u32 s21, s21, 0
	s_add_u32 s43, s43, 0x100
	s_addc_u32 s44, s44, 0
	s_cmp_gt_u32 s45, 13
	s_cbranch_scc0 .LBB0_452
	s_and_b64 vcc, exec, s[10:11]
	s_cbranch_vccz .LBB0_455
	s_barrier

; #define PG8_STAGE(bufoff, gbase, voff) do { _Pragma("unroll") for (int _i = 0; _i < 2; ++_i) \
;         __builtin_amdgcn_global_load_lds((const unsigned*)((const char*)(gbase) + (voff)[_i]), (PG8_LAS unsigned*)(lds + (bufoff) + ldsw + _i * 8192), 16, 0, 0); } while (0)
; #define PG8_LDA(dst, b, h) do { _Pragma("unroll") for (int m = 0; m < 4; ++m) _Pragma("unroll") for (int k = 0; k < 2; ++k) dst[m][k] = *(const PG8_LAS bf16x8*)(lds + PG8_SA(b, h) + aoff + m * 2048 + k * 1024); } while (0)
; #define PG8_LDB(dst, b, h) do { _Pragma("unroll") for (int n = 0; n < 2; ++n) _Pragma("unroll") for (int k = 0; k < 2; ++k) dst[n][k] = *(const PG8_LAS bf16x8*)(lds + PG8_SB(b, h) + boff + n * 2048 + k * 1024); } while (0)
; #define PG8_MMA(ai, bj, At, Bt) do { __builtin_amdgcn_s_setprio(1); _Pragma("unroll") for (int m = 0; m < 4; ++m) _Pragma("unroll") for (int n = 0; n < 2; ++n) _Pragma("unroll") for (int k = 0; k < 2; ++k) \
;         acc[ai][bj][m][n] = __builtin_amdgcn_mfma_f32_16x16x32_bf16(Bt[n][k], At[m][k], acc[ai][bj][m][n], 0, 0, 0); __builtin_amdgcn_s_setprio(0); } while (0)
; #define PG8_WAIT_V(n) asm volatile("s_waitcnt vmcnt(" #n ")" ::: "memory")
; #define PG8_WAIT_L(n) asm volatile("s_waitcnt lgkmcnt(" #n ")" ::: "memory")
; template <class Epi, class Sched, bool ALIGN_EPI = false, bool SP2 = false>
; __device__ __forceinline__ void gemm_phase(PG8_LAS unsigned char* lds, const Gemm g, const Sched& S, const Epi& E) {
;     ...
;             const bool last = (t == nt - 2);
;             const char* a1 = cA + (size_t)(t + 1) * kstep;
;             const char* a2 = last ? nA : cA + (size_t)(t + 2) * kstep; const char* b2 = last ? nB : cB + (size_t)(t + 2) * kstep;
;             const char* a3 = a2 + kstep; const char* b3 = b2 + kstep;
;             if (last && has_next) S.a_ready(nxt);
;             if constexpr (SP2) {
;             PG8_LDB(B0, 0, 0); PG8_LDB(B1, 0, 1); PG8_SCHED; PG8_LDA(At, 0, 0); PG8_STAGE(PG8_SA(1, 1), a1 + hstep, voffA);
;             PG8_WAIT_V(8); PG8_WAIT_L(0); PG8_BAR; PG8_MMA(0, 0, At, B0); PG8_MMA(0, 1, At, B1); PG8_BAR; PG8_SCHED;
;             PG8_LDA(At, 0, 1); PG8_STAGE(PG8_SB(0, 0), b2, voffB); PG8_STAGE(PG8_SB(0, 1), b2 + hstep, voffB); PG8_STAGE(PG8_SA(0, 0), a2, voffA);
;             PG8_WAIT_V(8); PG8_WAIT_L(0); PG8_BAR; PG8_MMA(1, 0, At, B0); PG8_MMA(1, 1, At, B1); PG8_BAR; PG8_SCHED;
.LBB0_535:
	ds_read_b128 v[128:131], v189
	ds_read_b128 v[132:135], v189 offset:1024
	ds_read_b128 v[136:139], v189 offset:2048
	ds_read_b128 v[140:143], v189 offset:3072
	ds_read_b128 v[144:147], v190
	ds_read_b128 v[148:151], v190 offset:1024
	ds_read_b128 v[168:171], v190 offset:2048
	ds_read_b128 v[172:175], v190 offset:3072
	s_add_u32 s20, s18, 0x100
	s_addc_u32 s21, s19, 0
	s_cmp_eq_u32 s42, 40
	s_cselect_b32 s25, s13, s21
	s_cselect_b32 s24, s12, s20
	s_cselect_b32 s23, s17, s41
	s_cselect_b32 s22, s16, s40
	v_lshl_add_u64 v[184:185], s[18:19], 0, v[160:161]
	s_add_i32 m0, s7, 0xc000
	ds_read_b128 v[176:179], v191
	ds_read_b128 v[180:183], v191 offset:1024
	ds_read_b128 v[194:197], v191 offset:2048
	ds_read_b128 v[202:205], v191 offset:3072
	ds_read_b128 v[206:209], v191 offset:4096
	ds_read_b128 v[210:213], v191 offset:5120
	ds_read_b128 v[214:217], v191 offset:6144
	ds_read_b128 v[218:221], v191 offset:7168
	global_load_lds_dwordx4 v[184:185], off
	v_lshl_add_u64 v[184:185], s[18:19], 0, v[162:163]
	s_add_i32 m0, s7, 0xe000
	s_nop 0
	global_load_lds_dwordx4 v[184:185], off
	s_waitcnt vmcnt(8)
	s_waitcnt lgkmcnt(0)
	s_barrier
	s_setprio 1
	s_waitcnt lgkmcnt(0)
	v_mfma_f32_16x16x32_bf16 v[124:127], v[128:131], v[176:179], v[124:127]
	v_mfma_f32_16x16x32_bf16 v[120:123], v[136:139], v[176:179], v[120:123]
	v_mfma_f32_16x16x32_bf16 v[108:111], v[128:131], v[194:197], v[108:111]
	v_mfma_f32_16x16x32_bf16 v[104:107], v[136:139], v[194:197], v[104:107]
	v_mfma_f32_16x16x32_bf16 v[92:95], v[128:131], v[206:209], v[92:95]
	v_mfma_f32_16x16x32_bf16 v[88:91], v[136:139], v[206:209], v[88:91]
	v_mfma_f32_16x16x32_bf16 v[76:79], v[128:131], v[214:217], v[76:79]
	v_mfma_f32_16x16x32_bf16 v[72:75], v[136:139], v[214:217], v[72:75]
	v_mfma_f32_16x16x32_bf16 v[124:127], v[132:135], v[180:183], v[124:127]
	v_mfma_f32_16x16x32_bf16 v[120:123], v[140:143], v[180:183], v[120:123]
	v_mfma_f32_16x16x32_bf16 v[108:111], v[132:135], v[202:205], v[108:111]
	v_mfma_f32_16x16x32_bf16 v[104:107], v[140:143], v[202:205], v[104:107]
	v_mfma_f32_16x16x32_bf16 v[92:95], v[132:135], v[210:213], v[92:95]
	v_mfma_f32_16x16x32_bf16 v[88:91], v[140:143], v[210:213], v[88:91]
	v_mfma_f32_16x16x32_bf16 v[76:79], v[132:135], v[218:221], v[76:79]
	v_mfma_f32_16x16x32_bf16 v[72:75], v[140:143], v[218:221], v[72:75]
	v_mfma_f32_16x16x32_bf16 v[116:119], v[144:147], v[176:179], v[116:119]
	v_mfma_f32_16x16x32_bf16 v[112:115], v[168:171], v[176:179], v[112:115]
	v_mfma_f32_16x16x32_bf16 v[100:103], v[144:147], v[194:197], v[100:103]
	v_mfma_f32_16x16x32_bf16 v[96:99], v[168:171], v[194:197], v[96:99]
	v_mfma_f32_16x16x32_bf16 v[84:87], v[144:147], v[206:209], v[84:87]
	v_mfma_f32_16x16x32_bf16 v[80:83], v[168:171], v[206:209], v[80:83]
	v_mfma_f32_16x16x32_bf16 v[68:71], v[144:147], v[214:217], v[68:71]
	v_mfma_f32_16x16x32_bf16 v[64:67], v[168:171], v[214:217], v[64:67]
	v_mfma_f32_16x16x32_bf16 v[116:119], v[148:151], v[180:183], v[116:119]
	v_mfma_f32_16x16x32_bf16 v[112:115], v[172:175], v[180:183], v[112:115]
	v_mfma_f32_16x16x32_bf16 v[100:103], v[148:151], v[202:205], v[100:103]
	v_mfma_f32_16x16x32_bf16 v[96:99], v[172:175], v[202:205], v[96:99]
	v_mfma_f32_16x16x32_bf16 v[84:87], v[148:151], v[210:213], v[84:87]
	v_mfma_f32_16x16x32_bf16 v[80:83], v[172:175], v[210:213], v[80:83]
	v_mfma_f32_16x16x32_bf16 v[68:71], v[148:151], v[218:221], v[68:71]
	v_mfma_f32_16x16x32_bf16 v[64:67], v[172:175], v[218:221], v[64:67]
	s_setprio 0
	s_barrier
	s_add_i32 s18, s34, s6
	v_lshl_add_u64 v[184:185], s[22:23], 0, v[154:155]
	s_mov_b32 m0, s18
	ds_read_b128 v[176:179], v191 offset:16384
	ds_read_b128 v[180:183], v191 offset:17408
	ds_read_b128 v[194:197], v191 offset:18432
	ds_read_b128 v[202:205], v191 offset:19456
	ds_read_b128 v[206:209], v191 offset:20480
	ds_read_b128 v[210:213], v191 offset:21504
	ds_read_b128 v[214:217], v191 offset:22528
	ds_read_b128 v[218:221], v191 offset:23552
	global_load_lds_dwordx4 v[184:185], off
	s_add_i32 m0, s18, 0x2000
	s_add_u32 s18, s22, 0xb0000
	v_lshl_add_u64 v[198:199], s[22:23], 0, v[158:159]
	s_addc_u32 s19, s23, 0
	s_add_i32 s43, s35, s6
	global_load_lds_dwordx4 v[198:199], off
	v_lshl_add_u64 v[222:223], s[18:19], 0, v[154:155]
	s_mov_b32 m0, s43
	v_lshl_add_u64 v[224:225], s[24:25], 0, v[156:157]
	global_load_lds_dwordx4 v[222:223], off
	v_lshl_add_u64 v[222:223], s[18:19], 0, v[158:159]
	s_add_i32 m0, s43, 0x2000
	s_nop 0
	global_load_lds_dwordx4 v[222:223], off
	v_lshl_add_u64 v[222:223], s[24:25], 0, v[152:153]
	s_mov_b32 m0, s7
	s_nop 0
	global_load_lds_dwordx4 v[222:223], off
	s_mov_b32 m0, s26
	s_nop 0
	global_load_lds_dwordx4 v[224:225], off
	s_waitcnt vmcnt(8)
	s_waitcnt lgkmcnt(0)
	s_barrier
; #define PG8_STAGE(bufoff, gbase, voff) do { _Pragma("unroll") for (int _i = 0; _i < 2; ++_i) \
;         __builtin_amdgcn_global_load_lds((const unsigned*)((const char*)(gbase) + (voff)[_i]), (PG8_LAS unsigned*)(lds + (bufoff) + ldsw + _i * 8192), 16, 0, 0); } while (0)
; #define PG8_LDA(dst, b, h) do { _Pragma("unroll") for (int m = 0; m < 4; ++m) _Pragma("unroll") for (int k = 0; k < 2; ++k) dst[m][k] = *(const PG8_LAS bf16x8*)(lds + PG8_SA(b, h) + aoff + m * 2048 + k * 1024); } while (0)
; #define PG8_LDB(dst, b, h) do { _Pragma("unroll") for (int n = 0; n < 2; ++n) _Pragma("unroll") for (int k = 0; k < 2; ++k) dst[n][k] = *(const PG8_LAS bf16x8*)(lds + PG8_SB(b, h) + boff + n * 2048 + k * 1024); } while (0)
; #define PG8_MMA(ai, bj, At, Bt) do { __builtin_amdgcn_s_setprio(1); _Pragma("unroll") for (int m = 0; m < 4; ++m) _Pragma("unroll") for (int n = 0; n < 2; ++n) _Pragma("unroll") for (int k = 0; k < 2; ++k) \
;         acc[ai][bj][m][n] = __builtin_amdgcn_mfma_f32_16x16x32_bf16(Bt[n][k], At[m][k], acc[ai][bj][m][n], 0, 0, 0); __builtin_amdgcn_s_setprio(0); } while (0)
; #define PG8_WAIT_V(n) asm volatile("s_waitcnt vmcnt(" #n ")" ::: "memory")
; #define PG8_WAIT_L(n) asm volatile("s_waitcnt lgkmcnt(" #n ")" ::: "memory")
; #define PG8_BAR __builtin_amdgcn_s_barrier()
; #define PG8_SCHED __builtin_amdgcn_sched_barrier(0)
; template <class Epi, class Sched, bool ALIGN_EPI = false, bool SP2 = false>
; __device__ __forceinline__ void gemm_phase(PG8_LAS unsigned char* lds, const Gemm g, const Sched& S, const Epi& E) {
;     ...
;             PG8_LDA(At, 0, 1); PG8_STAGE(PG8_SB(0, 0), b2, voffB); PG8_STAGE(PG8_SB(0, 1), b2 + hstep, voffB); PG8_STAGE(PG8_SA(0, 0), a2, voffA);
;             PG8_WAIT_V(8); PG8_WAIT_L(0); PG8_BAR; PG8_MMA(1, 0, At, B0); PG8_MMA(1, 1, At, B1); PG8_BAR; PG8_SCHED;
;             PG8_LDB(B0, 1, 0); PG8_LDB(B1, 1, 1); PG8_SCHED; PG8_LDA(At, 1, 0); PG8_STAGE(PG8_SA(0, 1), a2 + hstep, voffA);
;             PG8_WAIT_V(8); PG8_WAIT_L(0); PG8_BAR; PG8_MMA(0, 0, At, B0); PG8_MMA(0, 1, At, B1); PG8_BAR; PG8_SCHED;
	s_setprio 1
	s_waitcnt lgkmcnt(0)
	v_mfma_f32_16x16x32_bf16 v[60:63], v[128:131], v[176:179], v[60:63]
	v_mfma_f32_16x16x32_bf16 v[56:59], v[136:139], v[176:179], v[56:59]
	v_mfma_f32_16x16x32_bf16 v[44:47], v[128:131], v[194:197], v[44:47]
	v_mfma_f32_16x16x32_bf16 v[40:43], v[136:139], v[194:197], v[40:43]
	v_mfma_f32_16x16x32_bf16 v[28:31], v[128:131], v[206:209], v[28:31]
	v_mfma_f32_16x16x32_bf16 v[24:27], v[136:139], v[206:209], v[24:27]
	v_mfma_f32_16x16x32_bf16 v[12:15], v[128:131], v[214:217], v[12:15]
	v_mfma_f32_16x16x32_bf16 v[8:11], v[136:139], v[214:217], v[8:11]
	v_mfma_f32_16x16x32_bf16 v[60:63], v[132:135], v[180:183], v[60:63]
	v_mfma_f32_16x16x32_bf16 v[56:59], v[140:143], v[180:183], v[56:59]
	v_mfma_f32_16x16x32_bf16 v[44:47], v[132:135], v[202:205], v[44:47]
	v_mfma_f32_16x16x32_bf16 v[40:43], v[140:143], v[202:205], v[40:43]
	v_mfma_f32_16x16x32_bf16 v[28:31], v[132:135], v[210:213], v[28:31]
	v_mfma_f32_16x16x32_bf16 v[24:27], v[140:143], v[210:213], v[24:27]
	v_mfma_f32_16x16x32_bf16 v[12:15], v[132:135], v[218:221], v[12:15]
	v_mfma_f32_16x16x32_bf16 v[8:11], v[140:143], v[218:221], v[8:11]
	v_mfma_f32_16x16x32_bf16 v[52:55], v[144:147], v[176:179], v[52:55]
	v_mfma_f32_16x16x32_bf16 v[48:51], v[168:171], v[176:179], v[48:51]
	v_mfma_f32_16x16x32_bf16 v[36:39], v[144:147], v[194:197], v[36:39]
	v_mfma_f32_16x16x32_bf16 v[32:35], v[168:171], v[194:197], v[32:35]
	v_mfma_f32_16x16x32_bf16 v[20:23], v[144:147], v[206:209], v[20:23]
	v_mfma_f32_16x16x32_bf16 v[16:19], v[168:171], v[206:209], v[16:19]
	v_mfma_f32_16x16x32_bf16 v[4:7], v[144:147], v[214:217], v[4:7]
	v_mfma_f32_16x16x32_bf16 v[0:3], v[168:171], v[214:217], v[0:3]
	v_mfma_f32_16x16x32_bf16 v[52:55], v[148:151], v[180:183], v[52:55]
	v_mfma_f32_16x16x32_bf16 v[48:51], v[172:175], v[180:183], v[48:51]
	v_mfma_f32_16x16x32_bf16 v[36:39], v[148:151], v[202:205], v[36:39]
	v_mfma_f32_16x16x32_bf16 v[32:35], v[172:175], v[202:205], v[32:35]
	v_mfma_f32_16x16x32_bf16 v[20:23], v[148:151], v[210:213], v[20:23]
	v_mfma_f32_16x16x32_bf16 v[16:19], v[172:175], v[210:213], v[16:19]
	v_mfma_f32_16x16x32_bf16 v[4:7], v[148:151], v[218:221], v[4:7]
	v_mfma_f32_16x16x32_bf16 v[0:3], v[172:175], v[218:221], v[0:3]
	s_setprio 0
	s_barrier
	s_add_i32 s43, 0, 0x18000
	s_add_i32 s44, 0, 0x1c000
	v_add_u32_e32 v140, s43, v187
	v_add_u32_e32 v172, s44, v187
	ds_read_b128 v[128:131], v140
	ds_read_b128 v[132:135], v140 offset:1024
	ds_read_b128 v[136:139], v140 offset:2048
	ds_read_b128 v[140:143], v140 offset:3072
	ds_read_b128 v[144:147], v172
	ds_read_b128 v[148:151], v172 offset:1024
	ds_read_b128 v[168:171], v172 offset:2048
	ds_read_b128 v[172:175], v172 offset:3072
	s_add_u32 s18, s24, 0xb0000
	s_addc_u32 s19, s25, 0
	s_mov_b32 m0, s27
	v_lshl_add_u64 v[226:227], s[18:19], 0, v[152:153]
	ds_read_b128 v[176:179], v191 offset:32768
	ds_read_b128 v[180:183], v191 offset:33792
	ds_read_b128 v[194:197], v191 offset:34816
	ds_read_b128 v[202:205], v191 offset:35840
	ds_read_b128 v[206:209], v191 offset:36864
	ds_read_b128 v[210:213], v191 offset:37888
	ds_read_b128 v[214:217], v191 offset:38912
	ds_read_b128 v[218:221], v191 offset:39936
	global_load_lds_dwordx4 v[226:227], off
	v_lshl_add_u64 v[226:227], s[18:19], 0, v[156:157]
	s_mov_b32 m0, s28
	s_nop 0
	global_load_lds_dwordx4 v[226:227], off
	s_waitcnt vmcnt(8)
	s_waitcnt lgkmcnt(0)
	s_barrier
	s_setprio 1
	s_waitcnt lgkmcnt(0)
	v_mfma_f32_16x16x32_bf16 v[124:127], v[128:131], v[176:179], v[124:127]
	v_mfma_f32_16x16x32_bf16 v[120:123], v[136:139], v[176:179], v[120:123]
	v_mfma_f32_16x16x32_bf16 v[108:111], v[128:131], v[194:197], v[108:111]
	v_mfma_f32_16x16x32_bf16 v[104:107], v[136:139], v[194:197], v[104:107]
	v_mfma_f32_16x16x32_bf16 v[92:95], v[128:131], v[206:209], v[92:95]
	v_mfma_f32_16x16x32_bf16 v[88:91], v[136:139], v[206:209], v[88:91]
	v_mfma_f32_16x16x32_bf16 v[76:79], v[128:131], v[214:217], v[76:79]
	v_mfma_f32_16x16x32_bf16 v[72:75], v[136:139], v[214:217], v[72:75]
	v_mfma_f32_16x16x32_bf16 v[124:127], v[132:135], v[180:183], v[124:127]
	v_mfma_f32_16x16x32_bf16 v[120:123], v[140:143], v[180:183], v[120:123]
	v_mfma_f32_16x16x32_bf16 v[108:111], v[132:135], v[202:205], v[108:111]
	v_mfma_f32_16x16x32_bf16 v[104:107], v[140:143], v[202:205], v[104:107]
	v_mfma_f32_16x16x32_bf16 v[92:95], v[132:135], v[210:213], v[92:95]
	v_mfma_f32_16x16x32_bf16 v[88:91], v[140:143], v[210:213], v[88:91]
	v_mfma_f32_16x16x32_bf16 v[76:79], v[132:135], v[218:221], v[76:79]
	v_mfma_f32_16x16x32_bf16 v[72:75], v[140:143], v[218:221], v[72:75]
	v_mfma_f32_16x16x32_bf16 v[116:119], v[144:147], v[176:179], v[116:119]
	v_mfma_f32_16x16x32_bf16 v[112:115], v[168:171], v[176:179], v[112:115]
	v_mfma_f32_16x16x32_bf16 v[100:103], v[144:147], v[194:197], v[100:103]
	v_mfma_f32_16x16x32_bf16 v[96:99], v[168:171], v[194:197], v[96:99]
	v_mfma_f32_16x16x32_bf16 v[84:87], v[144:147], v[206:209], v[84:87]
	v_mfma_f32_16x16x32_bf16 v[80:83], v[168:171], v[206:209], v[80:83]
	v_mfma_f32_16x16x32_bf16 v[68:71], v[144:147], v[214:217], v[68:71]
	v_mfma_f32_16x16x32_bf16 v[64:67], v[168:171], v[214:217], v[64:67]
	v_mfma_f32_16x16x32_bf16 v[116:119], v[148:151], v[180:183], v[116:119]
	v_mfma_f32_16x16x32_bf16 v[112:115], v[172:175], v[180:183], v[112:115]
	v_mfma_f32_16x16x32_bf16 v[100:103], v[148:151], v[202:205], v[100:103]
	v_mfma_f32_16x16x32_bf16 v[96:99], v[172:175], v[202:205], v[96:99]
	v_mfma_f32_16x16x32_bf16 v[84:87], v[148:151], v[210:213], v[84:87]
	v_mfma_f32_16x16x32_bf16 v[80:83], v[172:175], v[210:213], v[80:83]
	v_mfma_f32_16x16x32_bf16 v[68:71], v[148:151], v[218:221], v[68:71]
	v_mfma_f32_16x16x32_bf16 v[64:67], v[172:175], v[218:221], v[64:67]
	s_setprio 0
	s_barrier
; #define PG8_STAGE(bufoff, gbase, voff) do { _Pragma("unroll") for (int _i = 0; _i < 2; ++_i) \
;         __builtin_amdgcn_global_load_lds((const unsigned*)((const char*)(gbase) + (voff)[_i]), (PG8_LAS unsigned*)(lds + (bufoff) + ldsw + _i * 8192), 16, 0, 0); } while (0)
; #define PG8_LDA(dst, b, h) do { _Pragma("unroll") for (int m = 0; m < 4; ++m) _Pragma("unroll") for (int k = 0; k < 2; ++k) dst[m][k] = *(const PG8_LAS bf16x8*)(lds + PG8_SA(b, h) + aoff + m * 2048 + k * 1024); } while (0)
; #define PG8_MMA(ai, bj, At, Bt) do { __builtin_amdgcn_s_setprio(1); _Pragma("unroll") for (int m = 0; m < 4; ++m) _Pragma("unroll") for (int n = 0; n < 2; ++n) _Pragma("unroll") for (int k = 0; k < 2; ++k) \
;         acc[ai][bj][m][n] = __builtin_amdgcn_mfma_f32_16x16x32_bf16(Bt[n][k], At[m][k], acc[ai][bj][m][n], 0, 0, 0); __builtin_amdgcn_s_setprio(0); } while (0)
; #define PG8_WAIT_V(n) asm volatile("s_waitcnt vmcnt(" #n ")" ::: "memory")
; #define PG8_WAIT_L(n) asm volatile("s_waitcnt lgkmcnt(" #n ")" ::: "memory")
; #define PG8_BAR __builtin_amdgcn_s_barrier()
; #define PG8_SCHED __builtin_amdgcn_sched_barrier(0)
; template <class Epi, class Sched, bool ALIGN_EPI = false, bool SP2 = false>
; __device__ __forceinline__ void gemm_phase(PG8_LAS unsigned char* lds, const Gemm g, const Sched& S, const Epi& E) {
;     ...
;             PG8_LDA(At, 1, 1); PG8_STAGE(PG8_SB(1, 0), b3, voffB); PG8_STAGE(PG8_SB(1, 1), b3 + hstep, voffB); PG8_STAGE(PG8_SA(1, 0), a3, voffA);
;             PG8_WAIT_V(8); PG8_WAIT_L(0); PG8_BAR; PG8_MMA(1, 0, At, B0); PG8_MMA(1, 1, At, B1); PG8_BAR; PG8_SCHED;
;     ...
;         }
;         if constexpr (ALIGN_EPI) { if (wr == 0) PG8_BAR; }
	s_add_i32 s18, s43, s6
	v_lshl_add_u64 v[184:185], v[184:185], 0, s[4:5]
	s_mov_b32 m0, s18
	ds_read_b128 v[176:179], v191 offset:49152
	ds_read_b128 v[180:183], v191 offset:50176
	ds_read_b128 v[194:197], v191 offset:51200
	ds_read_b128 v[202:205], v191 offset:52224
	ds_read_b128 v[206:209], v191 offset:53248
	ds_read_b128 v[210:213], v191 offset:54272
	ds_read_b128 v[214:217], v191 offset:55296
	ds_read_b128 v[218:221], v191 offset:56320
	global_load_lds_dwordx4 v[184:185], off
	s_add_i32 m0, s18, 0x2000
	s_add_u32 s18, s22, 0xb0080
	v_lshl_add_u64 v[184:185], v[198:199], 0, s[4:5]
	s_addc_u32 s19, s23, 0
	s_add_i32 s22, s44, s6
	global_load_lds_dwordx4 v[184:185], off
	v_lshl_add_u64 v[184:185], s[18:19], 0, v[154:155]
	s_mov_b32 m0, s22
	s_nop 0
	global_load_lds_dwordx4 v[184:185], off
	v_lshl_add_u64 v[184:185], s[18:19], 0, v[158:159]
	s_add_i32 m0, s22, 0x2000
	s_nop 0
	global_load_lds_dwordx4 v[184:185], off
	v_lshl_add_u64 v[184:185], v[222:223], 0, s[4:5]
	s_mov_b32 m0, s30
	s_nop 0
	global_load_lds_dwordx4 v[184:185], off
	v_lshl_add_u64 v[184:185], v[224:225], 0, s[4:5]
	s_mov_b32 m0, s31
	s_nop 0
	global_load_lds_dwordx4 v[184:185], off
	s_waitcnt vmcnt(8)
	s_waitcnt lgkmcnt(0)
	s_barrier
	s_setprio 1
	s_waitcnt lgkmcnt(0)
	v_mfma_f32_16x16x32_bf16 v[60:63], v[128:131], v[176:179], v[60:63]
	v_mfma_f32_16x16x32_bf16 v[56:59], v[136:139], v[176:179], v[56:59]
	v_mfma_f32_16x16x32_bf16 v[44:47], v[128:131], v[194:197], v[44:47]
	v_mfma_f32_16x16x32_bf16 v[40:43], v[136:139], v[194:197], v[40:43]
	v_mfma_f32_16x16x32_bf16 v[28:31], v[128:131], v[206:209], v[28:31]
	v_mfma_f32_16x16x32_bf16 v[24:27], v[136:139], v[206:209], v[24:27]
	v_mfma_f32_16x16x32_bf16 v[12:15], v[128:131], v[214:217], v[12:15]
	v_mfma_f32_16x16x32_bf16 v[8:11], v[136:139], v[214:217], v[8:11]
	v_mfma_f32_16x16x32_bf16 v[60:63], v[132:135], v[180:183], v[60:63]
	v_mfma_f32_16x16x32_bf16 v[56:59], v[140:143], v[180:183], v[56:59]
	v_mfma_f32_16x16x32_bf16 v[44:47], v[132:135], v[202:205], v[44:47]
	v_mfma_f32_16x16x32_bf16 v[40:43], v[140:143], v[202:205], v[40:43]
	v_mfma_f32_16x16x32_bf16 v[28:31], v[132:135], v[210:213], v[28:31]
	v_mfma_f32_16x16x32_bf16 v[24:27], v[140:143], v[210:213], v[24:27]
	v_mfma_f32_16x16x32_bf16 v[12:15], v[132:135], v[218:221], v[12:15]
	v_mfma_f32_16x16x32_bf16 v[8:11], v[140:143], v[218:221], v[8:11]
	v_mfma_f32_16x16x32_bf16 v[52:55], v[144:147], v[176:179], v[52:55]
	v_mfma_f32_16x16x32_bf16 v[48:51], v[168:171], v[176:179], v[48:51]
	v_mfma_f32_16x16x32_bf16 v[36:39], v[144:147], v[194:197], v[36:39]
	v_mfma_f32_16x16x32_bf16 v[32:35], v[168:171], v[194:197], v[32:35]
	v_mfma_f32_16x16x32_bf16 v[20:23], v[144:147], v[206:209], v[20:23]
	v_mfma_f32_16x16x32_bf16 v[16:19], v[168:171], v[206:209], v[16:19]
	v_mfma_f32_16x16x32_bf16 v[4:7], v[144:147], v[214:217], v[4:7]
	v_mfma_f32_16x16x32_bf16 v[0:3], v[168:171], v[214:217], v[0:3]
	v_mfma_f32_16x16x32_bf16 v[52:55], v[148:151], v[180:183], v[52:55]
	v_mfma_f32_16x16x32_bf16 v[48:51], v[172:175], v[180:183], v[48:51]
	v_mfma_f32_16x16x32_bf16 v[36:39], v[148:151], v[202:205], v[36:39]
	v_mfma_f32_16x16x32_bf16 v[32:35], v[172:175], v[202:205], v[32:35]
	v_mfma_f32_16x16x32_bf16 v[20:23], v[148:151], v[210:213], v[20:23]
	v_mfma_f32_16x16x32_bf16 v[16:19], v[172:175], v[210:213], v[16:19]
	v_mfma_f32_16x16x32_bf16 v[4:7], v[148:151], v[218:221], v[4:7]
	v_mfma_f32_16x16x32_bf16 v[0:3], v[172:175], v[218:221], v[0:3]
	s_setprio 0
	s_barrier
	s_add_i32 s42, s42, 2
	s_add_u32 s40, s40, 0x100
	s_addc_u32 s41, s41, 0
	s_cmp_gt_u32 s42, 41
	s_mov_b64 s[18:19], s[20:21]
	s_cbranch_scc0 .LBB0_535
	s_and_b64 vcc, exec, s[14:15]
	s_cbranch_vccz .LBB0_538
	s_barrier

; #define PG8_STAGE(bufoff, gbase, voff) do { _Pragma("unroll") for (int _i = 0; _i < 2; ++_i) \
;         __builtin_amdgcn_global_load_lds((const unsigned*)((const char*)(gbase) + (voff)[_i]), (PG8_LAS unsigned*)(lds + (bufoff) + ldsw + _i * 8192), 16, 0, 0); } while (0)
; #define PG8_LDA(dst, b, h) do { _Pragma("unroll") for (int m = 0; m < 4; ++m) _Pragma("unroll") for (int k = 0; k < 2; ++k) dst[m][k] = *(const PG8_LAS bf16x8*)(lds + PG8_SA(b, h) + aoff + m * 2048 + k * 1024); } while (0)
; #define PG8_LDB(dst, b, h) do { _Pragma("unroll") for (int n = 0; n < 2; ++n) _Pragma("unroll") for (int k = 0; k < 2; ++k) dst[n][k] = *(const PG8_LAS bf16x8*)(lds + PG8_SB(b, h) + boff + n * 2048 + k * 1024); } while (0)
; #define PG8_MMA(ai, bj, At, Bt) do { __builtin_amdgcn_s_setprio(1); _Pragma("unroll") for (int m = 0; m < 4; ++m) _Pragma("unroll") for (int n = 0; n < 2; ++n) _Pragma("unroll") for (int k = 0; k < 2; ++k) \
;         acc[ai][bj][m][n] = __builtin_amdgcn_mfma_f32_16x16x32_bf16(Bt[n][k], At[m][k], acc[ai][bj][m][n], 0, 0, 0); __builtin_amdgcn_s_setprio(0); } while (0)
; #define PG8_WAIT_V(n) asm volatile("s_waitcnt vmcnt(" #n ")" ::: "memory")
; #define PG8_WAIT_L(n) asm volatile("s_waitcnt lgkmcnt(" #n ")" ::: "memory")
; template <class Epi, class Sched, bool ALIGN_EPI = false, bool SP2 = false>
; __device__ __forceinline__ void gemm_phase(PG8_LAS unsigned char* lds, const Gemm g, const Sched& S, const Epi& E) {
;     ...
;             const bool last = (t == nt - 2);
;             const char* a1 = cA + (size_t)(t + 1) * kstep;
;             const char* a2 = last ? nA : cA + (size_t)(t + 2) * kstep; const char* b2 = last ? nB : cB + (size_t)(t + 2) * kstep;
;             const char* a3 = a2 + kstep; const char* b3 = b2 + kstep;
;             if (last && has_next) S.a_ready(nxt);
;             if constexpr (SP2) {
;             PG8_LDB(B0, 0, 0); PG8_LDB(B1, 0, 1); PG8_SCHED; PG8_LDA(At, 0, 0); PG8_STAGE(PG8_SA(1, 1), a1 + hstep, voffA);
;             PG8_WAIT_V(8); PG8_WAIT_L(0); PG8_BAR; PG8_MMA(0, 0, At, B0); PG8_MMA(0, 1, At, B1); PG8_BAR; PG8_SCHED;
;             PG8_LDA(At, 0, 1); PG8_STAGE(PG8_SB(0, 0), b2, voffB); PG8_STAGE(PG8_SB(0, 1), b2 + hstep, voffB); PG8_STAGE(PG8_SA(0, 0), a2, voffA);
;             PG8_WAIT_V(8); PG8_WAIT_L(0); PG8_BAR; PG8_MMA(1, 0, At, B0); PG8_MMA(1, 1, At, B1); PG8_BAR; PG8_SCHED;
.LBB0_624:
	s_add_u32 s12, s10, 0xfffc0080
	s_addc_u32 s13, s11, -1
	s_add_i32 s38, 0, 0x10000
	s_cmp_eq_u32 s37, 12
	s_cselect_b32 s15, s6, s13
	s_cselect_b32 s14, s27, s12
	s_cselect_b32 s13, s25, s36
	s_cselect_b32 s12, s34, s35
	s_add_i32 s40, 0, 0x14000
	v_add_u32_e32 v158, s38, v156
	v_add_u32_e32 v174, s40, v156
	ds_read_b128 v[144:147], v158
	ds_read_b128 v[148:151], v158 offset:1024
	ds_read_b128 v[152:155], v158 offset:2048
	ds_read_b128 v[158:161], v158 offset:3072
	ds_read_b128 v[162:165], v174
	ds_read_b128 v[166:169], v174 offset:1024
	ds_read_b128 v[170:173], v174 offset:2048
	s_waitcnt vmcnt(0)
	ds_read_b128 v[174:177], v174 offset:3072
	v_lshl_add_u64 v[182:183], s[10:11], 0, v[140:141]
	s_add_i32 m0, s46, 0xc000
	ds_read_b128 v[178:181], v157
	ds_read_b128 v[192:195], v157 offset:1024
	ds_read_b128 v[196:199], v157 offset:2048
	ds_read_b128 v[208:211], v157 offset:3072
	ds_read_b128 v[212:215], v157 offset:4096
	ds_read_b128 v[216:219], v157 offset:5120
	ds_read_b128 v[220:223], v157 offset:6144
	ds_read_b128 v[224:227], v157 offset:7168
	global_load_lds_dwordx4 v[182:183], off
	v_lshl_add_u64 v[182:183], s[10:11], 0, v[142:143]
	s_add_i32 m0, s46, 0xe000
	s_nop 0
	global_load_lds_dwordx4 v[182:183], off
	s_waitcnt vmcnt(8)
	s_waitcnt lgkmcnt(0)
	s_barrier
	s_setprio 1
	s_waitcnt lgkmcnt(0)
	v_mfma_f32_16x16x32_bf16 v[124:127], v[144:147], v[178:181], v[124:127]
	v_mfma_f32_16x16x32_bf16 v[120:123], v[152:155], v[178:181], v[120:123]
	v_mfma_f32_16x16x32_bf16 v[108:111], v[144:147], v[196:199], v[108:111]
	v_mfma_f32_16x16x32_bf16 v[104:107], v[152:155], v[196:199], v[104:107]
	v_mfma_f32_16x16x32_bf16 v[92:95], v[144:147], v[212:215], v[92:95]
	v_mfma_f32_16x16x32_bf16 v[88:91], v[152:155], v[212:215], v[88:91]
	v_mfma_f32_16x16x32_bf16 v[76:79], v[144:147], v[220:223], v[76:79]
	v_mfma_f32_16x16x32_bf16 v[72:75], v[152:155], v[220:223], v[72:75]
	v_mfma_f32_16x16x32_bf16 v[124:127], v[148:151], v[192:195], v[124:127]
	v_mfma_f32_16x16x32_bf16 v[120:123], v[158:161], v[192:195], v[120:123]
	v_mfma_f32_16x16x32_bf16 v[108:111], v[148:151], v[208:211], v[108:111]
	v_mfma_f32_16x16x32_bf16 v[104:107], v[158:161], v[208:211], v[104:107]
	v_mfma_f32_16x16x32_bf16 v[92:95], v[148:151], v[216:219], v[92:95]
	v_mfma_f32_16x16x32_bf16 v[88:91], v[158:161], v[216:219], v[88:91]
	v_mfma_f32_16x16x32_bf16 v[76:79], v[148:151], v[224:227], v[76:79]
	v_mfma_f32_16x16x32_bf16 v[72:75], v[158:161], v[224:227], v[72:75]
	v_mfma_f32_16x16x32_bf16 v[116:119], v[162:165], v[178:181], v[116:119]
	v_mfma_f32_16x16x32_bf16 v[112:115], v[170:173], v[178:181], v[112:115]
	v_mfma_f32_16x16x32_bf16 v[100:103], v[162:165], v[196:199], v[100:103]
	v_mfma_f32_16x16x32_bf16 v[96:99], v[170:173], v[196:199], v[96:99]
	v_mfma_f32_16x16x32_bf16 v[84:87], v[162:165], v[212:215], v[84:87]
	v_mfma_f32_16x16x32_bf16 v[80:83], v[170:173], v[212:215], v[80:83]
	v_mfma_f32_16x16x32_bf16 v[68:71], v[162:165], v[220:223], v[68:71]
	v_mfma_f32_16x16x32_bf16 v[64:67], v[170:173], v[220:223], v[64:67]
	v_mfma_f32_16x16x32_bf16 v[116:119], v[166:169], v[192:195], v[116:119]
	v_mfma_f32_16x16x32_bf16 v[112:115], v[174:177], v[192:195], v[112:115]
	v_mfma_f32_16x16x32_bf16 v[100:103], v[166:169], v[208:211], v[100:103]
	v_mfma_f32_16x16x32_bf16 v[96:99], v[174:177], v[208:211], v[96:99]
	v_mfma_f32_16x16x32_bf16 v[84:87], v[166:169], v[216:219], v[84:87]
	v_mfma_f32_16x16x32_bf16 v[80:83], v[174:177], v[216:219], v[80:83]
	v_mfma_f32_16x16x32_bf16 v[68:71], v[166:169], v[224:227], v[68:71]
	v_mfma_f32_16x16x32_bf16 v[64:67], v[174:177], v[224:227], v[64:67]
	s_setprio 0
	s_barrier
	s_add_i32 s38, s38, s45
	v_lshl_add_u64 v[182:183], s[12:13], 0, v[132:133]
	s_mov_b32 m0, s38
	ds_read_b128 v[178:181], v157 offset:16384
	ds_read_b128 v[192:195], v157 offset:17408
	ds_read_b128 v[196:199], v157 offset:18432
	ds_read_b128 v[208:211], v157 offset:19456
	ds_read_b128 v[212:215], v157 offset:20480
	ds_read_b128 v[216:219], v157 offset:21504
	ds_read_b128 v[220:223], v157 offset:22528
	ds_read_b128 v[224:227], v157 offset:23552
	global_load_lds_dwordx4 v[182:183], off
	s_add_i32 m0, s38, 0x2000
	s_add_u32 s38, s12, 0x40000
	v_lshl_add_u64 v[188:189], s[12:13], 0, v[128:129]
	s_addc_u32 s39, s13, 0
	s_add_i32 s40, s40, s45
	global_load_lds_dwordx4 v[188:189], off
	v_lshl_add_u64 v[190:191], s[38:39], 0, v[132:133]
	s_mov_b32 m0, s40
	v_lshl_add_u64 v[228:229], s[14:15], 0, v[130:131]
	global_load_lds_dwordx4 v[190:191], off
	v_lshl_add_u64 v[190:191], s[38:39], 0, v[128:129]
	s_add_i32 m0, s40, 0x2000
	s_nop 0
	global_load_lds_dwordx4 v[190:191], off
	v_lshl_add_u64 v[190:191], s[14:15], 0, v[134:135]
	s_mov_b32 m0, s46
	s_nop 0
	global_load_lds_dwordx4 v[190:191], off
	s_mov_b32 m0, s47
	s_nop 0
	global_load_lds_dwordx4 v[228:229], off
	s_waitcnt vmcnt(8)
	s_waitcnt lgkmcnt(0)
	s_barrier
; #define PG8_STAGE(bufoff, gbase, voff) do { _Pragma("unroll") for (int _i = 0; _i < 2; ++_i) \
;         __builtin_amdgcn_global_load_lds((const unsigned*)((const char*)(gbase) + (voff)[_i]), (PG8_LAS unsigned*)(lds + (bufoff) + ldsw + _i * 8192), 16, 0, 0); } while (0)
; #define PG8_LDA(dst, b, h) do { _Pragma("unroll") for (int m = 0; m < 4; ++m) _Pragma("unroll") for (int k = 0; k < 2; ++k) dst[m][k] = *(const PG8_LAS bf16x8*)(lds + PG8_SA(b, h) + aoff + m * 2048 + k * 1024); } while (0)
; #define PG8_LDB(dst, b, h) do { _Pragma("unroll") for (int n = 0; n < 2; ++n) _Pragma("unroll") for (int k = 0; k < 2; ++k) dst[n][k] = *(const PG8_LAS bf16x8*)(lds + PG8_SB(b, h) + boff + n * 2048 + k * 1024); } while (0)
; #define PG8_MMA(ai, bj, At, Bt) do { __builtin_amdgcn_s_setprio(1); _Pragma("unroll") for (int m = 0; m < 4; ++m) _Pragma("unroll") for (int n = 0; n < 2; ++n) _Pragma("unroll") for (int k = 0; k < 2; ++k) \
;         acc[ai][bj][m][n] = __builtin_amdgcn_mfma_f32_16x16x32_bf16(Bt[n][k], At[m][k], acc[ai][bj][m][n], 0, 0, 0); __builtin_amdgcn_s_setprio(0); } while (0)
; #define PG8_WAIT_V(n) asm volatile("s_waitcnt vmcnt(" #n ")" ::: "memory")
; #define PG8_WAIT_L(n) asm volatile("s_waitcnt lgkmcnt(" #n ")" ::: "memory")
; #define PG8_BAR __builtin_amdgcn_s_barrier()
; #define PG8_SCHED __builtin_amdgcn_sched_barrier(0)
; template <class Epi, class Sched, bool ALIGN_EPI = false, bool SP2 = false>
; __device__ __forceinline__ void gemm_phase(PG8_LAS unsigned char* lds, const Gemm g, const Sched& S, const Epi& E) {
;     ...
;             PG8_LDA(At, 0, 1); PG8_STAGE(PG8_SB(0, 0), b2, voffB); PG8_STAGE(PG8_SB(0, 1), b2 + hstep, voffB); PG8_STAGE(PG8_SA(0, 0), a2, voffA);
;             PG8_WAIT_V(8); PG8_WAIT_L(0); PG8_BAR; PG8_MMA(1, 0, At, B0); PG8_MMA(1, 1, At, B1); PG8_BAR; PG8_SCHED;
;             PG8_LDB(B0, 1, 0); PG8_LDB(B1, 1, 1); PG8_SCHED; PG8_LDA(At, 1, 0); PG8_STAGE(PG8_SA(0, 1), a2 + hstep, voffA);
;             PG8_WAIT_V(8); PG8_WAIT_L(0); PG8_BAR; PG8_MMA(0, 0, At, B0); PG8_MMA(0, 1, At, B1); PG8_BAR; PG8_SCHED;
	s_setprio 1
	s_waitcnt lgkmcnt(0)
	v_mfma_f32_16x16x32_bf16 v[60:63], v[144:147], v[178:181], v[60:63]
	v_mfma_f32_16x16x32_bf16 v[56:59], v[152:155], v[178:181], v[56:59]
	v_mfma_f32_16x16x32_bf16 v[44:47], v[144:147], v[196:199], v[44:47]
	v_mfma_f32_16x16x32_bf16 v[40:43], v[152:155], v[196:199], v[40:43]
	v_mfma_f32_16x16x32_bf16 v[28:31], v[144:147], v[212:215], v[28:31]
	v_mfma_f32_16x16x32_bf16 v[24:27], v[152:155], v[212:215], v[24:27]
	v_mfma_f32_16x16x32_bf16 v[12:15], v[144:147], v[220:223], v[12:15]
	v_mfma_f32_16x16x32_bf16 v[8:11], v[152:155], v[220:223], v[8:11]
	v_mfma_f32_16x16x32_bf16 v[60:63], v[148:151], v[192:195], v[60:63]
	v_mfma_f32_16x16x32_bf16 v[56:59], v[158:161], v[192:195], v[56:59]
	v_mfma_f32_16x16x32_bf16 v[44:47], v[148:151], v[208:211], v[44:47]
	v_mfma_f32_16x16x32_bf16 v[40:43], v[158:161], v[208:211], v[40:43]
	v_mfma_f32_16x16x32_bf16 v[28:31], v[148:151], v[216:219], v[28:31]
	v_mfma_f32_16x16x32_bf16 v[24:27], v[158:161], v[216:219], v[24:27]
	v_mfma_f32_16x16x32_bf16 v[12:15], v[148:151], v[224:227], v[12:15]
	v_mfma_f32_16x16x32_bf16 v[8:11], v[158:161], v[224:227], v[8:11]
	v_mfma_f32_16x16x32_bf16 v[52:55], v[162:165], v[178:181], v[52:55]
	v_mfma_f32_16x16x32_bf16 v[48:51], v[170:173], v[178:181], v[48:51]
	v_mfma_f32_16x16x32_bf16 v[36:39], v[162:165], v[196:199], v[36:39]
	v_mfma_f32_16x16x32_bf16 v[32:35], v[170:173], v[196:199], v[32:35]
	v_mfma_f32_16x16x32_bf16 v[20:23], v[162:165], v[212:215], v[20:23]
	v_mfma_f32_16x16x32_bf16 v[16:19], v[170:173], v[212:215], v[16:19]
	v_mfma_f32_16x16x32_bf16 v[4:7], v[162:165], v[220:223], v[4:7]
	v_mfma_f32_16x16x32_bf16 v[0:3], v[170:173], v[220:223], v[0:3]
	v_mfma_f32_16x16x32_bf16 v[52:55], v[166:169], v[192:195], v[52:55]
	v_mfma_f32_16x16x32_bf16 v[48:51], v[174:177], v[192:195], v[48:51]
	v_mfma_f32_16x16x32_bf16 v[36:39], v[166:169], v[208:211], v[36:39]
	v_mfma_f32_16x16x32_bf16 v[32:35], v[174:177], v[208:211], v[32:35]
	v_mfma_f32_16x16x32_bf16 v[20:23], v[166:169], v[216:219], v[20:23]
	v_mfma_f32_16x16x32_bf16 v[16:19], v[174:177], v[216:219], v[16:19]
	v_mfma_f32_16x16x32_bf16 v[4:7], v[166:169], v[224:227], v[4:7]
	v_mfma_f32_16x16x32_bf16 v[0:3], v[174:177], v[224:227], v[0:3]
	s_setprio 0
	s_barrier
	s_add_i32 s38, 0, 0x18000
	s_add_i32 s39, 0, 0x1c000
	v_add_u32_e32 v158, s38, v156
	v_add_u32_e32 v174, s39, v156
	ds_read_b128 v[144:147], v158
	ds_read_b128 v[148:151], v158 offset:1024
	ds_read_b128 v[152:155], v158 offset:2048
	ds_read_b128 v[158:161], v158 offset:3072
	ds_read_b128 v[162:165], v174
	ds_read_b128 v[166:169], v174 offset:1024
	ds_read_b128 v[170:173], v174 offset:2048
	ds_read_b128 v[174:177], v174 offset:3072
	s_add_u32 s14, s14, 0x40000
	s_addc_u32 s15, s15, 0
	s_mov_b32 m0, s1
	v_lshl_add_u64 v[230:231], s[14:15], 0, v[134:135]
	ds_read_b128 v[178:181], v157 offset:32768
	ds_read_b128 v[192:195], v157 offset:33792
	ds_read_b128 v[196:199], v157 offset:34816
	ds_read_b128 v[208:211], v157 offset:35840
	ds_read_b128 v[212:215], v157 offset:36864
	ds_read_b128 v[216:219], v157 offset:37888
	ds_read_b128 v[220:223], v157 offset:38912
	ds_read_b128 v[224:227], v157 offset:39936
	global_load_lds_dwordx4 v[230:231], off
	v_lshl_add_u64 v[230:231], s[14:15], 0, v[130:131]
	s_mov_b32 m0, s48
	s_nop 0
	global_load_lds_dwordx4 v[230:231], off
	s_waitcnt vmcnt(8)
	s_waitcnt lgkmcnt(0)
	s_barrier
	s_setprio 1
	s_waitcnt lgkmcnt(0)
	v_mfma_f32_16x16x32_bf16 v[124:127], v[144:147], v[178:181], v[124:127]
	v_mfma_f32_16x16x32_bf16 v[120:123], v[152:155], v[178:181], v[120:123]
	v_mfma_f32_16x16x32_bf16 v[108:111], v[144:147], v[196:199], v[108:111]
	v_mfma_f32_16x16x32_bf16 v[104:107], v[152:155], v[196:199], v[104:107]
	v_mfma_f32_16x16x32_bf16 v[92:95], v[144:147], v[212:215], v[92:95]
	v_mfma_f32_16x16x32_bf16 v[88:91], v[152:155], v[212:215], v[88:91]
	v_mfma_f32_16x16x32_bf16 v[76:79], v[144:147], v[220:223], v[76:79]
	v_mfma_f32_16x16x32_bf16 v[72:75], v[152:155], v[220:223], v[72:75]
	v_mfma_f32_16x16x32_bf16 v[124:127], v[148:151], v[192:195], v[124:127]
	v_mfma_f32_16x16x32_bf16 v[120:123], v[158:161], v[192:195], v[120:123]
	v_mfma_f32_16x16x32_bf16 v[108:111], v[148:151], v[208:211], v[108:111]
	v_mfma_f32_16x16x32_bf16 v[104:107], v[158:161], v[208:211], v[104:107]
	v_mfma_f32_16x16x32_bf16 v[92:95], v[148:151], v[216:219], v[92:95]
	v_mfma_f32_16x16x32_bf16 v[88:91], v[158:161], v[216:219], v[88:91]
	v_mfma_f32_16x16x32_bf16 v[76:79], v[148:151], v[224:227], v[76:79]
	v_mfma_f32_16x16x32_bf16 v[72:75], v[158:161], v[224:227], v[72:75]
	v_mfma_f32_16x16x32_bf16 v[116:119], v[162:165], v[178:181], v[116:119]
	v_mfma_f32_16x16x32_bf16 v[112:115], v[170:173], v[178:181], v[112:115]
	v_mfma_f32_16x16x32_bf16 v[100:103], v[162:165], v[196:199], v[100:103]
	v_mfma_f32_16x16x32_bf16 v[96:99], v[170:173], v[196:199], v[96:99]
	v_mfma_f32_16x16x32_bf16 v[84:87], v[162:165], v[212:215], v[84:87]
	v_mfma_f32_16x16x32_bf16 v[80:83], v[170:173], v[212:215], v[80:83]
	v_mfma_f32_16x16x32_bf16 v[68:71], v[162:165], v[220:223], v[68:71]
	v_mfma_f32_16x16x32_bf16 v[64:67], v[170:173], v[220:223], v[64:67]
	v_mfma_f32_16x16x32_bf16 v[116:119], v[166:169], v[192:195], v[116:119]
	v_mfma_f32_16x16x32_bf16 v[112:115], v[174:177], v[192:195], v[112:115]
	v_mfma_f32_16x16x32_bf16 v[100:103], v[166:169], v[208:211], v[100:103]
	v_mfma_f32_16x16x32_bf16 v[96:99], v[174:177], v[208:211], v[96:99]
	v_mfma_f32_16x16x32_bf16 v[84:87], v[166:169], v[216:219], v[84:87]
	v_mfma_f32_16x16x32_bf16 v[80:83], v[174:177], v[216:219], v[80:83]
	v_mfma_f32_16x16x32_bf16 v[68:71], v[166:169], v[224:227], v[68:71]
	v_mfma_f32_16x16x32_bf16 v[64:67], v[174:177], v[224:227], v[64:67]
	s_setprio 0
	s_barrier
; #define PG8_STAGE(bufoff, gbase, voff) do { _Pragma("unroll") for (int _i = 0; _i < 2; ++_i) \
;         __builtin_amdgcn_global_load_lds((const unsigned*)((const char*)(gbase) + (voff)[_i]), (PG8_LAS unsigned*)(lds + (bufoff) + ldsw + _i * 8192), 16, 0, 0); } while (0)
; #define PG8_LDA(dst, b, h) do { _Pragma("unroll") for (int m = 0; m < 4; ++m) _Pragma("unroll") for (int k = 0; k < 2; ++k) dst[m][k] = *(const PG8_LAS bf16x8*)(lds + PG8_SA(b, h) + aoff + m * 2048 + k * 1024); } while (0)
; #define PG8_MMA(ai, bj, At, Bt) do { __builtin_amdgcn_s_setprio(1); _Pragma("unroll") for (int m = 0; m < 4; ++m) _Pragma("unroll") for (int n = 0; n < 2; ++n) _Pragma("unroll") for (int k = 0; k < 2; ++k) \
;         acc[ai][bj][m][n] = __builtin_amdgcn_mfma_f32_16x16x32_bf16(Bt[n][k], At[m][k], acc[ai][bj][m][n], 0, 0, 0); __builtin_amdgcn_s_setprio(0); } while (0)
; #define PG8_WAIT_V(n) asm volatile("s_waitcnt vmcnt(" #n ")" ::: "memory")
; #define PG8_WAIT_L(n) asm volatile("s_waitcnt lgkmcnt(" #n ")" ::: "memory")
; #define PG8_BAR __builtin_amdgcn_s_barrier()
; #define PG8_SCHED __builtin_amdgcn_sched_barrier(0)
; template <class Epi, class Sched, bool ALIGN_EPI = false, bool SP2 = false>
; __device__ __forceinline__ void gemm_phase(PG8_LAS unsigned char* lds, const Gemm g, const Sched& S, const Epi& E) {
;     ...
;             PG8_LDA(At, 1, 1); PG8_STAGE(PG8_SB(1, 0), b3, voffB); PG8_STAGE(PG8_SB(1, 1), b3 + hstep, voffB); PG8_STAGE(PG8_SA(1, 0), a3, voffA);
;             PG8_WAIT_V(8); PG8_WAIT_L(0); PG8_BAR; PG8_MMA(1, 0, At, B0); PG8_MMA(1, 1, At, B1); PG8_BAR; PG8_SCHED;
;     ...
;         }
;         if constexpr (ALIGN_EPI) { if (wr == 0) PG8_BAR; }
	s_add_i32 s14, s38, s45
	v_lshl_add_u64 v[182:183], v[182:183], 0, s[92:93]
	s_mov_b32 m0, s14
	ds_read_b128 v[178:181], v157 offset:49152
	ds_read_b128 v[192:195], v157 offset:50176
	ds_read_b128 v[196:199], v157 offset:51200
	ds_read_b128 v[208:211], v157 offset:52224
	ds_read_b128 v[212:215], v157 offset:53248
	ds_read_b128 v[216:219], v157 offset:54272
	ds_read_b128 v[220:223], v157 offset:55296
	ds_read_b128 v[224:227], v157 offset:56320
	global_load_lds_dwordx4 v[182:183], off
	s_add_i32 m0, s14, 0x2000
	s_add_u32 s12, s12, 0x40080
	v_lshl_add_u64 v[182:183], v[188:189], 0, s[92:93]
	s_addc_u32 s13, s13, 0
	s_add_i32 s14, s39, s45
	global_load_lds_dwordx4 v[182:183], off
	v_lshl_add_u64 v[182:183], s[12:13], 0, v[132:133]
	s_mov_b32 m0, s14
	s_nop 0
	global_load_lds_dwordx4 v[182:183], off
	v_lshl_add_u64 v[182:183], s[12:13], 0, v[128:129]
	s_add_i32 m0, s14, 0x2000
	s_nop 0
	global_load_lds_dwordx4 v[182:183], off
	v_lshl_add_u64 v[182:183], v[190:191], 0, s[92:93]
	s_mov_b32 m0, s49
	s_nop 0
	global_load_lds_dwordx4 v[182:183], off
	v_lshl_add_u64 v[182:183], v[228:229], 0, s[92:93]
	s_mov_b32 m0, s50
	s_nop 0
	global_load_lds_dwordx4 v[182:183], off
	s_waitcnt vmcnt(8)
	s_waitcnt lgkmcnt(0)
	s_barrier
	s_setprio 1
	s_waitcnt lgkmcnt(0)
	v_mfma_f32_16x16x32_bf16 v[60:63], v[144:147], v[178:181], v[60:63]
	v_mfma_f32_16x16x32_bf16 v[56:59], v[152:155], v[178:181], v[56:59]
	v_mfma_f32_16x16x32_bf16 v[44:47], v[144:147], v[196:199], v[44:47]
	v_mfma_f32_16x16x32_bf16 v[40:43], v[152:155], v[196:199], v[40:43]
	v_mfma_f32_16x16x32_bf16 v[28:31], v[144:147], v[212:215], v[28:31]
	v_mfma_f32_16x16x32_bf16 v[24:27], v[152:155], v[212:215], v[24:27]
	v_mfma_f32_16x16x32_bf16 v[12:15], v[144:147], v[220:223], v[12:15]
	v_mfma_f32_16x16x32_bf16 v[8:11], v[152:155], v[220:223], v[8:11]
	v_mfma_f32_16x16x32_bf16 v[60:63], v[148:151], v[192:195], v[60:63]
	v_mfma_f32_16x16x32_bf16 v[56:59], v[158:161], v[192:195], v[56:59]
	v_mfma_f32_16x16x32_bf16 v[44:47], v[148:151], v[208:211], v[44:47]
	v_mfma_f32_16x16x32_bf16 v[40:43], v[158:161], v[208:211], v[40:43]
	v_mfma_f32_16x16x32_bf16 v[28:31], v[148:151], v[216:219], v[28:31]
	v_mfma_f32_16x16x32_bf16 v[24:27], v[158:161], v[216:219], v[24:27]
	v_mfma_f32_16x16x32_bf16 v[12:15], v[148:151], v[224:227], v[12:15]
	v_mfma_f32_16x16x32_bf16 v[8:11], v[158:161], v[224:227], v[8:11]
	v_mfma_f32_16x16x32_bf16 v[52:55], v[162:165], v[178:181], v[52:55]
	v_mfma_f32_16x16x32_bf16 v[48:51], v[170:173], v[178:181], v[48:51]
	v_mfma_f32_16x16x32_bf16 v[36:39], v[162:165], v[196:199], v[36:39]
	v_mfma_f32_16x16x32_bf16 v[32:35], v[170:173], v[196:199], v[32:35]
	v_mfma_f32_16x16x32_bf16 v[20:23], v[162:165], v[212:215], v[20:23]
	v_mfma_f32_16x16x32_bf16 v[16:19], v[170:173], v[212:215], v[16:19]
	v_mfma_f32_16x16x32_bf16 v[4:7], v[162:165], v[220:223], v[4:7]
	v_mfma_f32_16x16x32_bf16 v[0:3], v[170:173], v[220:223], v[0:3]
	v_mfma_f32_16x16x32_bf16 v[52:55], v[166:169], v[192:195], v[52:55]
	v_mfma_f32_16x16x32_bf16 v[48:51], v[174:177], v[192:195], v[48:51]
	v_mfma_f32_16x16x32_bf16 v[36:39], v[166:169], v[208:211], v[36:39]
	v_mfma_f32_16x16x32_bf16 v[32:35], v[174:177], v[208:211], v[32:35]
	v_mfma_f32_16x16x32_bf16 v[20:23], v[166:169], v[216:219], v[20:23]
	v_mfma_f32_16x16x32_bf16 v[16:19], v[174:177], v[216:219], v[16:19]
	v_mfma_f32_16x16x32_bf16 v[4:7], v[166:169], v[224:227], v[4:7]
	v_mfma_f32_16x16x32_bf16 v[0:3], v[174:177], v[224:227], v[0:3]
	s_setprio 0
	s_barrier
	s_add_i32 s37, s37, 2
	s_add_u32 s10, s10, 0x100
	s_addc_u32 s11, s11, 0
	s_add_u32 s35, s35, 0x100
	s_addc_u32 s36, s36, 0
	s_cmp_gt_u32 s37, 13
	s_cbranch_scc0 .LBB0_624
	s_and_b64 vcc, exec, s[20:21]
	s_cbranch_vccz .LBB0_627
	s_barrier

; #define PG8_STAGE(bufoff, gbase, voff) do { _Pragma("unroll") for (int _i = 0; _i < 2; ++_i) \
;         __builtin_amdgcn_global_load_lds((const unsigned*)((const char*)(gbase) + (voff)[_i]), (PG8_LAS unsigned*)(lds + (bufoff) + ldsw + _i * 8192), 16, 0, 0); } while (0)
; #define PG8_LDA(dst, b, h) do { _Pragma("unroll") for (int m = 0; m < 4; ++m) _Pragma("unroll") for (int k = 0; k < 2; ++k) dst[m][k] = *(const PG8_LAS bf16x8*)(lds + PG8_SA(b, h) + aoff + m * 2048 + k * 1024); } while (0)
; #define PG8_LDB(dst, b, h) do { _Pragma("unroll") for (int n = 0; n < 2; ++n) _Pragma("unroll") for (int k = 0; k < 2; ++k) dst[n][k] = *(const PG8_LAS bf16x8*)(lds + PG8_SB(b, h) + boff + n * 2048 + k * 1024); } while (0)
; #define PG8_MMA(ai, bj, At, Bt) do { __builtin_amdgcn_s_setprio(1); _Pragma("unroll") for (int m = 0; m < 4; ++m) _Pragma("unroll") for (int n = 0; n < 2; ++n) _Pragma("unroll") for (int k = 0; k < 2; ++k) \
;         acc[ai][bj][m][n] = __builtin_amdgcn_mfma_f32_16x16x32_bf16(Bt[n][k], At[m][k], acc[ai][bj][m][n], 0, 0, 0); __builtin_amdgcn_s_setprio(0); } while (0)
; #define PG8_WAIT_V(n) asm volatile("s_waitcnt vmcnt(" #n ")" ::: "memory")
; #define PG8_WAIT_L(n) asm volatile("s_waitcnt lgkmcnt(" #n ")" ::: "memory")
; template <class Epi, class Sched, bool ALIGN_EPI = false, bool SP2 = false>
; __device__ __forceinline__ void gemm_phase(PG8_LAS unsigned char* lds, const Gemm g, const Sched& S, const Epi& E) {
;     ...
;             const bool last = (t == nt - 2);
;             const char* a1 = cA + (size_t)(t + 1) * kstep;
;             const char* a2 = last ? nA : cA + (size_t)(t + 2) * kstep; const char* b2 = last ? nB : cB + (size_t)(t + 2) * kstep;
;             const char* a3 = a2 + kstep; const char* b3 = b2 + kstep;
;             if (last && has_next) S.a_ready(nxt);
;             if constexpr (SP2) {
;             PG8_LDB(B0, 0, 0); PG8_LDB(B1, 0, 1); PG8_SCHED; PG8_LDA(At, 0, 0); PG8_STAGE(PG8_SA(1, 1), a1 + hstep, voffA);
;             PG8_WAIT_V(8); PG8_WAIT_L(0); PG8_BAR; PG8_MMA(0, 0, At, B0); PG8_MMA(0, 1, At, B1); PG8_BAR; PG8_SCHED;
;             PG8_LDA(At, 0, 1); PG8_STAGE(PG8_SB(0, 0), b2, voffB); PG8_STAGE(PG8_SB(0, 1), b2 + hstep, voffB); PG8_STAGE(PG8_SA(0, 0), a2, voffA);
;             PG8_WAIT_V(8); PG8_WAIT_L(0); PG8_BAR; PG8_MMA(1, 0, At, B0); PG8_MMA(1, 1, At, B1); PG8_BAR; PG8_SCHED;
.LBB0_822:
	s_add_u32 s12, s75, s10
	s_addc_u32 s13, s65, s11
	s_add_u32 s12, s12, 0x2b400100
	s_addc_u32 s13, s13, 0
	s_add_u32 s22, s59, s10
	s_addc_u32 s23, s77, s11
	s_add_i32 s24, 0, 0x10000
	s_cmpk_eq_i32 s10, 0xf00
	s_cselect_b32 s15, s71, s13
	s_cselect_b32 s14, s70, s12
	s_cselect_b32 s13, s69, s23
	s_cselect_b32 s12, s68, s22
	s_add_i32 s25, 0, 0x14000
	v_add_u32_e32 v154, s24, v140
	v_add_u32_e32 v170, s25, v140
	ds_read_b128 v[142:145], v154
	ds_read_b128 v[146:149], v154 offset:1024
	ds_read_b128 v[150:153], v154 offset:2048
	ds_read_b128 v[154:157], v154 offset:3072
	ds_read_b128 v[158:161], v170
	ds_read_b128 v[162:165], v170 offset:1024
	ds_read_b128 v[166:169], v170 offset:2048
	ds_read_b128 v[170:173], v170 offset:3072
	v_lshl_add_u64 v[182:183], v[134:135], 0, s[10:11]
	s_add_i32 m0, s3, 0xc000
	ds_read_b128 v[174:177], v141
	ds_read_b128 v[178:181], v141 offset:1024
	ds_read_b128 v[192:195], v141 offset:2048
	ds_read_b128 v[196:199], v141 offset:3072
	ds_read_b128 v[208:211], v141 offset:4096
	ds_read_b128 v[212:215], v141 offset:5120
	ds_read_b128 v[216:219], v141 offset:6144
	ds_read_b128 v[220:223], v141 offset:7168
	global_load_lds_dwordx4 v[182:183], off
	v_lshl_add_u64 v[182:183], v[136:137], 0, s[10:11]
	s_add_i32 m0, s3, 0xe000
	s_nop 0
	global_load_lds_dwordx4 v[182:183], off
	s_waitcnt vmcnt(8)
	s_waitcnt lgkmcnt(0)
	s_barrier
	s_setprio 1
	s_waitcnt lgkmcnt(0)
	v_mfma_f32_16x16x32_bf16 v[124:127], v[142:145], v[174:177], v[124:127]
	v_mfma_f32_16x16x32_bf16 v[120:123], v[150:153], v[174:177], v[120:123]
	v_mfma_f32_16x16x32_bf16 v[108:111], v[142:145], v[192:195], v[108:111]
	v_mfma_f32_16x16x32_bf16 v[104:107], v[150:153], v[192:195], v[104:107]
	v_mfma_f32_16x16x32_bf16 v[92:95], v[142:145], v[208:211], v[92:95]
	v_mfma_f32_16x16x32_bf16 v[88:91], v[150:153], v[208:211], v[88:91]
	v_mfma_f32_16x16x32_bf16 v[76:79], v[142:145], v[216:219], v[76:79]
	v_mfma_f32_16x16x32_bf16 v[72:75], v[150:153], v[216:219], v[72:75]
	v_mfma_f32_16x16x32_bf16 v[124:127], v[146:149], v[178:181], v[124:127]
	v_mfma_f32_16x16x32_bf16 v[120:123], v[154:157], v[178:181], v[120:123]
	v_mfma_f32_16x16x32_bf16 v[108:111], v[146:149], v[196:199], v[108:111]
	v_mfma_f32_16x16x32_bf16 v[104:107], v[154:157], v[196:199], v[104:107]
	v_mfma_f32_16x16x32_bf16 v[92:95], v[146:149], v[212:215], v[92:95]
	v_mfma_f32_16x16x32_bf16 v[88:91], v[154:157], v[212:215], v[88:91]
	v_mfma_f32_16x16x32_bf16 v[76:79], v[146:149], v[220:223], v[76:79]
	v_mfma_f32_16x16x32_bf16 v[72:75], v[154:157], v[220:223], v[72:75]
	v_mfma_f32_16x16x32_bf16 v[116:119], v[158:161], v[174:177], v[116:119]
	v_mfma_f32_16x16x32_bf16 v[112:115], v[166:169], v[174:177], v[112:115]
	v_mfma_f32_16x16x32_bf16 v[100:103], v[158:161], v[192:195], v[100:103]
	v_mfma_f32_16x16x32_bf16 v[96:99], v[166:169], v[192:195], v[96:99]
	v_mfma_f32_16x16x32_bf16 v[84:87], v[158:161], v[208:211], v[84:87]
	v_mfma_f32_16x16x32_bf16 v[80:83], v[166:169], v[208:211], v[80:83]
	v_mfma_f32_16x16x32_bf16 v[68:71], v[158:161], v[216:219], v[68:71]
	v_mfma_f32_16x16x32_bf16 v[64:67], v[166:169], v[216:219], v[64:67]
	v_mfma_f32_16x16x32_bf16 v[116:119], v[162:165], v[178:181], v[116:119]
	v_mfma_f32_16x16x32_bf16 v[112:115], v[170:173], v[178:181], v[112:115]
	v_mfma_f32_16x16x32_bf16 v[100:103], v[162:165], v[196:199], v[100:103]
	v_mfma_f32_16x16x32_bf16 v[96:99], v[170:173], v[196:199], v[96:99]
	v_mfma_f32_16x16x32_bf16 v[84:87], v[162:165], v[212:215], v[84:87]
	v_mfma_f32_16x16x32_bf16 v[80:83], v[170:173], v[212:215], v[80:83]
	v_mfma_f32_16x16x32_bf16 v[68:71], v[162:165], v[220:223], v[68:71]
	v_mfma_f32_16x16x32_bf16 v[64:67], v[170:173], v[220:223], v[64:67]
	s_setprio 0
	s_barrier
	s_add_i32 s22, s24, s1
	v_lshl_add_u64 v[182:183], s[12:13], 0, v[186:187]
	s_mov_b32 m0, s22
	ds_read_b128 v[174:177], v141 offset:16384
	ds_read_b128 v[178:181], v141 offset:17408
	ds_read_b128 v[192:195], v141 offset:18432
	ds_read_b128 v[196:199], v141 offset:19456
	ds_read_b128 v[208:211], v141 offset:20480
	ds_read_b128 v[212:215], v141 offset:21504
	ds_read_b128 v[216:219], v141 offset:22528
	ds_read_b128 v[220:223], v141 offset:23552
	global_load_lds_dwordx4 v[182:183], off
	s_add_i32 m0, s22, 0x2000
	s_add_u32 s22, s12, 0x80000
	v_lshl_add_u64 v[188:189], s[12:13], 0, v[128:129]
	s_addc_u32 s23, s13, 0
	s_add_i32 s24, s25, s1
	global_load_lds_dwordx4 v[188:189], off
	v_lshl_add_u64 v[190:191], s[22:23], 0, v[186:187]
	s_mov_b32 m0, s24
	v_lshl_add_u64 v[224:225], s[14:15], 0, v[130:131]
	global_load_lds_dwordx4 v[190:191], off
	v_lshl_add_u64 v[190:191], s[22:23], 0, v[128:129]
	s_add_i32 m0, s24, 0x2000
	s_nop 0
	global_load_lds_dwordx4 v[190:191], off
	v_lshl_add_u64 v[190:191], s[14:15], 0, v[132:133]
	s_mov_b32 m0, s3
	s_nop 0
	global_load_lds_dwordx4 v[190:191], off
	s_mov_b32 m0, s6
	s_nop 0
	global_load_lds_dwordx4 v[224:225], off
	s_waitcnt vmcnt(8)
	s_waitcnt lgkmcnt(0)
	s_barrier
; #define PG8_STAGE(bufoff, gbase, voff) do { _Pragma("unroll") for (int _i = 0; _i < 2; ++_i) \
;         __builtin_amdgcn_global_load_lds((const unsigned*)((const char*)(gbase) + (voff)[_i]), (PG8_LAS unsigned*)(lds + (bufoff) + ldsw + _i * 8192), 16, 0, 0); } while (0)
; #define PG8_LDA(dst, b, h) do { _Pragma("unroll") for (int m = 0; m < 4; ++m) _Pragma("unroll") for (int k = 0; k < 2; ++k) dst[m][k] = *(const PG8_LAS bf16x8*)(lds + PG8_SA(b, h) + aoff + m * 2048 + k * 1024); } while (0)
; #define PG8_LDB(dst, b, h) do { _Pragma("unroll") for (int n = 0; n < 2; ++n) _Pragma("unroll") for (int k = 0; k < 2; ++k) dst[n][k] = *(const PG8_LAS bf16x8*)(lds + PG8_SB(b, h) + boff + n * 2048 + k * 1024); } while (0)
; #define PG8_MMA(ai, bj, At, Bt) do { __builtin_amdgcn_s_setprio(1); _Pragma("unroll") for (int m = 0; m < 4; ++m) _Pragma("unroll") for (int n = 0; n < 2; ++n) _Pragma("unroll") for (int k = 0; k < 2; ++k) \
;         acc[ai][bj][m][n] = __builtin_amdgcn_mfma_f32_16x16x32_bf16(Bt[n][k], At[m][k], acc[ai][bj][m][n], 0, 0, 0); __builtin_amdgcn_s_setprio(0); } while (0)
; #define PG8_WAIT_V(n) asm volatile("s_waitcnt vmcnt(" #n ")" ::: "memory")
; #define PG8_WAIT_L(n) asm volatile("s_waitcnt lgkmcnt(" #n ")" ::: "memory")
; #define PG8_BAR __builtin_amdgcn_s_barrier()
; #define PG8_SCHED __builtin_amdgcn_sched_barrier(0)
; template <class Epi, class Sched, bool ALIGN_EPI = false, bool SP2 = false>
; __device__ __forceinline__ void gemm_phase(PG8_LAS unsigned char* lds, const Gemm g, const Sched& S, const Epi& E) {
;     ...
;             PG8_LDA(At, 0, 1); PG8_STAGE(PG8_SB(0, 0), b2, voffB); PG8_STAGE(PG8_SB(0, 1), b2 + hstep, voffB); PG8_STAGE(PG8_SA(0, 0), a2, voffA);
;             PG8_WAIT_V(8); PG8_WAIT_L(0); PG8_BAR; PG8_MMA(1, 0, At, B0); PG8_MMA(1, 1, At, B1); PG8_BAR; PG8_SCHED;
;             PG8_LDB(B0, 1, 0); PG8_LDB(B1, 1, 1); PG8_SCHED; PG8_LDA(At, 1, 0); PG8_STAGE(PG8_SA(0, 1), a2 + hstep, voffA);
;             PG8_WAIT_V(8); PG8_WAIT_L(0); PG8_BAR; PG8_MMA(0, 0, At, B0); PG8_MMA(0, 1, At, B1); PG8_BAR; PG8_SCHED;
	s_setprio 1
	s_waitcnt lgkmcnt(0)
	v_mfma_f32_16x16x32_bf16 v[60:63], v[142:145], v[174:177], v[60:63]
	v_mfma_f32_16x16x32_bf16 v[56:59], v[150:153], v[174:177], v[56:59]
	v_mfma_f32_16x16x32_bf16 v[44:47], v[142:145], v[192:195], v[44:47]
	v_mfma_f32_16x16x32_bf16 v[40:43], v[150:153], v[192:195], v[40:43]
	v_mfma_f32_16x16x32_bf16 v[28:31], v[142:145], v[208:211], v[28:31]
	v_mfma_f32_16x16x32_bf16 v[24:27], v[150:153], v[208:211], v[24:27]
	v_mfma_f32_16x16x32_bf16 v[12:15], v[142:145], v[216:219], v[12:15]
	v_mfma_f32_16x16x32_bf16 v[8:11], v[150:153], v[216:219], v[8:11]
	v_mfma_f32_16x16x32_bf16 v[60:63], v[146:149], v[178:181], v[60:63]
	v_mfma_f32_16x16x32_bf16 v[56:59], v[154:157], v[178:181], v[56:59]
	v_mfma_f32_16x16x32_bf16 v[44:47], v[146:149], v[196:199], v[44:47]
	v_mfma_f32_16x16x32_bf16 v[40:43], v[154:157], v[196:199], v[40:43]
	v_mfma_f32_16x16x32_bf16 v[28:31], v[146:149], v[212:215], v[28:31]
	v_mfma_f32_16x16x32_bf16 v[24:27], v[154:157], v[212:215], v[24:27]
	v_mfma_f32_16x16x32_bf16 v[12:15], v[146:149], v[220:223], v[12:15]
	v_mfma_f32_16x16x32_bf16 v[8:11], v[154:157], v[220:223], v[8:11]
	v_mfma_f32_16x16x32_bf16 v[52:55], v[158:161], v[174:177], v[52:55]
	v_mfma_f32_16x16x32_bf16 v[48:51], v[166:169], v[174:177], v[48:51]
	v_mfma_f32_16x16x32_bf16 v[36:39], v[158:161], v[192:195], v[36:39]
	v_mfma_f32_16x16x32_bf16 v[32:35], v[166:169], v[192:195], v[32:35]
	v_mfma_f32_16x16x32_bf16 v[20:23], v[158:161], v[208:211], v[20:23]
	v_mfma_f32_16x16x32_bf16 v[16:19], v[166:169], v[208:211], v[16:19]
	v_mfma_f32_16x16x32_bf16 v[4:7], v[158:161], v[216:219], v[4:7]
	v_mfma_f32_16x16x32_bf16 v[0:3], v[166:169], v[216:219], v[0:3]
	v_mfma_f32_16x16x32_bf16 v[52:55], v[162:165], v[178:181], v[52:55]
	v_mfma_f32_16x16x32_bf16 v[48:51], v[170:173], v[178:181], v[48:51]
	v_mfma_f32_16x16x32_bf16 v[36:39], v[162:165], v[196:199], v[36:39]
	v_mfma_f32_16x16x32_bf16 v[32:35], v[170:173], v[196:199], v[32:35]
	v_mfma_f32_16x16x32_bf16 v[20:23], v[162:165], v[212:215], v[20:23]
	v_mfma_f32_16x16x32_bf16 v[16:19], v[170:173], v[212:215], v[16:19]
	v_mfma_f32_16x16x32_bf16 v[4:7], v[162:165], v[220:223], v[4:7]
	v_mfma_f32_16x16x32_bf16 v[0:3], v[170:173], v[220:223], v[0:3]
	s_setprio 0
	s_barrier
	s_add_i32 s22, 0, 0x18000
	s_add_i32 s23, 0, 0x1c000
	v_add_u32_e32 v154, s22, v140
	v_add_u32_e32 v170, s23, v140
	ds_read_b128 v[142:145], v154
	ds_read_b128 v[146:149], v154 offset:1024
	ds_read_b128 v[150:153], v154 offset:2048
	ds_read_b128 v[154:157], v154 offset:3072
	ds_read_b128 v[158:161], v170
	ds_read_b128 v[162:165], v170 offset:1024
	ds_read_b128 v[166:169], v170 offset:2048
	ds_read_b128 v[170:173], v170 offset:3072
	s_add_u32 s14, s14, 0x80000
	s_addc_u32 s15, s15, 0
	s_mov_b32 m0, s16
	v_lshl_add_u64 v[226:227], s[14:15], 0, v[132:133]
	ds_read_b128 v[174:177], v141 offset:32768
	ds_read_b128 v[178:181], v141 offset:33792
	ds_read_b128 v[192:195], v141 offset:34816
	ds_read_b128 v[196:199], v141 offset:35840
	ds_read_b128 v[208:211], v141 offset:36864
	ds_read_b128 v[212:215], v141 offset:37888
	ds_read_b128 v[216:219], v141 offset:38912
	ds_read_b128 v[220:223], v141 offset:39936
	global_load_lds_dwordx4 v[226:227], off
	v_lshl_add_u64 v[226:227], s[14:15], 0, v[130:131]
	s_mov_b32 m0, s17
	s_nop 0
	global_load_lds_dwordx4 v[226:227], off
	s_waitcnt vmcnt(8)
	s_waitcnt lgkmcnt(0)
	s_barrier
	s_setprio 1
	s_waitcnt lgkmcnt(0)
	v_mfma_f32_16x16x32_bf16 v[124:127], v[142:145], v[174:177], v[124:127]
	v_mfma_f32_16x16x32_bf16 v[120:123], v[150:153], v[174:177], v[120:123]
	v_mfma_f32_16x16x32_bf16 v[108:111], v[142:145], v[192:195], v[108:111]
	v_mfma_f32_16x16x32_bf16 v[104:107], v[150:153], v[192:195], v[104:107]
	v_mfma_f32_16x16x32_bf16 v[92:95], v[142:145], v[208:211], v[92:95]
	v_mfma_f32_16x16x32_bf16 v[88:91], v[150:153], v[208:211], v[88:91]
	v_mfma_f32_16x16x32_bf16 v[76:79], v[142:145], v[216:219], v[76:79]
	v_mfma_f32_16x16x32_bf16 v[72:75], v[150:153], v[216:219], v[72:75]
	v_mfma_f32_16x16x32_bf16 v[124:127], v[146:149], v[178:181], v[124:127]
	v_mfma_f32_16x16x32_bf16 v[120:123], v[154:157], v[178:181], v[120:123]
	v_mfma_f32_16x16x32_bf16 v[108:111], v[146:149], v[196:199], v[108:111]
	v_mfma_f32_16x16x32_bf16 v[104:107], v[154:157], v[196:199], v[104:107]
	v_mfma_f32_16x16x32_bf16 v[92:95], v[146:149], v[212:215], v[92:95]
	v_mfma_f32_16x16x32_bf16 v[88:91], v[154:157], v[212:215], v[88:91]
	v_mfma_f32_16x16x32_bf16 v[76:79], v[146:149], v[220:223], v[76:79]
	v_mfma_f32_16x16x32_bf16 v[72:75], v[154:157], v[220:223], v[72:75]
	v_mfma_f32_16x16x32_bf16 v[116:119], v[158:161], v[174:177], v[116:119]
	v_mfma_f32_16x16x32_bf16 v[112:115], v[166:169], v[174:177], v[112:115]
	v_mfma_f32_16x16x32_bf16 v[100:103], v[158:161], v[192:195], v[100:103]
	v_mfma_f32_16x16x32_bf16 v[96:99], v[166:169], v[192:195], v[96:99]
	v_mfma_f32_16x16x32_bf16 v[84:87], v[158:161], v[208:211], v[84:87]
	v_mfma_f32_16x16x32_bf16 v[80:83], v[166:169], v[208:211], v[80:83]
	v_mfma_f32_16x16x32_bf16 v[68:71], v[158:161], v[216:219], v[68:71]
	v_mfma_f32_16x16x32_bf16 v[64:67], v[166:169], v[216:219], v[64:67]
	v_mfma_f32_16x16x32_bf16 v[116:119], v[162:165], v[178:181], v[116:119]
	v_mfma_f32_16x16x32_bf16 v[112:115], v[170:173], v[178:181], v[112:115]
	v_mfma_f32_16x16x32_bf16 v[100:103], v[162:165], v[196:199], v[100:103]
	v_mfma_f32_16x16x32_bf16 v[96:99], v[170:173], v[196:199], v[96:99]
	v_mfma_f32_16x16x32_bf16 v[84:87], v[162:165], v[212:215], v[84:87]
	v_mfma_f32_16x16x32_bf16 v[80:83], v[170:173], v[212:215], v[80:83]
	v_mfma_f32_16x16x32_bf16 v[68:71], v[162:165], v[220:223], v[68:71]
	v_mfma_f32_16x16x32_bf16 v[64:67], v[170:173], v[220:223], v[64:67]
	s_setprio 0
	s_barrier
; #define PG8_STAGE(bufoff, gbase, voff) do { _Pragma("unroll") for (int _i = 0; _i < 2; ++_i) \
;         __builtin_amdgcn_global_load_lds((const unsigned*)((const char*)(gbase) + (voff)[_i]), (PG8_LAS unsigned*)(lds + (bufoff) + ldsw + _i * 8192), 16, 0, 0); } while (0)
; #define PG8_LDA(dst, b, h) do { _Pragma("unroll") for (int m = 0; m < 4; ++m) _Pragma("unroll") for (int k = 0; k < 2; ++k) dst[m][k] = *(const PG8_LAS bf16x8*)(lds + PG8_SA(b, h) + aoff + m * 2048 + k * 1024); } while (0)
; #define PG8_MMA(ai, bj, At, Bt) do { __builtin_amdgcn_s_setprio(1); _Pragma("unroll") for (int m = 0; m < 4; ++m) _Pragma("unroll") for (int n = 0; n < 2; ++n) _Pragma("unroll") for (int k = 0; k < 2; ++k) \
;         acc[ai][bj][m][n] = __builtin_amdgcn_mfma_f32_16x16x32_bf16(Bt[n][k], At[m][k], acc[ai][bj][m][n], 0, 0, 0); __builtin_amdgcn_s_setprio(0); } while (0)
; #define PG8_WAIT_V(n) asm volatile("s_waitcnt vmcnt(" #n ")" ::: "memory")
; #define PG8_WAIT_L(n) asm volatile("s_waitcnt lgkmcnt(" #n ")" ::: "memory")
; #define PG8_BAR __builtin_amdgcn_s_barrier()
; #define PG8_SCHED __builtin_amdgcn_sched_barrier(0)
; template <class Epi, class Sched, bool ALIGN_EPI = false, bool SP2 = false>
; __device__ __forceinline__ void gemm_phase(PG8_LAS unsigned char* lds, const Gemm g, const Sched& S, const Epi& E) {
;     ...
;             PG8_LDA(At, 1, 1); PG8_STAGE(PG8_SB(1, 0), b3, voffB); PG8_STAGE(PG8_SB(1, 1), b3 + hstep, voffB); PG8_STAGE(PG8_SA(1, 0), a3, voffA);
;             PG8_WAIT_V(8); PG8_WAIT_L(0); PG8_BAR; PG8_MMA(1, 0, At, B0); PG8_MMA(1, 1, At, B1); PG8_BAR; PG8_SCHED;
;     ...
;         }
;         if constexpr (ALIGN_EPI) { if (wr == 0) PG8_BAR; }
	s_add_i32 s14, s22, s1
	v_lshl_add_u64 v[182:183], v[182:183], 0, s[92:93]
	s_mov_b32 m0, s14
	ds_read_b128 v[174:177], v141 offset:49152
	ds_read_b128 v[178:181], v141 offset:50176
	ds_read_b128 v[192:195], v141 offset:51200
	ds_read_b128 v[196:199], v141 offset:52224
	ds_read_b128 v[208:211], v141 offset:53248
	ds_read_b128 v[212:215], v141 offset:54272
	ds_read_b128 v[216:219], v141 offset:55296
	ds_read_b128 v[220:223], v141 offset:56320
	global_load_lds_dwordx4 v[182:183], off
	s_add_i32 m0, s14, 0x2000
	s_add_u32 s12, s12, 0x80080
	v_lshl_add_u64 v[182:183], v[188:189], 0, s[92:93]
	s_addc_u32 s13, s13, 0
	s_add_i32 s14, s23, s1
	global_load_lds_dwordx4 v[182:183], off
	v_lshl_add_u64 v[182:183], s[12:13], 0, v[186:187]
	s_mov_b32 m0, s14
	s_nop 0
	global_load_lds_dwordx4 v[182:183], off
	v_lshl_add_u64 v[182:183], s[12:13], 0, v[128:129]
	s_add_i32 m0, s14, 0x2000
	s_nop 0
	global_load_lds_dwordx4 v[182:183], off
	v_lshl_add_u64 v[182:183], v[190:191], 0, s[92:93]
	s_mov_b32 m0, s19
	s_nop 0
	global_load_lds_dwordx4 v[182:183], off
	v_lshl_add_u64 v[182:183], v[224:225], 0, s[92:93]
	s_mov_b32 m0, s20
	s_nop 0
	global_load_lds_dwordx4 v[182:183], off
	s_waitcnt vmcnt(8)
	s_waitcnt lgkmcnt(0)
	s_barrier
	s_setprio 1
	s_waitcnt lgkmcnt(0)
	v_mfma_f32_16x16x32_bf16 v[60:63], v[142:145], v[174:177], v[60:63]
	v_mfma_f32_16x16x32_bf16 v[56:59], v[150:153], v[174:177], v[56:59]
	v_mfma_f32_16x16x32_bf16 v[44:47], v[142:145], v[192:195], v[44:47]
	v_mfma_f32_16x16x32_bf16 v[40:43], v[150:153], v[192:195], v[40:43]
	v_mfma_f32_16x16x32_bf16 v[28:31], v[142:145], v[208:211], v[28:31]
	v_mfma_f32_16x16x32_bf16 v[24:27], v[150:153], v[208:211], v[24:27]
	v_mfma_f32_16x16x32_bf16 v[12:15], v[142:145], v[216:219], v[12:15]
	v_mfma_f32_16x16x32_bf16 v[8:11], v[150:153], v[216:219], v[8:11]
	v_mfma_f32_16x16x32_bf16 v[60:63], v[146:149], v[178:181], v[60:63]
	v_mfma_f32_16x16x32_bf16 v[56:59], v[154:157], v[178:181], v[56:59]
	v_mfma_f32_16x16x32_bf16 v[44:47], v[146:149], v[196:199], v[44:47]
	v_mfma_f32_16x16x32_bf16 v[40:43], v[154:157], v[196:199], v[40:43]
	v_mfma_f32_16x16x32_bf16 v[28:31], v[146:149], v[212:215], v[28:31]
	v_mfma_f32_16x16x32_bf16 v[24:27], v[154:157], v[212:215], v[24:27]
	v_mfma_f32_16x16x32_bf16 v[12:15], v[146:149], v[220:223], v[12:15]
	v_mfma_f32_16x16x32_bf16 v[8:11], v[154:157], v[220:223], v[8:11]
	v_mfma_f32_16x16x32_bf16 v[52:55], v[158:161], v[174:177], v[52:55]
	v_mfma_f32_16x16x32_bf16 v[48:51], v[166:169], v[174:177], v[48:51]
	v_mfma_f32_16x16x32_bf16 v[36:39], v[158:161], v[192:195], v[36:39]
	v_mfma_f32_16x16x32_bf16 v[32:35], v[166:169], v[192:195], v[32:35]
	v_mfma_f32_16x16x32_bf16 v[20:23], v[158:161], v[208:211], v[20:23]
	v_mfma_f32_16x16x32_bf16 v[16:19], v[166:169], v[208:211], v[16:19]
	v_mfma_f32_16x16x32_bf16 v[4:7], v[158:161], v[216:219], v[4:7]
	v_mfma_f32_16x16x32_bf16 v[0:3], v[166:169], v[216:219], v[0:3]
	v_mfma_f32_16x16x32_bf16 v[52:55], v[162:165], v[178:181], v[52:55]
	v_mfma_f32_16x16x32_bf16 v[48:51], v[170:173], v[178:181], v[48:51]
	v_mfma_f32_16x16x32_bf16 v[36:39], v[162:165], v[196:199], v[36:39]
	v_mfma_f32_16x16x32_bf16 v[32:35], v[170:173], v[196:199], v[32:35]
	v_mfma_f32_16x16x32_bf16 v[20:23], v[162:165], v[212:215], v[20:23]
	v_mfma_f32_16x16x32_bf16 v[16:19], v[170:173], v[212:215], v[16:19]
	v_mfma_f32_16x16x32_bf16 v[4:7], v[162:165], v[220:223], v[4:7]
	v_mfma_f32_16x16x32_bf16 v[0:3], v[170:173], v[220:223], v[0:3]
	s_setprio 0
	s_barrier
	s_add_i32 s21, s21, 2
	s_add_u32 s10, s10, 0x100
	s_addc_u32 s11, s11, 0
	s_cmp_gt_u32 s21, 29
	s_cbranch_scc0 .LBB0_822
	s_cmpk_lt_u32 s0, 0x100
	s_cbranch_scc0 .LBB0_825
	s_barrier

; #define PG8_STAGE(bufoff, gbase, voff) do { _Pragma("unroll") for (int _i = 0; _i < 2; ++_i) \
;         __builtin_amdgcn_global_load_lds((const unsigned*)((const char*)(gbase) + (voff)[_i]), (PG8_LAS unsigned*)(lds + (bufoff) + ldsw + _i * 8192), 16, 0, 0); } while (0)
; #define PG8_LDA(dst, b, h) do { _Pragma("unroll") for (int m = 0; m < 4; ++m) _Pragma("unroll") for (int k = 0; k < 2; ++k) dst[m][k] = *(const PG8_LAS bf16x8*)(lds + PG8_SA(b, h) + aoff + m * 2048 + k * 1024); } while (0)
; #define PG8_LDB(dst, b, h) do { _Pragma("unroll") for (int n = 0; n < 2; ++n) _Pragma("unroll") for (int k = 0; k < 2; ++k) dst[n][k] = *(const PG8_LAS bf16x8*)(lds + PG8_SB(b, h) + boff + n * 2048 + k * 1024); } while (0)
; #define PG8_MMA(ai, bj, At, Bt) do { __builtin_amdgcn_s_setprio(1); _Pragma("unroll") for (int m = 0; m < 4; ++m) _Pragma("unroll") for (int n = 0; n < 2; ++n) _Pragma("unroll") for (int k = 0; k < 2; ++k) \
;         acc[ai][bj][m][n] = __builtin_amdgcn_mfma_f32_16x16x32_bf16(Bt[n][k], At[m][k], acc[ai][bj][m][n], 0, 0, 0); __builtin_amdgcn_s_setprio(0); } while (0)
; #define PG8_WAIT_V(n) asm volatile("s_waitcnt vmcnt(" #n ")" ::: "memory")
; #define PG8_WAIT_L(n) asm volatile("s_waitcnt lgkmcnt(" #n ")" ::: "memory")
; template <class Epi, class Sched, bool ALIGN_EPI = false, bool SP2 = false>
; __device__ __forceinline__ void gemm_phase(PG8_LAS unsigned char* lds, const Gemm g, const Sched& S, const Epi& E) {
;     ...
;             const bool last = (t == nt - 2);
;             const char* a1 = cA + (size_t)(t + 1) * kstep;
;             const char* a2 = last ? nA : cA + (size_t)(t + 2) * kstep; const char* b2 = last ? nB : cB + (size_t)(t + 2) * kstep;
;             const char* a3 = a2 + kstep; const char* b3 = b2 + kstep;
;             if (last && has_next) S.a_ready(nxt);
;             if constexpr (SP2) {
;             PG8_LDB(B0, 0, 0); PG8_LDB(B1, 0, 1); PG8_SCHED; PG8_LDA(At, 0, 0); PG8_STAGE(PG8_SA(1, 1), a1 + hstep, voffA);
;             PG8_WAIT_V(8); PG8_WAIT_L(0); PG8_BAR; PG8_MMA(0, 0, At, B0); PG8_MMA(0, 1, At, B1); PG8_BAR; PG8_SCHED;
;             PG8_LDA(At, 0, 1); PG8_STAGE(PG8_SB(0, 0), b2, voffB); PG8_STAGE(PG8_SB(0, 1), b2 + hstep, voffB); PG8_STAGE(PG8_SA(0, 0), a2, voffA);
;             PG8_WAIT_V(8); PG8_WAIT_L(0); PG8_BAR; PG8_MMA(1, 0, At, B0); PG8_MMA(1, 1, At, B1); PG8_BAR; PG8_SCHED;
.LBB0_1078:
	s_add_u32 s26, s24, 0xfffc0080
	s_addc_u32 s27, s25, -1
	s_add_i32 s43, 0, 0x10000
	s_cmp_eq_u32 s42, 12
	s_cselect_b32 s29, s19, s27
	s_cselect_b32 s28, s38, s26
	s_cselect_b32 s27, s17, s41
	s_cselect_b32 s26, s39, s40
	s_add_i32 s46, 0, 0x14000
	v_add_u32_e32 v140, s43, v171
	v_add_u32_e32 v166, s46, v171
	ds_read_b128 v[128:131], v140
	ds_read_b128 v[132:135], v140 offset:1024
	ds_read_b128 v[136:139], v140 offset:2048
	ds_read_b128 v[140:143], v140 offset:3072
	ds_read_b128 v[144:147], v166
	ds_read_b128 v[158:161], v166 offset:1024
	ds_read_b128 v[162:165], v166 offset:2048
	ds_read_b128 v[166:169], v166 offset:3072
	v_lshl_add_u64 v[182:183], s[24:25], 0, v[154:155]
	s_add_i32 m0, s1, 0xc000
	ds_read_b128 v[174:177], v173
	ds_read_b128 v[178:181], v173 offset:1024
	ds_read_b128 v[192:195], v173 offset:2048
	ds_read_b128 v[196:199], v173 offset:3072
	ds_read_b128 v[208:211], v173 offset:4096
	ds_read_b128 v[212:215], v173 offset:5120
	ds_read_b128 v[216:219], v173 offset:6144
	ds_read_b128 v[220:223], v173 offset:7168
	global_load_lds_dwordx4 v[182:183], off
	v_lshl_add_u64 v[182:183], s[24:25], 0, v[156:157]
	s_add_i32 m0, s1, 0xe000
	s_nop 0
	global_load_lds_dwordx4 v[182:183], off
	s_waitcnt vmcnt(8)
	s_waitcnt lgkmcnt(0)
	s_barrier
	s_setprio 1
	s_waitcnt lgkmcnt(0)
	v_mfma_f32_16x16x32_bf16 v[124:127], v[128:131], v[174:177], v[124:127]
	v_mfma_f32_16x16x32_bf16 v[120:123], v[136:139], v[174:177], v[120:123]
	v_mfma_f32_16x16x32_bf16 v[116:119], v[128:131], v[192:195], v[116:119]
	v_mfma_f32_16x16x32_bf16 v[108:111], v[136:139], v[192:195], v[108:111]
	v_mfma_f32_16x16x32_bf16 v[96:99], v[128:131], v[208:211], v[96:99]
	v_mfma_f32_16x16x32_bf16 v[88:91], v[136:139], v[208:211], v[88:91]
	v_mfma_f32_16x16x32_bf16 v[80:83], v[128:131], v[216:219], v[80:83]
	v_mfma_f32_16x16x32_bf16 v[72:75], v[136:139], v[216:219], v[72:75]
	v_mfma_f32_16x16x32_bf16 v[124:127], v[132:135], v[178:181], v[124:127]
	v_mfma_f32_16x16x32_bf16 v[120:123], v[140:143], v[178:181], v[120:123]
	v_mfma_f32_16x16x32_bf16 v[116:119], v[132:135], v[196:199], v[116:119]
	v_mfma_f32_16x16x32_bf16 v[108:111], v[140:143], v[196:199], v[108:111]
	v_mfma_f32_16x16x32_bf16 v[96:99], v[132:135], v[212:215], v[96:99]
	v_mfma_f32_16x16x32_bf16 v[88:91], v[140:143], v[212:215], v[88:91]
	v_mfma_f32_16x16x32_bf16 v[80:83], v[132:135], v[220:223], v[80:83]
	v_mfma_f32_16x16x32_bf16 v[72:75], v[140:143], v[220:223], v[72:75]
	v_mfma_f32_16x16x32_bf16 v[112:115], v[144:147], v[174:177], v[112:115]
	v_mfma_f32_16x16x32_bf16 v[104:107], v[162:165], v[174:177], v[104:107]
	v_mfma_f32_16x16x32_bf16 v[100:103], v[144:147], v[192:195], v[100:103]
	v_mfma_f32_16x16x32_bf16 v[92:95], v[162:165], v[192:195], v[92:95]
	v_mfma_f32_16x16x32_bf16 v[84:87], v[144:147], v[208:211], v[84:87]
	v_mfma_f32_16x16x32_bf16 v[76:79], v[162:165], v[208:211], v[76:79]
	v_mfma_f32_16x16x32_bf16 v[68:71], v[144:147], v[216:219], v[68:71]
	v_mfma_f32_16x16x32_bf16 v[64:67], v[162:165], v[216:219], v[64:67]
	v_mfma_f32_16x16x32_bf16 v[112:115], v[158:161], v[178:181], v[112:115]
	v_mfma_f32_16x16x32_bf16 v[104:107], v[166:169], v[178:181], v[104:107]
	v_mfma_f32_16x16x32_bf16 v[100:103], v[158:161], v[196:199], v[100:103]
	v_mfma_f32_16x16x32_bf16 v[92:95], v[166:169], v[196:199], v[92:95]
	v_mfma_f32_16x16x32_bf16 v[84:87], v[158:161], v[212:215], v[84:87]
	v_mfma_f32_16x16x32_bf16 v[76:79], v[166:169], v[212:215], v[76:79]
	v_mfma_f32_16x16x32_bf16 v[68:71], v[158:161], v[220:223], v[68:71]
	v_mfma_f32_16x16x32_bf16 v[64:67], v[166:169], v[220:223], v[64:67]
	s_setprio 0
	s_barrier
	s_add_i32 s43, s43, s0
	v_lshl_add_u64 v[182:183], s[26:27], 0, v[186:187]
	s_mov_b32 m0, s43
	ds_read_b128 v[174:177], v173 offset:16384
	ds_read_b128 v[178:181], v173 offset:17408
	ds_read_b128 v[192:195], v173 offset:18432
	ds_read_b128 v[196:199], v173 offset:19456
	ds_read_b128 v[208:211], v173 offset:20480
	ds_read_b128 v[212:215], v173 offset:21504
	ds_read_b128 v[216:219], v173 offset:22528
	ds_read_b128 v[220:223], v173 offset:23552
	global_load_lds_dwordx4 v[182:183], off
	s_add_i32 m0, s43, 0x2000
	s_add_u32 s44, s26, 0x40000
	v_lshl_add_u64 v[188:189], s[26:27], 0, v[148:149]
	s_addc_u32 s45, s27, 0
	s_add_i32 s43, s46, s0
	global_load_lds_dwordx4 v[188:189], off
	v_lshl_add_u64 v[190:191], s[44:45], 0, v[186:187]
	s_mov_b32 m0, s43
	v_lshl_add_u64 v[224:225], s[28:29], 0, v[150:151]
	global_load_lds_dwordx4 v[190:191], off
	v_lshl_add_u64 v[190:191], s[44:45], 0, v[148:149]
	s_add_i32 m0, s43, 0x2000
	s_nop 0
	global_load_lds_dwordx4 v[190:191], off
	v_lshl_add_u64 v[190:191], s[28:29], 0, v[152:153]
	s_mov_b32 m0, s1
	s_nop 0
	global_load_lds_dwordx4 v[190:191], off
	s_mov_b32 m0, s3
	s_nop 0
	global_load_lds_dwordx4 v[224:225], off
	s_waitcnt vmcnt(8)
	s_waitcnt lgkmcnt(0)
	s_barrier
; #define PG8_STAGE(bufoff, gbase, voff) do { _Pragma("unroll") for (int _i = 0; _i < 2; ++_i) \
;         __builtin_amdgcn_global_load_lds((const unsigned*)((const char*)(gbase) + (voff)[_i]), (PG8_LAS unsigned*)(lds + (bufoff) + ldsw + _i * 8192), 16, 0, 0); } while (0)
; #define PG8_LDA(dst, b, h) do { _Pragma("unroll") for (int m = 0; m < 4; ++m) _Pragma("unroll") for (int k = 0; k < 2; ++k) dst[m][k] = *(const PG8_LAS bf16x8*)(lds + PG8_SA(b, h) + aoff + m * 2048 + k * 1024); } while (0)
; #define PG8_LDB(dst, b, h) do { _Pragma("unroll") for (int n = 0; n < 2; ++n) _Pragma("unroll") for (int k = 0; k < 2; ++k) dst[n][k] = *(const PG8_LAS bf16x8*)(lds + PG8_SB(b, h) + boff + n * 2048 + k * 1024); } while (0)
; #define PG8_MMA(ai, bj, At, Bt) do { __builtin_amdgcn_s_setprio(1); _Pragma("unroll") for (int m = 0; m < 4; ++m) _Pragma("unroll") for (int n = 0; n < 2; ++n) _Pragma("unroll") for (int k = 0; k < 2; ++k) \
;         acc[ai][bj][m][n] = __builtin_amdgcn_mfma_f32_16x16x32_bf16(Bt[n][k], At[m][k], acc[ai][bj][m][n], 0, 0, 0); __builtin_amdgcn_s_setprio(0); } while (0)
; #define PG8_WAIT_V(n) asm volatile("s_waitcnt vmcnt(" #n ")" ::: "memory")
; #define PG8_WAIT_L(n) asm volatile("s_waitcnt lgkmcnt(" #n ")" ::: "memory")
; #define PG8_BAR __builtin_amdgcn_s_barrier()
; #define PG8_SCHED __builtin_amdgcn_sched_barrier(0)
; template <class Epi, class Sched, bool ALIGN_EPI = false, bool SP2 = false>
; __device__ __forceinline__ void gemm_phase(PG8_LAS unsigned char* lds, const Gemm g, const Sched& S, const Epi& E) {
;     ...
;             PG8_LDA(At, 0, 1); PG8_STAGE(PG8_SB(0, 0), b2, voffB); PG8_STAGE(PG8_SB(0, 1), b2 + hstep, voffB); PG8_STAGE(PG8_SA(0, 0), a2, voffA);
;             PG8_WAIT_V(8); PG8_WAIT_L(0); PG8_BAR; PG8_MMA(1, 0, At, B0); PG8_MMA(1, 1, At, B1); PG8_BAR; PG8_SCHED;
;             PG8_LDB(B0, 1, 0); PG8_LDB(B1, 1, 1); PG8_SCHED; PG8_LDA(At, 1, 0); PG8_STAGE(PG8_SA(0, 1), a2 + hstep, voffA);
;             PG8_WAIT_V(8); PG8_WAIT_L(0); PG8_BAR; PG8_MMA(0, 0, At, B0); PG8_MMA(0, 1, At, B1); PG8_BAR; PG8_SCHED;
	s_setprio 1
	s_waitcnt lgkmcnt(0)
	v_mfma_f32_16x16x32_bf16 v[60:63], v[128:131], v[174:177], v[60:63]
	v_mfma_f32_16x16x32_bf16 v[56:59], v[136:139], v[174:177], v[56:59]
	v_mfma_f32_16x16x32_bf16 v[48:51], v[128:131], v[192:195], v[48:51]
	v_mfma_f32_16x16x32_bf16 v[40:43], v[136:139], v[192:195], v[40:43]
	v_mfma_f32_16x16x32_bf16 v[32:35], v[128:131], v[208:211], v[32:35]
	v_mfma_f32_16x16x32_bf16 v[24:27], v[136:139], v[208:211], v[24:27]
	v_mfma_f32_16x16x32_bf16 v[16:19], v[128:131], v[216:219], v[16:19]
	v_mfma_f32_16x16x32_bf16 v[8:11], v[136:139], v[216:219], v[8:11]
	v_mfma_f32_16x16x32_bf16 v[60:63], v[132:135], v[178:181], v[60:63]
	v_mfma_f32_16x16x32_bf16 v[56:59], v[140:143], v[178:181], v[56:59]
	v_mfma_f32_16x16x32_bf16 v[48:51], v[132:135], v[196:199], v[48:51]
	v_mfma_f32_16x16x32_bf16 v[40:43], v[140:143], v[196:199], v[40:43]
	v_mfma_f32_16x16x32_bf16 v[32:35], v[132:135], v[212:215], v[32:35]
	v_mfma_f32_16x16x32_bf16 v[24:27], v[140:143], v[212:215], v[24:27]
	v_mfma_f32_16x16x32_bf16 v[16:19], v[132:135], v[220:223], v[16:19]
	v_mfma_f32_16x16x32_bf16 v[8:11], v[140:143], v[220:223], v[8:11]
	v_mfma_f32_16x16x32_bf16 v[52:55], v[144:147], v[174:177], v[52:55]
	v_mfma_f32_16x16x32_bf16 v[44:47], v[162:165], v[174:177], v[44:47]
	v_mfma_f32_16x16x32_bf16 v[36:39], v[144:147], v[192:195], v[36:39]
	v_mfma_f32_16x16x32_bf16 v[28:31], v[162:165], v[192:195], v[28:31]
	v_mfma_f32_16x16x32_bf16 v[20:23], v[144:147], v[208:211], v[20:23]
	v_mfma_f32_16x16x32_bf16 v[12:15], v[162:165], v[208:211], v[12:15]
	v_mfma_f32_16x16x32_bf16 v[4:7], v[144:147], v[216:219], v[4:7]
	v_mfma_f32_16x16x32_bf16 v[0:3], v[162:165], v[216:219], v[0:3]
	v_mfma_f32_16x16x32_bf16 v[52:55], v[158:161], v[178:181], v[52:55]
	v_mfma_f32_16x16x32_bf16 v[44:47], v[166:169], v[178:181], v[44:47]
	v_mfma_f32_16x16x32_bf16 v[36:39], v[158:161], v[196:199], v[36:39]
	v_mfma_f32_16x16x32_bf16 v[28:31], v[166:169], v[196:199], v[28:31]
	v_mfma_f32_16x16x32_bf16 v[20:23], v[158:161], v[212:215], v[20:23]
	v_mfma_f32_16x16x32_bf16 v[12:15], v[166:169], v[212:215], v[12:15]
	v_mfma_f32_16x16x32_bf16 v[4:7], v[158:161], v[220:223], v[4:7]
	v_mfma_f32_16x16x32_bf16 v[0:3], v[166:169], v[220:223], v[0:3]
	s_setprio 0
	s_barrier
	s_add_i32 s43, 0, 0x18000
	s_add_i32 s44, 0, 0x1c000
	v_add_u32_e32 v140, s43, v171
	v_add_u32_e32 v166, s44, v171
	ds_read_b128 v[128:131], v140
	ds_read_b128 v[132:135], v140 offset:1024
	ds_read_b128 v[136:139], v140 offset:2048
	ds_read_b128 v[140:143], v140 offset:3072
	ds_read_b128 v[144:147], v166
	ds_read_b128 v[158:161], v166 offset:1024
	ds_read_b128 v[162:165], v166 offset:2048
	ds_read_b128 v[166:169], v166 offset:3072
	s_add_u32 s28, s28, 0x40000
	s_addc_u32 s29, s29, 0
	s_mov_b32 m0, s30
	v_lshl_add_u64 v[226:227], s[28:29], 0, v[152:153]
	ds_read_b128 v[174:177], v173 offset:32768
	ds_read_b128 v[178:181], v173 offset:33792
	ds_read_b128 v[192:195], v173 offset:34816
	ds_read_b128 v[196:199], v173 offset:35840
	ds_read_b128 v[208:211], v173 offset:36864
	ds_read_b128 v[212:215], v173 offset:37888
	ds_read_b128 v[216:219], v173 offset:38912
	ds_read_b128 v[220:223], v173 offset:39936
	global_load_lds_dwordx4 v[226:227], off
	v_lshl_add_u64 v[226:227], s[28:29], 0, v[150:151]
	s_mov_b32 m0, s31
	s_nop 0
	global_load_lds_dwordx4 v[226:227], off
	s_waitcnt vmcnt(8)
	s_waitcnt lgkmcnt(0)
	s_barrier
	s_setprio 1
	s_waitcnt lgkmcnt(0)
	v_mfma_f32_16x16x32_bf16 v[124:127], v[128:131], v[174:177], v[124:127]
	v_mfma_f32_16x16x32_bf16 v[120:123], v[136:139], v[174:177], v[120:123]
	v_mfma_f32_16x16x32_bf16 v[116:119], v[128:131], v[192:195], v[116:119]
	v_mfma_f32_16x16x32_bf16 v[108:111], v[136:139], v[192:195], v[108:111]
	v_mfma_f32_16x16x32_bf16 v[96:99], v[128:131], v[208:211], v[96:99]
	v_mfma_f32_16x16x32_bf16 v[88:91], v[136:139], v[208:211], v[88:91]
	v_mfma_f32_16x16x32_bf16 v[80:83], v[128:131], v[216:219], v[80:83]
	v_mfma_f32_16x16x32_bf16 v[72:75], v[136:139], v[216:219], v[72:75]
	v_mfma_f32_16x16x32_bf16 v[124:127], v[132:135], v[178:181], v[124:127]
	v_mfma_f32_16x16x32_bf16 v[120:123], v[140:143], v[178:181], v[120:123]
	v_mfma_f32_16x16x32_bf16 v[116:119], v[132:135], v[196:199], v[116:119]
	v_mfma_f32_16x16x32_bf16 v[108:111], v[140:143], v[196:199], v[108:111]
	v_mfma_f32_16x16x32_bf16 v[96:99], v[132:135], v[212:215], v[96:99]
	v_mfma_f32_16x16x32_bf16 v[88:91], v[140:143], v[212:215], v[88:91]
	v_mfma_f32_16x16x32_bf16 v[80:83], v[132:135], v[220:223], v[80:83]
	v_mfma_f32_16x16x32_bf16 v[72:75], v[140:143], v[220:223], v[72:75]
	v_mfma_f32_16x16x32_bf16 v[112:115], v[144:147], v[174:177], v[112:115]
	v_mfma_f32_16x16x32_bf16 v[104:107], v[162:165], v[174:177], v[104:107]
	v_mfma_f32_16x16x32_bf16 v[100:103], v[144:147], v[192:195], v[100:103]
	v_mfma_f32_16x16x32_bf16 v[92:95], v[162:165], v[192:195], v[92:95]
	v_mfma_f32_16x16x32_bf16 v[84:87], v[144:147], v[208:211], v[84:87]
	v_mfma_f32_16x16x32_bf16 v[76:79], v[162:165], v[208:211], v[76:79]
	v_mfma_f32_16x16x32_bf16 v[68:71], v[144:147], v[216:219], v[68:71]
	v_mfma_f32_16x16x32_bf16 v[64:67], v[162:165], v[216:219], v[64:67]
	v_mfma_f32_16x16x32_bf16 v[112:115], v[158:161], v[178:181], v[112:115]
	v_mfma_f32_16x16x32_bf16 v[104:107], v[166:169], v[178:181], v[104:107]
	v_mfma_f32_16x16x32_bf16 v[100:103], v[158:161], v[196:199], v[100:103]
	v_mfma_f32_16x16x32_bf16 v[92:95], v[166:169], v[196:199], v[92:95]
	v_mfma_f32_16x16x32_bf16 v[84:87], v[158:161], v[212:215], v[84:87]
	v_mfma_f32_16x16x32_bf16 v[76:79], v[166:169], v[212:215], v[76:79]
	v_mfma_f32_16x16x32_bf16 v[68:71], v[158:161], v[220:223], v[68:71]
	v_mfma_f32_16x16x32_bf16 v[64:67], v[166:169], v[220:223], v[64:67]
	s_setprio 0
	s_barrier
; #define PG8_STAGE(bufoff, gbase, voff) do { _Pragma("unroll") for (int _i = 0; _i < 2; ++_i) \
;         __builtin_amdgcn_global_load_lds((const unsigned*)((const char*)(gbase) + (voff)[_i]), (PG8_LAS unsigned*)(lds + (bufoff) + ldsw + _i * 8192), 16, 0, 0); } while (0)
; #define PG8_LDA(dst, b, h) do { _Pragma("unroll") for (int m = 0; m < 4; ++m) _Pragma("unroll") for (int k = 0; k < 2; ++k) dst[m][k] = *(const PG8_LAS bf16x8*)(lds + PG8_SA(b, h) + aoff + m * 2048 + k * 1024); } while (0)
; #define PG8_MMA(ai, bj, At, Bt) do { __builtin_amdgcn_s_setprio(1); _Pragma("unroll") for (int m = 0; m < 4; ++m) _Pragma("unroll") for (int n = 0; n < 2; ++n) _Pragma("unroll") for (int k = 0; k < 2; ++k) \
;         acc[ai][bj][m][n] = __builtin_amdgcn_mfma_f32_16x16x32_bf16(Bt[n][k], At[m][k], acc[ai][bj][m][n], 0, 0, 0); __builtin_amdgcn_s_setprio(0); } while (0)
; #define PG8_WAIT_V(n) asm volatile("s_waitcnt vmcnt(" #n ")" ::: "memory")
; #define PG8_WAIT_L(n) asm volatile("s_waitcnt lgkmcnt(" #n ")" ::: "memory")
; #define PG8_BAR __builtin_amdgcn_s_barrier()
; #define PG8_SCHED __builtin_amdgcn_sched_barrier(0)
; template <class Epi, class Sched, bool ALIGN_EPI = false, bool SP2 = false>
; __device__ __forceinline__ void gemm_phase(PG8_LAS unsigned char* lds, const Gemm g, const Sched& S, const Epi& E) {
;     ...
;             PG8_LDA(At, 1, 1); PG8_STAGE(PG8_SB(1, 0), b3, voffB); PG8_STAGE(PG8_SB(1, 1), b3 + hstep, voffB); PG8_STAGE(PG8_SA(1, 0), a3, voffA);
;             PG8_WAIT_V(8); PG8_WAIT_L(0); PG8_BAR; PG8_MMA(1, 0, At, B0); PG8_MMA(1, 1, At, B1); PG8_BAR; PG8_SCHED;
;     ...
;         }
;         if constexpr (ALIGN_EPI) { if (wr == 0) PG8_BAR; }
	s_add_i32 s28, s43, s0
	v_lshl_add_u64 v[182:183], v[182:183], 0, s[92:93]
	s_mov_b32 m0, s28
	ds_read_b128 v[174:177], v173 offset:49152
	ds_read_b128 v[178:181], v173 offset:50176
	ds_read_b128 v[192:195], v173 offset:51200
	ds_read_b128 v[196:199], v173 offset:52224
	ds_read_b128 v[208:211], v173 offset:53248
	ds_read_b128 v[212:215], v173 offset:54272
	ds_read_b128 v[216:219], v173 offset:55296
	ds_read_b128 v[220:223], v173 offset:56320
	global_load_lds_dwordx4 v[182:183], off
	s_add_i32 m0, s28, 0x2000
	s_add_u32 s26, s26, 0x40080
	v_lshl_add_u64 v[182:183], v[188:189], 0, s[92:93]
	s_addc_u32 s27, s27, 0
	s_add_i32 s28, s44, s0
	global_load_lds_dwordx4 v[182:183], off
	v_lshl_add_u64 v[182:183], s[26:27], 0, v[186:187]
	s_mov_b32 m0, s28
	s_nop 0
	global_load_lds_dwordx4 v[182:183], off
	v_lshl_add_u64 v[182:183], s[26:27], 0, v[148:149]
	s_add_i32 m0, s28, 0x2000
	s_nop 0
	global_load_lds_dwordx4 v[182:183], off
	v_lshl_add_u64 v[182:183], v[190:191], 0, s[92:93]
	s_mov_b32 m0, s34
	s_nop 0
	global_load_lds_dwordx4 v[182:183], off
	v_lshl_add_u64 v[182:183], v[224:225], 0, s[92:93]
	s_mov_b32 m0, s35
	s_nop 0
	global_load_lds_dwordx4 v[182:183], off
	s_waitcnt vmcnt(8)
	s_waitcnt lgkmcnt(0)
	s_barrier
	s_setprio 1
	s_waitcnt lgkmcnt(0)
	v_mfma_f32_16x16x32_bf16 v[60:63], v[128:131], v[174:177], v[60:63]
	v_mfma_f32_16x16x32_bf16 v[56:59], v[136:139], v[174:177], v[56:59]
	v_mfma_f32_16x16x32_bf16 v[48:51], v[128:131], v[192:195], v[48:51]
	v_mfma_f32_16x16x32_bf16 v[40:43], v[136:139], v[192:195], v[40:43]
	v_mfma_f32_16x16x32_bf16 v[32:35], v[128:131], v[208:211], v[32:35]
	v_mfma_f32_16x16x32_bf16 v[24:27], v[136:139], v[208:211], v[24:27]
	v_mfma_f32_16x16x32_bf16 v[16:19], v[128:131], v[216:219], v[16:19]
	v_mfma_f32_16x16x32_bf16 v[8:11], v[136:139], v[216:219], v[8:11]
	v_mfma_f32_16x16x32_bf16 v[60:63], v[132:135], v[178:181], v[60:63]
	v_mfma_f32_16x16x32_bf16 v[56:59], v[140:143], v[178:181], v[56:59]
	v_mfma_f32_16x16x32_bf16 v[48:51], v[132:135], v[196:199], v[48:51]
	v_mfma_f32_16x16x32_bf16 v[40:43], v[140:143], v[196:199], v[40:43]
	v_mfma_f32_16x16x32_bf16 v[32:35], v[132:135], v[212:215], v[32:35]
	v_mfma_f32_16x16x32_bf16 v[24:27], v[140:143], v[212:215], v[24:27]
	v_mfma_f32_16x16x32_bf16 v[16:19], v[132:135], v[220:223], v[16:19]
	v_mfma_f32_16x16x32_bf16 v[8:11], v[140:143], v[220:223], v[8:11]
	v_mfma_f32_16x16x32_bf16 v[52:55], v[144:147], v[174:177], v[52:55]
	v_mfma_f32_16x16x32_bf16 v[44:47], v[162:165], v[174:177], v[44:47]
	v_mfma_f32_16x16x32_bf16 v[36:39], v[144:147], v[192:195], v[36:39]
	v_mfma_f32_16x16x32_bf16 v[28:31], v[162:165], v[192:195], v[28:31]
	v_mfma_f32_16x16x32_bf16 v[20:23], v[144:147], v[208:211], v[20:23]
	v_mfma_f32_16x16x32_bf16 v[12:15], v[162:165], v[208:211], v[12:15]
	v_mfma_f32_16x16x32_bf16 v[4:7], v[144:147], v[216:219], v[4:7]
	v_mfma_f32_16x16x32_bf16 v[0:3], v[162:165], v[216:219], v[0:3]
	v_mfma_f32_16x16x32_bf16 v[52:55], v[158:161], v[178:181], v[52:55]
	v_mfma_f32_16x16x32_bf16 v[44:47], v[166:169], v[178:181], v[44:47]
	v_mfma_f32_16x16x32_bf16 v[36:39], v[158:161], v[196:199], v[36:39]
	v_mfma_f32_16x16x32_bf16 v[28:31], v[166:169], v[196:199], v[28:31]
	v_mfma_f32_16x16x32_bf16 v[20:23], v[158:161], v[212:215], v[20:23]
	v_mfma_f32_16x16x32_bf16 v[12:15], v[166:169], v[212:215], v[12:15]
	v_mfma_f32_16x16x32_bf16 v[4:7], v[158:161], v[220:223], v[4:7]
	v_mfma_f32_16x16x32_bf16 v[0:3], v[166:169], v[220:223], v[0:3]
	s_setprio 0
	s_barrier
	s_add_i32 s42, s42, 2
	s_add_u32 s24, s24, 0x100
	s_addc_u32 s25, s25, 0
	s_add_u32 s40, s40, 0x100
	s_addc_u32 s41, s41, 0
	s_cmp_gt_u32 s42, 13
	s_cbranch_scc0 .LBB0_1078
	s_and_b64 vcc, exec, s[14:15]
	s_cbranch_vccz .LBB0_1081
	s_barrier

; #define PG8_STAGE(bufoff, gbase, voff) do { _Pragma("unroll") for (int _i = 0; _i < 2; ++_i) \
;         __builtin_amdgcn_global_load_lds((const unsigned*)((const char*)(gbase) + (voff)[_i]), (PG8_LAS unsigned*)(lds + (bufoff) + ldsw + _i * 8192), 16, 0, 0); } while (0)
; #define PG8_LDA(dst, b, h) do { _Pragma("unroll") for (int m = 0; m < 4; ++m) _Pragma("unroll") for (int k = 0; k < 2; ++k) dst[m][k] = *(const PG8_LAS bf16x8*)(lds + PG8_SA(b, h) + aoff + m * 2048 + k * 1024); } while (0)
; #define PG8_LDB(dst, b, h) do { _Pragma("unroll") for (int n = 0; n < 2; ++n) _Pragma("unroll") for (int k = 0; k < 2; ++k) dst[n][k] = *(const PG8_LAS bf16x8*)(lds + PG8_SB(b, h) + boff + n * 2048 + k * 1024); } while (0)
; #define PG8_MMA(ai, bj, At, Bt) do { __builtin_amdgcn_s_setprio(1); _Pragma("unroll") for (int m = 0; m < 4; ++m) _Pragma("unroll") for (int n = 0; n < 2; ++n) _Pragma("unroll") for (int k = 0; k < 2; ++k) \
;         acc[ai][bj][m][n] = __builtin_amdgcn_mfma_f32_16x16x32_bf16(Bt[n][k], At[m][k], acc[ai][bj][m][n], 0, 0, 0); __builtin_amdgcn_s_setprio(0); } while (0)
; #define PG8_WAIT_V(n) asm volatile("s_waitcnt vmcnt(" #n ")" ::: "memory")
; #define PG8_WAIT_L(n) asm volatile("s_waitcnt lgkmcnt(" #n ")" ::: "memory")
; template <class Epi, class Sched, bool ALIGN_EPI = false, bool SP2 = false>
; __device__ __forceinline__ void gemm_phase(PG8_LAS unsigned char* lds, const Gemm g, const Sched& S, const Epi& E) {
;     ...
;             const bool last = (t == nt - 2);
;             const char* a1 = cA + (size_t)(t + 1) * kstep;
;             const char* a2 = last ? nA : cA + (size_t)(t + 2) * kstep; const char* b2 = last ? nB : cB + (size_t)(t + 2) * kstep;
;             const char* a3 = a2 + kstep; const char* b3 = b2 + kstep;
;             if (last && has_next) S.a_ready(nxt);
;             if constexpr (SP2) {
;             PG8_LDB(B0, 0, 0); PG8_LDB(B1, 0, 1); PG8_SCHED; PG8_LDA(At, 0, 0); PG8_STAGE(PG8_SA(1, 1), a1 + hstep, voffA);
;             PG8_WAIT_V(8); PG8_WAIT_L(0); PG8_BAR; PG8_MMA(0, 0, At, B0); PG8_MMA(0, 1, At, B1); PG8_BAR; PG8_SCHED;
;             PG8_LDA(At, 0, 1); PG8_STAGE(PG8_SB(0, 0), b2, voffB); PG8_STAGE(PG8_SB(0, 1), b2 + hstep, voffB); PG8_STAGE(PG8_SA(0, 0), a2, voffA);
;             PG8_WAIT_V(8); PG8_WAIT_L(0); PG8_BAR; PG8_MMA(1, 0, At, B0); PG8_MMA(1, 1, At, B1); PG8_BAR; PG8_SCHED;
.LBB0_1098:
	s_add_u32 s26, s24, 0xfffc0080
	s_addc_u32 s27, s25, -1
	s_add_i32 s43, 0, 0x10000
	s_cmp_eq_u32 s42, 12
	s_cselect_b32 s29, s19, s27
	s_cselect_b32 s28, s38, s26
	s_cselect_b32 s27, s17, s41
	s_cselect_b32 s26, s39, s40
	s_add_i32 s46, 0, 0x14000
	v_add_u32_e32 v140, s43, v209
	v_add_u32_e32 v156, s46, v209
	ds_read_b128 v[120:123], v140
	ds_read_b128 v[124:127], v140 offset:1024
	ds_read_b128 v[128:131], v140 offset:2048
	ds_read_b128 v[140:143], v140 offset:3072
	ds_read_b128 v[144:147], v156
	ds_read_b128 v[148:151], v156 offset:1024
	ds_read_b128 v[152:155], v156 offset:2048
	ds_read_b128 v[156:159], v156 offset:3072
	v_lshl_add_u64 v[182:183], s[24:25], 0, v[174:175]
	s_add_i32 m0, s1, 0xc000
	ds_read_b128 v[160:163], v211
	ds_read_b128 v[164:167], v211 offset:1024
	ds_read_b128 v[178:181], v211 offset:2048
	ds_read_b128 v[192:195], v211 offset:3072
	ds_read_b128 v[196:199], v211 offset:4096
	ds_read_b128 v[212:215], v211 offset:5120
	ds_read_b128 v[216:219], v211 offset:6144
	ds_read_b128 v[220:223], v211 offset:7168
	global_load_lds_dwordx4 v[182:183], off
	v_lshl_add_u64 v[182:183], s[24:25], 0, v[176:177]
	s_add_i32 m0, s1, 0xe000
	s_nop 0
	global_load_lds_dwordx4 v[182:183], off
	s_waitcnt vmcnt(8)
	s_waitcnt lgkmcnt(0)
	s_barrier
	s_setprio 1
	s_waitcnt lgkmcnt(0)
	v_mfma_f32_16x16x32_bf16 v[136:139], v[120:123], v[160:163], v[136:139]
	v_mfma_f32_16x16x32_bf16 v[132:135], v[128:131], v[160:163], v[132:135]
	v_mfma_f32_16x16x32_bf16 v[108:111], v[120:123], v[178:181], v[108:111]
	v_mfma_f32_16x16x32_bf16 v[104:107], v[128:131], v[178:181], v[104:107]
	v_mfma_f32_16x16x32_bf16 v[96:99], v[120:123], v[196:199], v[96:99]
	v_mfma_f32_16x16x32_bf16 v[88:91], v[128:131], v[196:199], v[88:91]
	v_mfma_f32_16x16x32_bf16 v[76:79], v[120:123], v[216:219], v[76:79]
	v_mfma_f32_16x16x32_bf16 v[72:75], v[128:131], v[216:219], v[72:75]
	v_mfma_f32_16x16x32_bf16 v[136:139], v[124:127], v[164:167], v[136:139]
	v_mfma_f32_16x16x32_bf16 v[132:135], v[140:143], v[164:167], v[132:135]
	v_mfma_f32_16x16x32_bf16 v[108:111], v[124:127], v[192:195], v[108:111]
	v_mfma_f32_16x16x32_bf16 v[104:107], v[140:143], v[192:195], v[104:107]
	v_mfma_f32_16x16x32_bf16 v[96:99], v[124:127], v[212:215], v[96:99]
	v_mfma_f32_16x16x32_bf16 v[88:91], v[140:143], v[212:215], v[88:91]
	v_mfma_f32_16x16x32_bf16 v[76:79], v[124:127], v[220:223], v[76:79]
	v_mfma_f32_16x16x32_bf16 v[72:75], v[140:143], v[220:223], v[72:75]
	v_mfma_f32_16x16x32_bf16 v[116:119], v[144:147], v[160:163], v[116:119]
	v_mfma_f32_16x16x32_bf16 v[112:115], v[152:155], v[160:163], v[112:115]
	v_mfma_f32_16x16x32_bf16 v[100:103], v[144:147], v[178:181], v[100:103]
	v_mfma_f32_16x16x32_bf16 v[92:95], v[152:155], v[178:181], v[92:95]
	v_mfma_f32_16x16x32_bf16 v[84:87], v[144:147], v[196:199], v[84:87]
	v_mfma_f32_16x16x32_bf16 v[80:83], v[152:155], v[196:199], v[80:83]
	v_mfma_f32_16x16x32_bf16 v[68:71], v[144:147], v[216:219], v[68:71]
	v_mfma_f32_16x16x32_bf16 v[64:67], v[152:155], v[216:219], v[64:67]
	v_mfma_f32_16x16x32_bf16 v[116:119], v[148:151], v[164:167], v[116:119]
	v_mfma_f32_16x16x32_bf16 v[112:115], v[156:159], v[164:167], v[112:115]
	v_mfma_f32_16x16x32_bf16 v[100:103], v[148:151], v[192:195], v[100:103]
	v_mfma_f32_16x16x32_bf16 v[92:95], v[156:159], v[192:195], v[92:95]
	v_mfma_f32_16x16x32_bf16 v[84:87], v[148:151], v[212:215], v[84:87]
	v_mfma_f32_16x16x32_bf16 v[80:83], v[156:159], v[212:215], v[80:83]
	v_mfma_f32_16x16x32_bf16 v[68:71], v[148:151], v[220:223], v[68:71]
	v_mfma_f32_16x16x32_bf16 v[64:67], v[156:159], v[220:223], v[64:67]
	s_setprio 0
	s_barrier
	s_add_i32 s43, s43, s0
	v_lshl_add_u64 v[182:183], s[26:27], 0, v[186:187]
	s_mov_b32 m0, s43
	ds_read_b128 v[160:163], v211 offset:16384
	ds_read_b128 v[164:167], v211 offset:17408
	ds_read_b128 v[178:181], v211 offset:18432
	ds_read_b128 v[192:195], v211 offset:19456
	ds_read_b128 v[196:199], v211 offset:20480
	ds_read_b128 v[212:215], v211 offset:21504
	ds_read_b128 v[216:219], v211 offset:22528
	ds_read_b128 v[220:223], v211 offset:23552
	global_load_lds_dwordx4 v[182:183], off
	s_add_i32 m0, s43, 0x2000
	s_add_u32 s44, s26, 0x40000
	v_lshl_add_u64 v[188:189], s[26:27], 0, v[168:169]
	s_addc_u32 s45, s27, 0
	s_add_i32 s43, s46, s0
	global_load_lds_dwordx4 v[188:189], off
	v_lshl_add_u64 v[190:191], s[44:45], 0, v[186:187]
	s_mov_b32 m0, s43
	v_lshl_add_u64 v[224:225], s[28:29], 0, v[170:171]
	global_load_lds_dwordx4 v[190:191], off
	v_lshl_add_u64 v[190:191], s[44:45], 0, v[168:169]
	s_add_i32 m0, s43, 0x2000
	s_nop 0
	global_load_lds_dwordx4 v[190:191], off
	v_lshl_add_u64 v[190:191], s[28:29], 0, v[172:173]
	s_mov_b32 m0, s1
	s_nop 0
	global_load_lds_dwordx4 v[190:191], off
	s_mov_b32 m0, s3
	s_nop 0
	global_load_lds_dwordx4 v[224:225], off
	s_waitcnt vmcnt(8)
	s_waitcnt lgkmcnt(0)
	s_barrier
; #define PG8_STAGE(bufoff, gbase, voff) do { _Pragma("unroll") for (int _i = 0; _i < 2; ++_i) \
;         __builtin_amdgcn_global_load_lds((const unsigned*)((const char*)(gbase) + (voff)[_i]), (PG8_LAS unsigned*)(lds + (bufoff) + ldsw + _i * 8192), 16, 0, 0); } while (0)
; #define PG8_LDA(dst, b, h) do { _Pragma("unroll") for (int m = 0; m < 4; ++m) _Pragma("unroll") for (int k = 0; k < 2; ++k) dst[m][k] = *(const PG8_LAS bf16x8*)(lds + PG8_SA(b, h) + aoff + m * 2048 + k * 1024); } while (0)
; #define PG8_LDB(dst, b, h) do { _Pragma("unroll") for (int n = 0; n < 2; ++n) _Pragma("unroll") for (int k = 0; k < 2; ++k) dst[n][k] = *(const PG8_LAS bf16x8*)(lds + PG8_SB(b, h) + boff + n * 2048 + k * 1024); } while (0)
; #define PG8_MMA(ai, bj, At, Bt) do { __builtin_amdgcn_s_setprio(1); _Pragma("unroll") for (int m = 0; m < 4; ++m) _Pragma("unroll") for (int n = 0; n < 2; ++n) _Pragma("unroll") for (int k = 0; k < 2; ++k) \
;         acc[ai][bj][m][n] = __builtin_amdgcn_mfma_f32_16x16x32_bf16(Bt[n][k], At[m][k], acc[ai][bj][m][n], 0, 0, 0); __builtin_amdgcn_s_setprio(0); } while (0)
; #define PG8_WAIT_V(n) asm volatile("s_waitcnt vmcnt(" #n ")" ::: "memory")
; #define PG8_WAIT_L(n) asm volatile("s_waitcnt lgkmcnt(" #n ")" ::: "memory")
; #define PG8_BAR __builtin_amdgcn_s_barrier()
; #define PG8_SCHED __builtin_amdgcn_sched_barrier(0)
; template <class Epi, class Sched, bool ALIGN_EPI = false, bool SP2 = false>
; __device__ __forceinline__ void gemm_phase(PG8_LAS unsigned char* lds, const Gemm g, const Sched& S, const Epi& E) {
;     ...
;             PG8_LDA(At, 0, 1); PG8_STAGE(PG8_SB(0, 0), b2, voffB); PG8_STAGE(PG8_SB(0, 1), b2 + hstep, voffB); PG8_STAGE(PG8_SA(0, 0), a2, voffA);
;             PG8_WAIT_V(8); PG8_WAIT_L(0); PG8_BAR; PG8_MMA(1, 0, At, B0); PG8_MMA(1, 1, At, B1); PG8_BAR; PG8_SCHED;
;             PG8_LDB(B0, 1, 0); PG8_LDB(B1, 1, 1); PG8_SCHED; PG8_LDA(At, 1, 0); PG8_STAGE(PG8_SA(0, 1), a2 + hstep, voffA);
;             PG8_WAIT_V(8); PG8_WAIT_L(0); PG8_BAR; PG8_MMA(0, 0, At, B0); PG8_MMA(0, 1, At, B1); PG8_BAR; PG8_SCHED;
	s_setprio 1
	s_waitcnt lgkmcnt(0)
	v_mfma_f32_16x16x32_bf16 v[60:63], v[120:123], v[160:163], v[60:63]
	v_mfma_f32_16x16x32_bf16 v[56:59], v[128:131], v[160:163], v[56:59]
	v_mfma_f32_16x16x32_bf16 v[44:47], v[120:123], v[178:181], v[44:47]
	v_mfma_f32_16x16x32_bf16 v[40:43], v[128:131], v[178:181], v[40:43]
	v_mfma_f32_16x16x32_bf16 v[28:31], v[120:123], v[196:199], v[28:31]
	v_mfma_f32_16x16x32_bf16 v[24:27], v[128:131], v[196:199], v[24:27]
	v_mfma_f32_16x16x32_bf16 v[12:15], v[120:123], v[216:219], v[12:15]
	v_mfma_f32_16x16x32_bf16 v[8:11], v[128:131], v[216:219], v[8:11]
	v_mfma_f32_16x16x32_bf16 v[60:63], v[124:127], v[164:167], v[60:63]
	v_mfma_f32_16x16x32_bf16 v[56:59], v[140:143], v[164:167], v[56:59]
	v_mfma_f32_16x16x32_bf16 v[44:47], v[124:127], v[192:195], v[44:47]
	v_mfma_f32_16x16x32_bf16 v[40:43], v[140:143], v[192:195], v[40:43]
	v_mfma_f32_16x16x32_bf16 v[28:31], v[124:127], v[212:215], v[28:31]
	v_mfma_f32_16x16x32_bf16 v[24:27], v[140:143], v[212:215], v[24:27]
	v_mfma_f32_16x16x32_bf16 v[12:15], v[124:127], v[220:223], v[12:15]
	v_mfma_f32_16x16x32_bf16 v[8:11], v[140:143], v[220:223], v[8:11]
	v_mfma_f32_16x16x32_bf16 v[52:55], v[144:147], v[160:163], v[52:55]
	v_mfma_f32_16x16x32_bf16 v[48:51], v[152:155], v[160:163], v[48:51]
	v_mfma_f32_16x16x32_bf16 v[36:39], v[144:147], v[178:181], v[36:39]
	v_mfma_f32_16x16x32_bf16 v[32:35], v[152:155], v[178:181], v[32:35]
	v_mfma_f32_16x16x32_bf16 v[20:23], v[144:147], v[196:199], v[20:23]
	v_mfma_f32_16x16x32_bf16 v[16:19], v[152:155], v[196:199], v[16:19]
	v_mfma_f32_16x16x32_bf16 v[4:7], v[144:147], v[216:219], v[4:7]
	v_mfma_f32_16x16x32_bf16 v[0:3], v[152:155], v[216:219], v[0:3]
	v_mfma_f32_16x16x32_bf16 v[52:55], v[148:151], v[164:167], v[52:55]
	v_mfma_f32_16x16x32_bf16 v[48:51], v[156:159], v[164:167], v[48:51]
	v_mfma_f32_16x16x32_bf16 v[36:39], v[148:151], v[192:195], v[36:39]
	v_mfma_f32_16x16x32_bf16 v[32:35], v[156:159], v[192:195], v[32:35]
	v_mfma_f32_16x16x32_bf16 v[20:23], v[148:151], v[212:215], v[20:23]
	v_mfma_f32_16x16x32_bf16 v[16:19], v[156:159], v[212:215], v[16:19]
	v_mfma_f32_16x16x32_bf16 v[4:7], v[148:151], v[220:223], v[4:7]
	v_mfma_f32_16x16x32_bf16 v[0:3], v[156:159], v[220:223], v[0:3]
	s_setprio 0
	s_barrier
	s_add_i32 s43, 0, 0x18000
	s_add_i32 s44, 0, 0x1c000
	v_add_u32_e32 v140, s43, v209
	v_add_u32_e32 v156, s44, v209
	ds_read_b128 v[120:123], v140
	ds_read_b128 v[124:127], v140 offset:1024
	ds_read_b128 v[128:131], v140 offset:2048
	ds_read_b128 v[140:143], v140 offset:3072
	ds_read_b128 v[144:147], v156
	ds_read_b128 v[148:151], v156 offset:1024
	ds_read_b128 v[152:155], v156 offset:2048
	ds_read_b128 v[156:159], v156 offset:3072
	s_add_u32 s28, s28, 0x40000
	s_addc_u32 s29, s29, 0
	s_mov_b32 m0, s30
	v_lshl_add_u64 v[226:227], s[28:29], 0, v[172:173]
	ds_read_b128 v[160:163], v211 offset:32768
	ds_read_b128 v[164:167], v211 offset:33792
	ds_read_b128 v[178:181], v211 offset:34816
	ds_read_b128 v[192:195], v211 offset:35840
	ds_read_b128 v[196:199], v211 offset:36864
	ds_read_b128 v[212:215], v211 offset:37888
	ds_read_b128 v[216:219], v211 offset:38912
	ds_read_b128 v[220:223], v211 offset:39936
	global_load_lds_dwordx4 v[226:227], off
	v_lshl_add_u64 v[226:227], s[28:29], 0, v[170:171]
	s_mov_b32 m0, s31
	s_nop 0
	global_load_lds_dwordx4 v[226:227], off
	s_waitcnt vmcnt(8)
	s_waitcnt lgkmcnt(0)
	s_barrier
	s_setprio 1
	s_waitcnt lgkmcnt(0)
	v_mfma_f32_16x16x32_bf16 v[136:139], v[120:123], v[160:163], v[136:139]
	v_mfma_f32_16x16x32_bf16 v[132:135], v[128:131], v[160:163], v[132:135]
	v_mfma_f32_16x16x32_bf16 v[108:111], v[120:123], v[178:181], v[108:111]
	v_mfma_f32_16x16x32_bf16 v[104:107], v[128:131], v[178:181], v[104:107]
	v_mfma_f32_16x16x32_bf16 v[96:99], v[120:123], v[196:199], v[96:99]
	v_mfma_f32_16x16x32_bf16 v[88:91], v[128:131], v[196:199], v[88:91]
	v_mfma_f32_16x16x32_bf16 v[76:79], v[120:123], v[216:219], v[76:79]
	v_mfma_f32_16x16x32_bf16 v[72:75], v[128:131], v[216:219], v[72:75]
	v_mfma_f32_16x16x32_bf16 v[136:139], v[124:127], v[164:167], v[136:139]
	v_mfma_f32_16x16x32_bf16 v[132:135], v[140:143], v[164:167], v[132:135]
	v_mfma_f32_16x16x32_bf16 v[108:111], v[124:127], v[192:195], v[108:111]
	v_mfma_f32_16x16x32_bf16 v[104:107], v[140:143], v[192:195], v[104:107]
	v_mfma_f32_16x16x32_bf16 v[96:99], v[124:127], v[212:215], v[96:99]
	v_mfma_f32_16x16x32_bf16 v[88:91], v[140:143], v[212:215], v[88:91]
	v_mfma_f32_16x16x32_bf16 v[76:79], v[124:127], v[220:223], v[76:79]
	v_mfma_f32_16x16x32_bf16 v[72:75], v[140:143], v[220:223], v[72:75]
	v_mfma_f32_16x16x32_bf16 v[116:119], v[144:147], v[160:163], v[116:119]
	v_mfma_f32_16x16x32_bf16 v[112:115], v[152:155], v[160:163], v[112:115]
	v_mfma_f32_16x16x32_bf16 v[100:103], v[144:147], v[178:181], v[100:103]
	v_mfma_f32_16x16x32_bf16 v[92:95], v[152:155], v[178:181], v[92:95]
	v_mfma_f32_16x16x32_bf16 v[84:87], v[144:147], v[196:199], v[84:87]
	v_mfma_f32_16x16x32_bf16 v[80:83], v[152:155], v[196:199], v[80:83]
	v_mfma_f32_16x16x32_bf16 v[68:71], v[144:147], v[216:219], v[68:71]
	v_mfma_f32_16x16x32_bf16 v[64:67], v[152:155], v[216:219], v[64:67]
	v_mfma_f32_16x16x32_bf16 v[116:119], v[148:151], v[164:167], v[116:119]
	v_mfma_f32_16x16x32_bf16 v[112:115], v[156:159], v[164:167], v[112:115]
	v_mfma_f32_16x16x32_bf16 v[100:103], v[148:151], v[192:195], v[100:103]
	v_mfma_f32_16x16x32_bf16 v[92:95], v[156:159], v[192:195], v[92:95]
	v_mfma_f32_16x16x32_bf16 v[84:87], v[148:151], v[212:215], v[84:87]
	v_mfma_f32_16x16x32_bf16 v[80:83], v[156:159], v[212:215], v[80:83]
	v_mfma_f32_16x16x32_bf16 v[68:71], v[148:151], v[220:223], v[68:71]
	v_mfma_f32_16x16x32_bf16 v[64:67], v[156:159], v[220:223], v[64:67]
	s_setprio 0
	s_barrier
; #define PG8_STAGE(bufoff, gbase, voff) do { _Pragma("unroll") for (int _i = 0; _i < 2; ++_i) \
;         __builtin_amdgcn_global_load_lds((const unsigned*)((const char*)(gbase) + (voff)[_i]), (PG8_LAS unsigned*)(lds + (bufoff) + ldsw + _i * 8192), 16, 0, 0); } while (0)
; #define PG8_LDA(dst, b, h) do { _Pragma("unroll") for (int m = 0; m < 4; ++m) _Pragma("unroll") for (int k = 0; k < 2; ++k) dst[m][k] = *(const PG8_LAS bf16x8*)(lds + PG8_SA(b, h) + aoff + m * 2048 + k * 1024); } while (0)
; #define PG8_MMA(ai, bj, At, Bt) do { __builtin_amdgcn_s_setprio(1); _Pragma("unroll") for (int m = 0; m < 4; ++m) _Pragma("unroll") for (int n = 0; n < 2; ++n) _Pragma("unroll") for (int k = 0; k < 2; ++k) \
;         acc[ai][bj][m][n] = __builtin_amdgcn_mfma_f32_16x16x32_bf16(Bt[n][k], At[m][k], acc[ai][bj][m][n], 0, 0, 0); __builtin_amdgcn_s_setprio(0); } while (0)
; #define PG8_WAIT_V(n) asm volatile("s_waitcnt vmcnt(" #n ")" ::: "memory")
; #define PG8_WAIT_L(n) asm volatile("s_waitcnt lgkmcnt(" #n ")" ::: "memory")
; #define PG8_BAR __builtin_amdgcn_s_barrier()
; #define PG8_SCHED __builtin_amdgcn_sched_barrier(0)
; template <class Epi, class Sched, bool ALIGN_EPI = false, bool SP2 = false>
; __device__ __forceinline__ void gemm_phase(PG8_LAS unsigned char* lds, const Gemm g, const Sched& S, const Epi& E) {
;     ...
;             PG8_LDA(At, 1, 1); PG8_STAGE(PG8_SB(1, 0), b3, voffB); PG8_STAGE(PG8_SB(1, 1), b3 + hstep, voffB); PG8_STAGE(PG8_SA(1, 0), a3, voffA);
;             PG8_WAIT_V(8); PG8_WAIT_L(0); PG8_BAR; PG8_MMA(1, 0, At, B0); PG8_MMA(1, 1, At, B1); PG8_BAR; PG8_SCHED;
;     ...
;         }
;         if constexpr (ALIGN_EPI) { if (wr == 0) PG8_BAR; }
	s_add_i32 s28, s43, s0
	v_lshl_add_u64 v[182:183], v[182:183], 0, s[92:93]
	s_mov_b32 m0, s28
	ds_read_b128 v[160:163], v211 offset:49152
	ds_read_b128 v[164:167], v211 offset:50176
	ds_read_b128 v[178:181], v211 offset:51200
	ds_read_b128 v[192:195], v211 offset:52224
	ds_read_b128 v[196:199], v211 offset:53248
	ds_read_b128 v[212:215], v211 offset:54272
	ds_read_b128 v[216:219], v211 offset:55296
	ds_read_b128 v[220:223], v211 offset:56320
	global_load_lds_dwordx4 v[182:183], off
	s_add_i32 m0, s28, 0x2000
	s_add_u32 s26, s26, 0x40080
	v_lshl_add_u64 v[182:183], v[188:189], 0, s[92:93]
	s_addc_u32 s27, s27, 0
	s_add_i32 s28, s44, s0
	global_load_lds_dwordx4 v[182:183], off
	v_lshl_add_u64 v[182:183], s[26:27], 0, v[186:187]
	s_mov_b32 m0, s28
	s_nop 0
	global_load_lds_dwordx4 v[182:183], off
	v_lshl_add_u64 v[182:183], s[26:27], 0, v[168:169]
	s_add_i32 m0, s28, 0x2000
	s_nop 0
	global_load_lds_dwordx4 v[182:183], off
	v_lshl_add_u64 v[182:183], v[190:191], 0, s[92:93]
	s_mov_b32 m0, s34
	s_nop 0
	global_load_lds_dwordx4 v[182:183], off
	v_lshl_add_u64 v[182:183], v[224:225], 0, s[92:93]
	s_mov_b32 m0, s35
	s_nop 0
	global_load_lds_dwordx4 v[182:183], off
	s_waitcnt vmcnt(8)
	s_waitcnt lgkmcnt(0)
	s_barrier
	s_setprio 1
	s_waitcnt lgkmcnt(0)
	v_mfma_f32_16x16x32_bf16 v[60:63], v[120:123], v[160:163], v[60:63]
	v_mfma_f32_16x16x32_bf16 v[56:59], v[128:131], v[160:163], v[56:59]
	v_mfma_f32_16x16x32_bf16 v[44:47], v[120:123], v[178:181], v[44:47]
	v_mfma_f32_16x16x32_bf16 v[40:43], v[128:131], v[178:181], v[40:43]
	v_mfma_f32_16x16x32_bf16 v[28:31], v[120:123], v[196:199], v[28:31]
	v_mfma_f32_16x16x32_bf16 v[24:27], v[128:131], v[196:199], v[24:27]
	v_mfma_f32_16x16x32_bf16 v[12:15], v[120:123], v[216:219], v[12:15]
	v_mfma_f32_16x16x32_bf16 v[8:11], v[128:131], v[216:219], v[8:11]
	v_mfma_f32_16x16x32_bf16 v[60:63], v[124:127], v[164:167], v[60:63]
	v_mfma_f32_16x16x32_bf16 v[56:59], v[140:143], v[164:167], v[56:59]
	v_mfma_f32_16x16x32_bf16 v[44:47], v[124:127], v[192:195], v[44:47]
	v_mfma_f32_16x16x32_bf16 v[40:43], v[140:143], v[192:195], v[40:43]
	v_mfma_f32_16x16x32_bf16 v[28:31], v[124:127], v[212:215], v[28:31]
	v_mfma_f32_16x16x32_bf16 v[24:27], v[140:143], v[212:215], v[24:27]
	v_mfma_f32_16x16x32_bf16 v[12:15], v[124:127], v[220:223], v[12:15]
	v_mfma_f32_16x16x32_bf16 v[8:11], v[140:143], v[220:223], v[8:11]
	v_mfma_f32_16x16x32_bf16 v[52:55], v[144:147], v[160:163], v[52:55]
	v_mfma_f32_16x16x32_bf16 v[48:51], v[152:155], v[160:163], v[48:51]
	v_mfma_f32_16x16x32_bf16 v[36:39], v[144:147], v[178:181], v[36:39]
	v_mfma_f32_16x16x32_bf16 v[32:35], v[152:155], v[178:181], v[32:35]
	v_mfma_f32_16x16x32_bf16 v[20:23], v[144:147], v[196:199], v[20:23]
	v_mfma_f32_16x16x32_bf16 v[16:19], v[152:155], v[196:199], v[16:19]
	v_mfma_f32_16x16x32_bf16 v[4:7], v[144:147], v[216:219], v[4:7]
	v_mfma_f32_16x16x32_bf16 v[0:3], v[152:155], v[216:219], v[0:3]
	v_mfma_f32_16x16x32_bf16 v[52:55], v[148:151], v[164:167], v[52:55]
	v_mfma_f32_16x16x32_bf16 v[48:51], v[156:159], v[164:167], v[48:51]
	v_mfma_f32_16x16x32_bf16 v[36:39], v[148:151], v[192:195], v[36:39]
	v_mfma_f32_16x16x32_bf16 v[32:35], v[156:159], v[192:195], v[32:35]
	v_mfma_f32_16x16x32_bf16 v[20:23], v[148:151], v[212:215], v[20:23]
	v_mfma_f32_16x16x32_bf16 v[16:19], v[156:159], v[212:215], v[16:19]
	v_mfma_f32_16x16x32_bf16 v[4:7], v[148:151], v[220:223], v[4:7]
	v_mfma_f32_16x16x32_bf16 v[0:3], v[156:159], v[220:223], v[0:3]
	s_setprio 0
	s_barrier
	s_add_i32 s42, s42, 2
	s_add_u32 s24, s24, 0x100
	s_addc_u32 s25, s25, 0
	s_add_u32 s40, s40, 0x100
	s_addc_u32 s41, s41, 0
	s_cmp_gt_u32 s42, 13
	s_cbranch_scc0 .LBB0_1098
	s_and_b64 vcc, exec, s[14:15]
	s_cbranch_vccz .LBB0_1101
	s_barrier

; #define PG8_STAGE(bufoff, gbase, voff) do { _Pragma("unroll") for (int _i = 0; _i < 2; ++_i) \
;         __builtin_amdgcn_global_load_lds((const unsigned*)((const char*)(gbase) + (voff)[_i]), (PG8_LAS unsigned*)(lds + (bufoff) + ldsw + _i * 8192), 16, 0, 0); } while (0)
; #define PG8_LDA(dst, b, h) do { _Pragma("unroll") for (int m = 0; m < 4; ++m) _Pragma("unroll") for (int k = 0; k < 2; ++k) dst[m][k] = *(const PG8_LAS bf16x8*)(lds + PG8_SA(b, h) + aoff + m * 2048 + k * 1024); } while (0)
; #define PG8_LDB(dst, b, h) do { _Pragma("unroll") for (int n = 0; n < 2; ++n) _Pragma("unroll") for (int k = 0; k < 2; ++k) dst[n][k] = *(const PG8_LAS bf16x8*)(lds + PG8_SB(b, h) + boff + n * 2048 + k * 1024); } while (0)
; #define PG8_MMA(ai, bj, At, Bt) do { __builtin_amdgcn_s_setprio(1); _Pragma("unroll") for (int m = 0; m < 4; ++m) _Pragma("unroll") for (int n = 0; n < 2; ++n) _Pragma("unroll") for (int k = 0; k < 2; ++k) \
;         acc[ai][bj][m][n] = __builtin_amdgcn_mfma_f32_16x16x32_bf16(Bt[n][k], At[m][k], acc[ai][bj][m][n], 0, 0, 0); __builtin_amdgcn_s_setprio(0); } while (0)
; #define PG8_WAIT_V(n) asm volatile("s_waitcnt vmcnt(" #n ")" ::: "memory")
; #define PG8_WAIT_L(n) asm volatile("s_waitcnt lgkmcnt(" #n ")" ::: "memory")
; template <class Epi, class Sched, bool ALIGN_EPI = false, bool SP2 = false>
; __device__ __forceinline__ void gemm_phase(PG8_LAS unsigned char* lds, const Gemm g, const Sched& S, const Epi& E) {
;     ...
;             const bool last = (t == nt - 2);
;             const char* a1 = cA + (size_t)(t + 1) * kstep;
;             const char* a2 = last ? nA : cA + (size_t)(t + 2) * kstep; const char* b2 = last ? nB : cB + (size_t)(t + 2) * kstep;
;             const char* a3 = a2 + kstep; const char* b3 = b2 + kstep;
;             if (last && has_next) S.a_ready(nxt);
;             if constexpr (SP2) {
;             PG8_LDB(B0, 0, 0); PG8_LDB(B1, 0, 1); PG8_SCHED; PG8_LDA(At, 0, 0); PG8_STAGE(PG8_SA(1, 1), a1 + hstep, voffA);
;             PG8_WAIT_V(8); PG8_WAIT_L(0); PG8_BAR; PG8_MMA(0, 0, At, B0); PG8_MMA(0, 1, At, B1); PG8_BAR; PG8_SCHED;
;             PG8_LDA(At, 0, 1); PG8_STAGE(PG8_SB(0, 0), b2, voffB); PG8_STAGE(PG8_SB(0, 1), b2 + hstep, voffB); PG8_STAGE(PG8_SA(0, 0), a2, voffA);
;             PG8_WAIT_V(8); PG8_WAIT_L(0); PG8_BAR; PG8_MMA(1, 0, At, B0); PG8_MMA(1, 1, At, B1); PG8_BAR; PG8_SCHED;
.LBB0_1170:
	s_add_u32 s26, s24, 0xfffc0080
	s_addc_u32 s27, s25, -1
	s_add_i32 s43, 0, 0x10000
	s_cmp_eq_u32 s42, 12
	s_cselect_b32 s29, s19, s27
	s_cselect_b32 s28, s38, s26
	s_cselect_b32 s27, s17, s41
	s_cselect_b32 s26, s39, s40
	s_add_i32 s46, 0, 0x14000
	v_add_u32_e32 v140, s43, v192
	v_add_u32_e32 v166, s46, v192
	ds_read_b128 v[128:131], v140
	ds_read_b128 v[132:135], v140 offset:1024
	ds_read_b128 v[136:139], v140 offset:2048
	ds_read_b128 v[140:143], v140 offset:3072
	ds_read_b128 v[144:147], v166
	ds_read_b128 v[148:151], v166 offset:1024
	ds_read_b128 v[152:155], v166 offset:2048
	ds_read_b128 v[166:169], v166 offset:3072
	v_lshl_add_u64 v[182:183], s[24:25], 0, v[162:163]
	s_add_i32 m0, s1, 0xc000
	ds_read_b128 v[170:173], v195
	ds_read_b128 v[174:177], v195 offset:1024
	ds_read_b128 v[178:181], v195 offset:2048
	ds_read_b128 v[196:199], v195 offset:3072
	ds_read_b128 v[208:211], v195 offset:4096
	ds_read_b128 v[212:215], v195 offset:5120
	ds_read_b128 v[216:219], v195 offset:6144
	ds_read_b128 v[220:223], v195 offset:7168
	global_load_lds_dwordx4 v[182:183], off
	v_lshl_add_u64 v[182:183], s[24:25], 0, v[164:165]
	s_add_i32 m0, s1, 0xe000
	s_nop 0
	global_load_lds_dwordx4 v[182:183], off
	s_waitcnt vmcnt(8)
	s_waitcnt lgkmcnt(0)
	s_barrier
	s_setprio 1
	s_waitcnt lgkmcnt(0)
	v_mfma_f32_16x16x32_bf16 v[124:127], v[128:131], v[170:173], v[124:127]
	v_mfma_f32_16x16x32_bf16 v[120:123], v[136:139], v[170:173], v[120:123]
	v_mfma_f32_16x16x32_bf16 v[108:111], v[128:131], v[178:181], v[108:111]
	v_mfma_f32_16x16x32_bf16 v[104:107], v[136:139], v[178:181], v[104:107]
	v_mfma_f32_16x16x32_bf16 v[92:95], v[128:131], v[208:211], v[92:95]
	v_mfma_f32_16x16x32_bf16 v[88:91], v[136:139], v[208:211], v[88:91]
	v_mfma_f32_16x16x32_bf16 v[76:79], v[128:131], v[216:219], v[76:79]
	v_mfma_f32_16x16x32_bf16 v[72:75], v[136:139], v[216:219], v[72:75]
	v_mfma_f32_16x16x32_bf16 v[124:127], v[132:135], v[174:177], v[124:127]
	v_mfma_f32_16x16x32_bf16 v[120:123], v[140:143], v[174:177], v[120:123]
	v_mfma_f32_16x16x32_bf16 v[108:111], v[132:135], v[196:199], v[108:111]
	v_mfma_f32_16x16x32_bf16 v[104:107], v[140:143], v[196:199], v[104:107]
	v_mfma_f32_16x16x32_bf16 v[92:95], v[132:135], v[212:215], v[92:95]
	v_mfma_f32_16x16x32_bf16 v[88:91], v[140:143], v[212:215], v[88:91]
	v_mfma_f32_16x16x32_bf16 v[76:79], v[132:135], v[220:223], v[76:79]
	v_mfma_f32_16x16x32_bf16 v[72:75], v[140:143], v[220:223], v[72:75]
	v_mfma_f32_16x16x32_bf16 v[116:119], v[144:147], v[170:173], v[116:119]
	v_mfma_f32_16x16x32_bf16 v[112:115], v[152:155], v[170:173], v[112:115]
	v_mfma_f32_16x16x32_bf16 v[100:103], v[144:147], v[178:181], v[100:103]
	v_mfma_f32_16x16x32_bf16 v[96:99], v[152:155], v[178:181], v[96:99]
	v_mfma_f32_16x16x32_bf16 v[84:87], v[144:147], v[208:211], v[84:87]
	v_mfma_f32_16x16x32_bf16 v[80:83], v[152:155], v[208:211], v[80:83]
	v_mfma_f32_16x16x32_bf16 v[68:71], v[144:147], v[216:219], v[68:71]
	v_mfma_f32_16x16x32_bf16 v[64:67], v[152:155], v[216:219], v[64:67]
	v_mfma_f32_16x16x32_bf16 v[116:119], v[148:151], v[174:177], v[116:119]
	v_mfma_f32_16x16x32_bf16 v[112:115], v[166:169], v[174:177], v[112:115]
	v_mfma_f32_16x16x32_bf16 v[100:103], v[148:151], v[196:199], v[100:103]
	v_mfma_f32_16x16x32_bf16 v[96:99], v[166:169], v[196:199], v[96:99]
	v_mfma_f32_16x16x32_bf16 v[84:87], v[148:151], v[212:215], v[84:87]
	v_mfma_f32_16x16x32_bf16 v[80:83], v[166:169], v[212:215], v[80:83]
	v_mfma_f32_16x16x32_bf16 v[68:71], v[148:151], v[220:223], v[68:71]
	v_mfma_f32_16x16x32_bf16 v[64:67], v[166:169], v[220:223], v[64:67]
	s_setprio 0
	s_barrier
	s_add_i32 s43, s43, s0
	v_lshl_add_u64 v[182:183], s[26:27], 0, v[186:187]
	s_mov_b32 m0, s43
	ds_read_b128 v[170:173], v195 offset:16384
	ds_read_b128 v[174:177], v195 offset:17408
	ds_read_b128 v[178:181], v195 offset:18432
	ds_read_b128 v[196:199], v195 offset:19456
	ds_read_b128 v[208:211], v195 offset:20480
	ds_read_b128 v[212:215], v195 offset:21504
	ds_read_b128 v[216:219], v195 offset:22528
	ds_read_b128 v[220:223], v195 offset:23552
	global_load_lds_dwordx4 v[182:183], off
	s_add_i32 m0, s43, 0x2000
	s_add_u32 s44, s26, 0x40000
	v_lshl_add_u64 v[188:189], s[26:27], 0, v[156:157]
	s_addc_u32 s45, s27, 0
	s_add_i32 s43, s46, s0
	global_load_lds_dwordx4 v[188:189], off
	v_lshl_add_u64 v[190:191], s[44:45], 0, v[186:187]
	s_mov_b32 m0, s43
	v_lshl_add_u64 v[224:225], s[28:29], 0, v[158:159]
	global_load_lds_dwordx4 v[190:191], off
	v_lshl_add_u64 v[190:191], s[44:45], 0, v[156:157]
	s_add_i32 m0, s43, 0x2000
	s_nop 0
	global_load_lds_dwordx4 v[190:191], off
	v_lshl_add_u64 v[190:191], s[28:29], 0, v[160:161]
	s_mov_b32 m0, s1
	s_nop 0
	global_load_lds_dwordx4 v[190:191], off
	s_mov_b32 m0, s3
	s_nop 0
	global_load_lds_dwordx4 v[224:225], off
	s_waitcnt vmcnt(8)
	s_waitcnt lgkmcnt(0)
	s_barrier
; #define PG8_STAGE(bufoff, gbase, voff) do { _Pragma("unroll") for (int _i = 0; _i < 2; ++_i) \
;         __builtin_amdgcn_global_load_lds((const unsigned*)((const char*)(gbase) + (voff)[_i]), (PG8_LAS unsigned*)(lds + (bufoff) + ldsw + _i * 8192), 16, 0, 0); } while (0)
; #define PG8_LDA(dst, b, h) do { _Pragma("unroll") for (int m = 0; m < 4; ++m) _Pragma("unroll") for (int k = 0; k < 2; ++k) dst[m][k] = *(const PG8_LAS bf16x8*)(lds + PG8_SA(b, h) + aoff + m * 2048 + k * 1024); } while (0)
; #define PG8_LDB(dst, b, h) do { _Pragma("unroll") for (int n = 0; n < 2; ++n) _Pragma("unroll") for (int k = 0; k < 2; ++k) dst[n][k] = *(const PG8_LAS bf16x8*)(lds + PG8_SB(b, h) + boff + n * 2048 + k * 1024); } while (0)
; #define PG8_MMA(ai, bj, At, Bt) do { __builtin_amdgcn_s_setprio(1); _Pragma("unroll") for (int m = 0; m < 4; ++m) _Pragma("unroll") for (int n = 0; n < 2; ++n) _Pragma("unroll") for (int k = 0; k < 2; ++k) \
;         acc[ai][bj][m][n] = __builtin_amdgcn_mfma_f32_16x16x32_bf16(Bt[n][k], At[m][k], acc[ai][bj][m][n], 0, 0, 0); __builtin_amdgcn_s_setprio(0); } while (0)
; #define PG8_WAIT_V(n) asm volatile("s_waitcnt vmcnt(" #n ")" ::: "memory")
; #define PG8_WAIT_L(n) asm volatile("s_waitcnt lgkmcnt(" #n ")" ::: "memory")
; #define PG8_BAR __builtin_amdgcn_s_barrier()
; #define PG8_SCHED __builtin_amdgcn_sched_barrier(0)
; template <class Epi, class Sched, bool ALIGN_EPI = false, bool SP2 = false>
; __device__ __forceinline__ void gemm_phase(PG8_LAS unsigned char* lds, const Gemm g, const Sched& S, const Epi& E) {
;     ...
;             PG8_LDA(At, 0, 1); PG8_STAGE(PG8_SB(0, 0), b2, voffB); PG8_STAGE(PG8_SB(0, 1), b2 + hstep, voffB); PG8_STAGE(PG8_SA(0, 0), a2, voffA);
;             PG8_WAIT_V(8); PG8_WAIT_L(0); PG8_BAR; PG8_MMA(1, 0, At, B0); PG8_MMA(1, 1, At, B1); PG8_BAR; PG8_SCHED;
;             PG8_LDB(B0, 1, 0); PG8_LDB(B1, 1, 1); PG8_SCHED; PG8_LDA(At, 1, 0); PG8_STAGE(PG8_SA(0, 1), a2 + hstep, voffA);
;             PG8_WAIT_V(8); PG8_WAIT_L(0); PG8_BAR; PG8_MMA(0, 0, At, B0); PG8_MMA(0, 1, At, B1); PG8_BAR; PG8_SCHED;
	s_setprio 1
	s_waitcnt lgkmcnt(0)
	v_mfma_f32_16x16x32_bf16 v[60:63], v[128:131], v[170:173], v[60:63]
	v_mfma_f32_16x16x32_bf16 v[56:59], v[136:139], v[170:173], v[56:59]
	v_mfma_f32_16x16x32_bf16 v[44:47], v[128:131], v[178:181], v[44:47]
	v_mfma_f32_16x16x32_bf16 v[40:43], v[136:139], v[178:181], v[40:43]
	v_mfma_f32_16x16x32_bf16 v[28:31], v[128:131], v[208:211], v[28:31]
	v_mfma_f32_16x16x32_bf16 v[24:27], v[136:139], v[208:211], v[24:27]
	v_mfma_f32_16x16x32_bf16 v[12:15], v[128:131], v[216:219], v[12:15]
	v_mfma_f32_16x16x32_bf16 v[8:11], v[136:139], v[216:219], v[8:11]
	v_mfma_f32_16x16x32_bf16 v[60:63], v[132:135], v[174:177], v[60:63]
	v_mfma_f32_16x16x32_bf16 v[56:59], v[140:143], v[174:177], v[56:59]
	v_mfma_f32_16x16x32_bf16 v[44:47], v[132:135], v[196:199], v[44:47]
	v_mfma_f32_16x16x32_bf16 v[40:43], v[140:143], v[196:199], v[40:43]
	v_mfma_f32_16x16x32_bf16 v[28:31], v[132:135], v[212:215], v[28:31]
	v_mfma_f32_16x16x32_bf16 v[24:27], v[140:143], v[212:215], v[24:27]
	v_mfma_f32_16x16x32_bf16 v[12:15], v[132:135], v[220:223], v[12:15]
	v_mfma_f32_16x16x32_bf16 v[8:11], v[140:143], v[220:223], v[8:11]
	v_mfma_f32_16x16x32_bf16 v[52:55], v[144:147], v[170:173], v[52:55]
	v_mfma_f32_16x16x32_bf16 v[48:51], v[152:155], v[170:173], v[48:51]
	v_mfma_f32_16x16x32_bf16 v[36:39], v[144:147], v[178:181], v[36:39]
	v_mfma_f32_16x16x32_bf16 v[32:35], v[152:155], v[178:181], v[32:35]
	v_mfma_f32_16x16x32_bf16 v[20:23], v[144:147], v[208:211], v[20:23]
	v_mfma_f32_16x16x32_bf16 v[16:19], v[152:155], v[208:211], v[16:19]
	v_mfma_f32_16x16x32_bf16 v[4:7], v[144:147], v[216:219], v[4:7]
	v_mfma_f32_16x16x32_bf16 v[0:3], v[152:155], v[216:219], v[0:3]
	v_mfma_f32_16x16x32_bf16 v[52:55], v[148:151], v[174:177], v[52:55]
	v_mfma_f32_16x16x32_bf16 v[48:51], v[166:169], v[174:177], v[48:51]
	v_mfma_f32_16x16x32_bf16 v[36:39], v[148:151], v[196:199], v[36:39]
	v_mfma_f32_16x16x32_bf16 v[32:35], v[166:169], v[196:199], v[32:35]
	v_mfma_f32_16x16x32_bf16 v[20:23], v[148:151], v[212:215], v[20:23]
	v_mfma_f32_16x16x32_bf16 v[16:19], v[166:169], v[212:215], v[16:19]
	v_mfma_f32_16x16x32_bf16 v[4:7], v[148:151], v[220:223], v[4:7]
	v_mfma_f32_16x16x32_bf16 v[0:3], v[166:169], v[220:223], v[0:3]
	s_setprio 0
	s_barrier
	s_add_i32 s43, 0, 0x18000
	s_add_i32 s44, 0, 0x1c000
	v_add_u32_e32 v140, s43, v192
	v_add_u32_e32 v166, s44, v192
	ds_read_b128 v[128:131], v140
	ds_read_b128 v[132:135], v140 offset:1024
	ds_read_b128 v[136:139], v140 offset:2048
	ds_read_b128 v[140:143], v140 offset:3072
	ds_read_b128 v[144:147], v166
	ds_read_b128 v[148:151], v166 offset:1024
	ds_read_b128 v[152:155], v166 offset:2048
	ds_read_b128 v[166:169], v166 offset:3072
	s_add_u32 s28, s28, 0x40000
	s_addc_u32 s29, s29, 0
	s_mov_b32 m0, s30
	v_lshl_add_u64 v[226:227], s[28:29], 0, v[160:161]
	ds_read_b128 v[170:173], v195 offset:32768
	ds_read_b128 v[174:177], v195 offset:33792
	ds_read_b128 v[178:181], v195 offset:34816
	ds_read_b128 v[196:199], v195 offset:35840
	ds_read_b128 v[208:211], v195 offset:36864
	ds_read_b128 v[212:215], v195 offset:37888
	ds_read_b128 v[216:219], v195 offset:38912
	ds_read_b128 v[220:223], v195 offset:39936
	global_load_lds_dwordx4 v[226:227], off
	v_lshl_add_u64 v[226:227], s[28:29], 0, v[158:159]
	s_mov_b32 m0, s31
	s_nop 0
	global_load_lds_dwordx4 v[226:227], off
	s_waitcnt vmcnt(8)
	s_waitcnt lgkmcnt(0)
	s_barrier
	s_setprio 1
	s_waitcnt lgkmcnt(0)
	v_mfma_f32_16x16x32_bf16 v[124:127], v[128:131], v[170:173], v[124:127]
	v_mfma_f32_16x16x32_bf16 v[120:123], v[136:139], v[170:173], v[120:123]
	v_mfma_f32_16x16x32_bf16 v[108:111], v[128:131], v[178:181], v[108:111]
	v_mfma_f32_16x16x32_bf16 v[104:107], v[136:139], v[178:181], v[104:107]
	v_mfma_f32_16x16x32_bf16 v[92:95], v[128:131], v[208:211], v[92:95]
	v_mfma_f32_16x16x32_bf16 v[88:91], v[136:139], v[208:211], v[88:91]
	v_mfma_f32_16x16x32_bf16 v[76:79], v[128:131], v[216:219], v[76:79]
	v_mfma_f32_16x16x32_bf16 v[72:75], v[136:139], v[216:219], v[72:75]
	v_mfma_f32_16x16x32_bf16 v[124:127], v[132:135], v[174:177], v[124:127]
	v_mfma_f32_16x16x32_bf16 v[120:123], v[140:143], v[174:177], v[120:123]
	v_mfma_f32_16x16x32_bf16 v[108:111], v[132:135], v[196:199], v[108:111]
	v_mfma_f32_16x16x32_bf16 v[104:107], v[140:143], v[196:199], v[104:107]
	v_mfma_f32_16x16x32_bf16 v[92:95], v[132:135], v[212:215], v[92:95]
	v_mfma_f32_16x16x32_bf16 v[88:91], v[140:143], v[212:215], v[88:91]
	v_mfma_f32_16x16x32_bf16 v[76:79], v[132:135], v[220:223], v[76:79]
	v_mfma_f32_16x16x32_bf16 v[72:75], v[140:143], v[220:223], v[72:75]
	v_mfma_f32_16x16x32_bf16 v[116:119], v[144:147], v[170:173], v[116:119]
	v_mfma_f32_16x16x32_bf16 v[112:115], v[152:155], v[170:173], v[112:115]
	v_mfma_f32_16x16x32_bf16 v[100:103], v[144:147], v[178:181], v[100:103]
	v_mfma_f32_16x16x32_bf16 v[96:99], v[152:155], v[178:181], v[96:99]
	v_mfma_f32_16x16x32_bf16 v[84:87], v[144:147], v[208:211], v[84:87]
	v_mfma_f32_16x16x32_bf16 v[80:83], v[152:155], v[208:211], v[80:83]
	v_mfma_f32_16x16x32_bf16 v[68:71], v[144:147], v[216:219], v[68:71]
	v_mfma_f32_16x16x32_bf16 v[64:67], v[152:155], v[216:219], v[64:67]
	v_mfma_f32_16x16x32_bf16 v[116:119], v[148:151], v[174:177], v[116:119]
	v_mfma_f32_16x16x32_bf16 v[112:115], v[166:169], v[174:177], v[112:115]
	v_mfma_f32_16x16x32_bf16 v[100:103], v[148:151], v[196:199], v[100:103]
	v_mfma_f32_16x16x32_bf16 v[96:99], v[166:169], v[196:199], v[96:99]
	v_mfma_f32_16x16x32_bf16 v[84:87], v[148:151], v[212:215], v[84:87]
	v_mfma_f32_16x16x32_bf16 v[80:83], v[166:169], v[212:215], v[80:83]
	v_mfma_f32_16x16x32_bf16 v[68:71], v[148:151], v[220:223], v[68:71]
	v_mfma_f32_16x16x32_bf16 v[64:67], v[166:169], v[220:223], v[64:67]
	s_setprio 0
	s_barrier
; #define PG8_STAGE(bufoff, gbase, voff) do { _Pragma("unroll") for (int _i = 0; _i < 2; ++_i) \
;         __builtin_amdgcn_global_load_lds((const unsigned*)((const char*)(gbase) + (voff)[_i]), (PG8_LAS unsigned*)(lds + (bufoff) + ldsw + _i * 8192), 16, 0, 0); } while (0)
; #define PG8_LDA(dst, b, h) do { _Pragma("unroll") for (int m = 0; m < 4; ++m) _Pragma("unroll") for (int k = 0; k < 2; ++k) dst[m][k] = *(const PG8_LAS bf16x8*)(lds + PG8_SA(b, h) + aoff + m * 2048 + k * 1024); } while (0)
; #define PG8_MMA(ai, bj, At, Bt) do { __builtin_amdgcn_s_setprio(1); _Pragma("unroll") for (int m = 0; m < 4; ++m) _Pragma("unroll") for (int n = 0; n < 2; ++n) _Pragma("unroll") for (int k = 0; k < 2; ++k) \
;         acc[ai][bj][m][n] = __builtin_amdgcn_mfma_f32_16x16x32_bf16(Bt[n][k], At[m][k], acc[ai][bj][m][n], 0, 0, 0); __builtin_amdgcn_s_setprio(0); } while (0)
; #define PG8_WAIT_V(n) asm volatile("s_waitcnt vmcnt(" #n ")" ::: "memory")
; #define PG8_WAIT_L(n) asm volatile("s_waitcnt lgkmcnt(" #n ")" ::: "memory")
; #define PG8_BAR __builtin_amdgcn_s_barrier()
; #define PG8_SCHED __builtin_amdgcn_sched_barrier(0)
; template <class Epi, class Sched, bool ALIGN_EPI = false, bool SP2 = false>
; __device__ __forceinline__ void gemm_phase(PG8_LAS unsigned char* lds, const Gemm g, const Sched& S, const Epi& E) {
;     ...
;             PG8_LDA(At, 1, 1); PG8_STAGE(PG8_SB(1, 0), b3, voffB); PG8_STAGE(PG8_SB(1, 1), b3 + hstep, voffB); PG8_STAGE(PG8_SA(1, 0), a3, voffA);
;             PG8_WAIT_V(8); PG8_WAIT_L(0); PG8_BAR; PG8_MMA(1, 0, At, B0); PG8_MMA(1, 1, At, B1); PG8_BAR; PG8_SCHED;
;     ...
;         }
;         if constexpr (ALIGN_EPI) { if (wr == 0) PG8_BAR; }
	s_add_i32 s28, s43, s0
	v_lshl_add_u64 v[182:183], v[182:183], 0, s[92:93]
	s_mov_b32 m0, s28
	ds_read_b128 v[170:173], v195 offset:49152
	ds_read_b128 v[174:177], v195 offset:50176
	ds_read_b128 v[178:181], v195 offset:51200
	ds_read_b128 v[196:199], v195 offset:52224
	ds_read_b128 v[208:211], v195 offset:53248
	ds_read_b128 v[212:215], v195 offset:54272
	ds_read_b128 v[216:219], v195 offset:55296
	ds_read_b128 v[220:223], v195 offset:56320
	global_load_lds_dwordx4 v[182:183], off
	s_add_i32 m0, s28, 0x2000
	s_add_u32 s26, s26, 0x40080
	v_lshl_add_u64 v[182:183], v[188:189], 0, s[92:93]
	s_addc_u32 s27, s27, 0
	s_add_i32 s28, s44, s0
	global_load_lds_dwordx4 v[182:183], off
	v_lshl_add_u64 v[182:183], s[26:27], 0, v[186:187]
	s_mov_b32 m0, s28
	s_nop 0
	global_load_lds_dwordx4 v[182:183], off
	v_lshl_add_u64 v[182:183], s[26:27], 0, v[156:157]
	s_add_i32 m0, s28, 0x2000
	s_nop 0
	global_load_lds_dwordx4 v[182:183], off
	v_lshl_add_u64 v[182:183], v[190:191], 0, s[92:93]
	s_mov_b32 m0, s34
	s_nop 0
	global_load_lds_dwordx4 v[182:183], off
	v_lshl_add_u64 v[182:183], v[224:225], 0, s[92:93]
	s_mov_b32 m0, s35
	s_nop 0
	global_load_lds_dwordx4 v[182:183], off
	s_waitcnt vmcnt(8)
	s_waitcnt lgkmcnt(0)
	s_barrier
	s_setprio 1
	s_waitcnt lgkmcnt(0)
	v_mfma_f32_16x16x32_bf16 v[60:63], v[128:131], v[170:173], v[60:63]
	v_mfma_f32_16x16x32_bf16 v[56:59], v[136:139], v[170:173], v[56:59]
	v_mfma_f32_16x16x32_bf16 v[44:47], v[128:131], v[178:181], v[44:47]
	v_mfma_f32_16x16x32_bf16 v[40:43], v[136:139], v[178:181], v[40:43]
	v_mfma_f32_16x16x32_bf16 v[28:31], v[128:131], v[208:211], v[28:31]
	v_mfma_f32_16x16x32_bf16 v[24:27], v[136:139], v[208:211], v[24:27]
	v_mfma_f32_16x16x32_bf16 v[12:15], v[128:131], v[216:219], v[12:15]
	v_mfma_f32_16x16x32_bf16 v[8:11], v[136:139], v[216:219], v[8:11]
	v_mfma_f32_16x16x32_bf16 v[60:63], v[132:135], v[174:177], v[60:63]
	v_mfma_f32_16x16x32_bf16 v[56:59], v[140:143], v[174:177], v[56:59]
	v_mfma_f32_16x16x32_bf16 v[44:47], v[132:135], v[196:199], v[44:47]
	v_mfma_f32_16x16x32_bf16 v[40:43], v[140:143], v[196:199], v[40:43]
	v_mfma_f32_16x16x32_bf16 v[28:31], v[132:135], v[212:215], v[28:31]
	v_mfma_f32_16x16x32_bf16 v[24:27], v[140:143], v[212:215], v[24:27]
	v_mfma_f32_16x16x32_bf16 v[12:15], v[132:135], v[220:223], v[12:15]
	v_mfma_f32_16x16x32_bf16 v[8:11], v[140:143], v[220:223], v[8:11]
	v_mfma_f32_16x16x32_bf16 v[52:55], v[144:147], v[170:173], v[52:55]
	v_mfma_f32_16x16x32_bf16 v[48:51], v[152:155], v[170:173], v[48:51]
	v_mfma_f32_16x16x32_bf16 v[36:39], v[144:147], v[178:181], v[36:39]
	v_mfma_f32_16x16x32_bf16 v[32:35], v[152:155], v[178:181], v[32:35]
	v_mfma_f32_16x16x32_bf16 v[20:23], v[144:147], v[208:211], v[20:23]
	v_mfma_f32_16x16x32_bf16 v[16:19], v[152:155], v[208:211], v[16:19]
	v_mfma_f32_16x16x32_bf16 v[4:7], v[144:147], v[216:219], v[4:7]
	v_mfma_f32_16x16x32_bf16 v[0:3], v[152:155], v[216:219], v[0:3]
	v_mfma_f32_16x16x32_bf16 v[52:55], v[148:151], v[174:177], v[52:55]
	v_mfma_f32_16x16x32_bf16 v[48:51], v[166:169], v[174:177], v[48:51]
	v_mfma_f32_16x16x32_bf16 v[36:39], v[148:151], v[196:199], v[36:39]
	v_mfma_f32_16x16x32_bf16 v[32:35], v[166:169], v[196:199], v[32:35]
	v_mfma_f32_16x16x32_bf16 v[20:23], v[148:151], v[212:215], v[20:23]
	v_mfma_f32_16x16x32_bf16 v[16:19], v[166:169], v[212:215], v[16:19]
	v_mfma_f32_16x16x32_bf16 v[4:7], v[148:151], v[220:223], v[4:7]
	v_mfma_f32_16x16x32_bf16 v[0:3], v[166:169], v[220:223], v[0:3]
	s_setprio 0
	s_barrier
	s_add_i32 s42, s42, 2
	s_add_u32 s24, s24, 0x100
	s_addc_u32 s25, s25, 0
	s_add_u32 s40, s40, 0x100
	s_addc_u32 s41, s41, 0
	s_cmp_gt_u32 s42, 13
	s_cbranch_scc0 .LBB0_1170
	s_and_b64 vcc, exec, s[14:15]
	s_cbranch_vccz .LBB0_1173
	s_barrier

; #define PG8_STAGE(bufoff, gbase, voff) do { _Pragma("unroll") for (int _i = 0; _i < 2; ++_i) \
;         __builtin_amdgcn_global_load_lds((const unsigned*)((const char*)(gbase) + (voff)[_i]), (PG8_LAS unsigned*)(lds + (bufoff) + ldsw + _i * 8192), 16, 0, 0); } while (0)
; #define PG8_LDA(dst, b, h) do { _Pragma("unroll") for (int m = 0; m < 4; ++m) _Pragma("unroll") for (int k = 0; k < 2; ++k) dst[m][k] = *(const PG8_LAS bf16x8*)(lds + PG8_SA(b, h) + aoff + m * 2048 + k * 1024); } while (0)
; #define PG8_LDB(dst, b, h) do { _Pragma("unroll") for (int n = 0; n < 2; ++n) _Pragma("unroll") for (int k = 0; k < 2; ++k) dst[n][k] = *(const PG8_LAS bf16x8*)(lds + PG8_SB(b, h) + boff + n * 2048 + k * 1024); } while (0)
; #define PG8_MMA(ai, bj, At, Bt) do { __builtin_amdgcn_s_setprio(1); _Pragma("unroll") for (int m = 0; m < 4; ++m) _Pragma("unroll") for (int n = 0; n < 2; ++n) _Pragma("unroll") for (int k = 0; k < 2; ++k) \
;         acc[ai][bj][m][n] = __builtin_amdgcn_mfma_f32_16x16x32_bf16(Bt[n][k], At[m][k], acc[ai][bj][m][n], 0, 0, 0); __builtin_amdgcn_s_setprio(0); } while (0)
; #define PG8_WAIT_V(n) asm volatile("s_waitcnt vmcnt(" #n ")" ::: "memory")
; #define PG8_WAIT_L(n) asm volatile("s_waitcnt lgkmcnt(" #n ")" ::: "memory")
; template <class Epi, class Sched, bool ALIGN_EPI = false, bool SP2 = false>
; __device__ __forceinline__ void gemm_phase(PG8_LAS unsigned char* lds, const Gemm g, const Sched& S, const Epi& E) {
;     ...
;             const bool last = (t == nt - 2);
;             const char* a1 = cA + (size_t)(t + 1) * kstep;
;             const char* a2 = last ? nA : cA + (size_t)(t + 2) * kstep; const char* b2 = last ? nB : cB + (size_t)(t + 2) * kstep;
;             const char* a3 = a2 + kstep; const char* b3 = b2 + kstep;
;             if (last && has_next) S.a_ready(nxt);
;             if constexpr (SP2) {
;             PG8_LDB(B0, 0, 0); PG8_LDB(B1, 0, 1); PG8_SCHED; PG8_LDA(At, 0, 0); PG8_STAGE(PG8_SA(1, 1), a1 + hstep, voffA);
;             PG8_WAIT_V(8); PG8_WAIT_L(0); PG8_BAR; PG8_MMA(0, 0, At, B0); PG8_MMA(0, 1, At, B1); PG8_BAR; PG8_SCHED;
;             PG8_LDA(At, 0, 1); PG8_STAGE(PG8_SB(0, 0), b2, voffB); PG8_STAGE(PG8_SB(0, 1), b2 + hstep, voffB); PG8_STAGE(PG8_SA(0, 0), a2, voffA);
;             PG8_WAIT_V(8); PG8_WAIT_L(0); PG8_BAR; PG8_MMA(1, 0, At, B0); PG8_MMA(1, 1, At, B1); PG8_BAR; PG8_SCHED;
.LBB0_1253:
	ds_read_b128 v[144:147], v153
	ds_read_b128 v[158:161], v153 offset:1024
	ds_read_b128 v[162:165], v153 offset:2048
	ds_read_b128 v[166:169], v153 offset:3072
	ds_read_b128 v[170:173], v154
	ds_read_b128 v[174:177], v154 offset:1024
	ds_read_b128 v[178:181], v154 offset:2048
	ds_read_b128 v[182:185], v154 offset:3072
	s_add_u32 s22, s20, 0xfffc0080
	s_addc_u32 s23, s21, -1
	s_cmp_eq_u32 s44, 12
	s_cselect_b32 s25, s15, s23
	s_cselect_b32 s24, s40, s22
	s_cselect_b32 s23, s13, s43
	s_cselect_b32 s22, s41, s42
	v_lshl_add_u64 v[148:149], s[20:21], 0, v[136:137]
	s_add_i32 m0, s28, 0xc000
	ds_read_b128 v[186:189], v155
	ds_read_b128 v[190:193], v155 offset:1024
	ds_read_b128 v[194:197], v155 offset:2048
	ds_read_b128 v[204:207], v155 offset:3072
	ds_read_b128 v[208:211], v155 offset:4096
	ds_read_b128 v[212:215], v155 offset:5120
	ds_read_b128 v[216:219], v155 offset:6144
	ds_read_b128 v[220:223], v155 offset:7168
	global_load_lds_dwordx4 v[148:149], off
	v_lshl_add_u64 v[148:149], s[20:21], 0, v[138:139]
	s_add_i32 m0, s28, 0xe000
	s_nop 0
	global_load_lds_dwordx4 v[148:149], off
	s_waitcnt vmcnt(8)
	s_waitcnt lgkmcnt(0)
	s_barrier
	s_setprio 1
	s_waitcnt lgkmcnt(0)
	v_mfma_f32_16x16x32_bf16 v[124:127], v[144:147], v[186:189], v[124:127]
	v_mfma_f32_16x16x32_bf16 v[120:123], v[162:165], v[186:189], v[120:123]
	v_mfma_f32_16x16x32_bf16 v[116:119], v[144:147], v[194:197], v[116:119]
	v_mfma_f32_16x16x32_bf16 v[104:107], v[162:165], v[194:197], v[104:107]
	v_mfma_f32_16x16x32_bf16 v[92:95], v[144:147], v[208:211], v[92:95]
	v_mfma_f32_16x16x32_bf16 v[88:91], v[162:165], v[208:211], v[88:91]
	v_mfma_f32_16x16x32_bf16 v[76:79], v[144:147], v[216:219], v[76:79]
	v_mfma_f32_16x16x32_bf16 v[72:75], v[162:165], v[216:219], v[72:75]
	v_mfma_f32_16x16x32_bf16 v[124:127], v[158:161], v[190:193], v[124:127]
	v_mfma_f32_16x16x32_bf16 v[120:123], v[166:169], v[190:193], v[120:123]
	v_mfma_f32_16x16x32_bf16 v[116:119], v[158:161], v[204:207], v[116:119]
	v_mfma_f32_16x16x32_bf16 v[104:107], v[166:169], v[204:207], v[104:107]
	v_mfma_f32_16x16x32_bf16 v[92:95], v[158:161], v[212:215], v[92:95]
	v_mfma_f32_16x16x32_bf16 v[88:91], v[166:169], v[212:215], v[88:91]
	v_mfma_f32_16x16x32_bf16 v[76:79], v[158:161], v[220:223], v[76:79]
	v_mfma_f32_16x16x32_bf16 v[72:75], v[166:169], v[220:223], v[72:75]
	v_mfma_f32_16x16x32_bf16 v[112:115], v[170:173], v[186:189], v[112:115]
	v_mfma_f32_16x16x32_bf16 v[108:111], v[178:181], v[186:189], v[108:111]
	v_mfma_f32_16x16x32_bf16 v[100:103], v[170:173], v[194:197], v[100:103]
	v_mfma_f32_16x16x32_bf16 v[96:99], v[178:181], v[194:197], v[96:99]
	v_mfma_f32_16x16x32_bf16 v[84:87], v[170:173], v[208:211], v[84:87]
	v_mfma_f32_16x16x32_bf16 v[80:83], v[178:181], v[208:211], v[80:83]
	v_mfma_f32_16x16x32_bf16 v[68:71], v[170:173], v[216:219], v[68:71]
	v_mfma_f32_16x16x32_bf16 v[64:67], v[178:181], v[216:219], v[64:67]
	v_mfma_f32_16x16x32_bf16 v[112:115], v[174:177], v[190:193], v[112:115]
	v_mfma_f32_16x16x32_bf16 v[108:111], v[182:185], v[190:193], v[108:111]
	v_mfma_f32_16x16x32_bf16 v[100:103], v[174:177], v[204:207], v[100:103]
	v_mfma_f32_16x16x32_bf16 v[96:99], v[182:185], v[204:207], v[96:99]
	v_mfma_f32_16x16x32_bf16 v[84:87], v[174:177], v[212:215], v[84:87]
	v_mfma_f32_16x16x32_bf16 v[80:83], v[182:185], v[212:215], v[80:83]
	v_mfma_f32_16x16x32_bf16 v[68:71], v[174:177], v[220:223], v[68:71]
	v_mfma_f32_16x16x32_bf16 v[64:67], v[182:185], v[220:223], v[64:67]
	s_setprio 0
	s_barrier
	s_add_i32 s45, s36, s26
	v_lshl_add_u64 v[148:149], s[22:23], 0, v[132:133]
	s_mov_b32 m0, s45
	ds_read_b128 v[186:189], v155 offset:16384
	ds_read_b128 v[190:193], v155 offset:17408
	ds_read_b128 v[194:197], v155 offset:18432
	ds_read_b128 v[204:207], v155 offset:19456
	ds_read_b128 v[208:211], v155 offset:20480
	ds_read_b128 v[212:215], v155 offset:21504
	ds_read_b128 v[216:219], v155 offset:22528
	ds_read_b128 v[220:223], v155 offset:23552
	global_load_lds_dwordx4 v[148:149], off
	s_add_i32 m0, s45, 0x2000
	s_add_u32 s46, s22, 0x40000
	v_lshl_add_u64 v[198:199], s[22:23], 0, v[128:129]
	s_addc_u32 s47, s23, 0
	s_add_i32 s45, s37, s26
	global_load_lds_dwordx4 v[198:199], off
	v_lshl_add_u64 v[224:225], s[46:47], 0, v[132:133]
	s_mov_b32 m0, s45
	v_lshl_add_u64 v[226:227], s[24:25], 0, v[130:131]
	global_load_lds_dwordx4 v[224:225], off
	v_lshl_add_u64 v[224:225], s[46:47], 0, v[128:129]
	s_add_i32 m0, s45, 0x2000
	s_nop 0
	global_load_lds_dwordx4 v[224:225], off
	v_lshl_add_u64 v[224:225], s[24:25], 0, v[134:135]
	s_mov_b32 m0, s28
	s_nop 0
	global_load_lds_dwordx4 v[224:225], off
	s_mov_b32 m0, s29
	s_nop 0
	global_load_lds_dwordx4 v[226:227], off
	s_waitcnt vmcnt(8)
	s_waitcnt lgkmcnt(0)
	s_barrier
; #define PG8_STAGE(bufoff, gbase, voff) do { _Pragma("unroll") for (int _i = 0; _i < 2; ++_i) \
;         __builtin_amdgcn_global_load_lds((const unsigned*)((const char*)(gbase) + (voff)[_i]), (PG8_LAS unsigned*)(lds + (bufoff) + ldsw + _i * 8192), 16, 0, 0); } while (0)
; #define PG8_LDA(dst, b, h) do { _Pragma("unroll") for (int m = 0; m < 4; ++m) _Pragma("unroll") for (int k = 0; k < 2; ++k) dst[m][k] = *(const PG8_LAS bf16x8*)(lds + PG8_SA(b, h) + aoff + m * 2048 + k * 1024); } while (0)
; #define PG8_LDB(dst, b, h) do { _Pragma("unroll") for (int n = 0; n < 2; ++n) _Pragma("unroll") for (int k = 0; k < 2; ++k) dst[n][k] = *(const PG8_LAS bf16x8*)(lds + PG8_SB(b, h) + boff + n * 2048 + k * 1024); } while (0)
; #define PG8_MMA(ai, bj, At, Bt) do { __builtin_amdgcn_s_setprio(1); _Pragma("unroll") for (int m = 0; m < 4; ++m) _Pragma("unroll") for (int n = 0; n < 2; ++n) _Pragma("unroll") for (int k = 0; k < 2; ++k) \
;         acc[ai][bj][m][n] = __builtin_amdgcn_mfma_f32_16x16x32_bf16(Bt[n][k], At[m][k], acc[ai][bj][m][n], 0, 0, 0); __builtin_amdgcn_s_setprio(0); } while (0)
; #define PG8_WAIT_V(n) asm volatile("s_waitcnt vmcnt(" #n ")" ::: "memory")
; #define PG8_WAIT_L(n) asm volatile("s_waitcnt lgkmcnt(" #n ")" ::: "memory")
; #define PG8_BAR __builtin_amdgcn_s_barrier()
; #define PG8_SCHED __builtin_amdgcn_sched_barrier(0)
; template <class Epi, class Sched, bool ALIGN_EPI = false, bool SP2 = false>
; __device__ __forceinline__ void gemm_phase(PG8_LAS unsigned char* lds, const Gemm g, const Sched& S, const Epi& E) {
;     ...
;             PG8_LDA(At, 0, 1); PG8_STAGE(PG8_SB(0, 0), b2, voffB); PG8_STAGE(PG8_SB(0, 1), b2 + hstep, voffB); PG8_STAGE(PG8_SA(0, 0), a2, voffA);
;             PG8_WAIT_V(8); PG8_WAIT_L(0); PG8_BAR; PG8_MMA(1, 0, At, B0); PG8_MMA(1, 1, At, B1); PG8_BAR; PG8_SCHED;
;             PG8_LDB(B0, 1, 0); PG8_LDB(B1, 1, 1); PG8_SCHED; PG8_LDA(At, 1, 0); PG8_STAGE(PG8_SA(0, 1), a2 + hstep, voffA);
;             PG8_WAIT_V(8); PG8_WAIT_L(0); PG8_BAR; PG8_MMA(0, 0, At, B0); PG8_MMA(0, 1, At, B1); PG8_BAR; PG8_SCHED;
	s_setprio 1
	s_waitcnt lgkmcnt(0)
	v_mfma_f32_16x16x32_bf16 v[60:63], v[144:147], v[186:189], v[60:63]
	v_mfma_f32_16x16x32_bf16 v[56:59], v[162:165], v[186:189], v[56:59]
	v_mfma_f32_16x16x32_bf16 v[44:47], v[144:147], v[194:197], v[44:47]
	v_mfma_f32_16x16x32_bf16 v[40:43], v[162:165], v[194:197], v[40:43]
	v_mfma_f32_16x16x32_bf16 v[28:31], v[144:147], v[208:211], v[28:31]
	v_mfma_f32_16x16x32_bf16 v[24:27], v[162:165], v[208:211], v[24:27]
	v_mfma_f32_16x16x32_bf16 v[12:15], v[144:147], v[216:219], v[12:15]
	v_mfma_f32_16x16x32_bf16 v[8:11], v[162:165], v[216:219], v[8:11]
	v_mfma_f32_16x16x32_bf16 v[60:63], v[158:161], v[190:193], v[60:63]
	v_mfma_f32_16x16x32_bf16 v[56:59], v[166:169], v[190:193], v[56:59]
	v_mfma_f32_16x16x32_bf16 v[44:47], v[158:161], v[204:207], v[44:47]
	v_mfma_f32_16x16x32_bf16 v[40:43], v[166:169], v[204:207], v[40:43]
	v_mfma_f32_16x16x32_bf16 v[28:31], v[158:161], v[212:215], v[28:31]
	v_mfma_f32_16x16x32_bf16 v[24:27], v[166:169], v[212:215], v[24:27]
	v_mfma_f32_16x16x32_bf16 v[12:15], v[158:161], v[220:223], v[12:15]
	v_mfma_f32_16x16x32_bf16 v[8:11], v[166:169], v[220:223], v[8:11]
	v_mfma_f32_16x16x32_bf16 v[52:55], v[170:173], v[186:189], v[52:55]
	v_mfma_f32_16x16x32_bf16 v[48:51], v[178:181], v[186:189], v[48:51]
	v_mfma_f32_16x16x32_bf16 v[36:39], v[170:173], v[194:197], v[36:39]
	v_mfma_f32_16x16x32_bf16 v[32:35], v[178:181], v[194:197], v[32:35]
	v_mfma_f32_16x16x32_bf16 v[20:23], v[170:173], v[208:211], v[20:23]
	v_mfma_f32_16x16x32_bf16 v[16:19], v[178:181], v[208:211], v[16:19]
	v_mfma_f32_16x16x32_bf16 v[4:7], v[170:173], v[216:219], v[4:7]
	v_mfma_f32_16x16x32_bf16 v[0:3], v[178:181], v[216:219], v[0:3]
	v_mfma_f32_16x16x32_bf16 v[52:55], v[174:177], v[190:193], v[52:55]
	v_mfma_f32_16x16x32_bf16 v[48:51], v[182:185], v[190:193], v[48:51]
	v_mfma_f32_16x16x32_bf16 v[36:39], v[174:177], v[204:207], v[36:39]
	v_mfma_f32_16x16x32_bf16 v[32:35], v[182:185], v[204:207], v[32:35]
	v_mfma_f32_16x16x32_bf16 v[20:23], v[174:177], v[212:215], v[20:23]
	v_mfma_f32_16x16x32_bf16 v[16:19], v[182:185], v[212:215], v[16:19]
	v_mfma_f32_16x16x32_bf16 v[4:7], v[174:177], v[220:223], v[4:7]
	v_mfma_f32_16x16x32_bf16 v[0:3], v[182:185], v[220:223], v[0:3]
	s_setprio 0
	s_barrier
	s_add_i32 s45, 0, 0x18000
	v_add_u32_e32 v157, s45, v151
	s_add_i32 s46, 0, 0x1c000
	ds_read_b128 v[144:147], v157
	ds_read_b128 v[158:161], v157 offset:1024
	ds_read_b128 v[162:165], v157 offset:2048
	ds_read_b128 v[166:169], v157 offset:3072
	v_add_u32_e32 v157, s46, v151
	ds_read_b128 v[170:173], v157
	ds_read_b128 v[174:177], v157 offset:1024
	ds_read_b128 v[178:181], v157 offset:2048
	ds_read_b128 v[182:185], v157 offset:3072
	s_add_u32 s24, s24, 0x40000
	s_addc_u32 s25, s25, 0
	s_mov_b32 m0, s30
	v_lshl_add_u64 v[228:229], s[24:25], 0, v[134:135]
	ds_read_b128 v[186:189], v155 offset:32768
	ds_read_b128 v[190:193], v155 offset:33792
	ds_read_b128 v[194:197], v155 offset:34816
	ds_read_b128 v[204:207], v155 offset:35840
	ds_read_b128 v[208:211], v155 offset:36864
	ds_read_b128 v[212:215], v155 offset:37888
	ds_read_b128 v[216:219], v155 offset:38912
	ds_read_b128 v[220:223], v155 offset:39936
	global_load_lds_dwordx4 v[228:229], off
	v_lshl_add_u64 v[228:229], s[24:25], 0, v[130:131]
	s_mov_b32 m0, s31
	s_nop 0
	global_load_lds_dwordx4 v[228:229], off
	s_waitcnt vmcnt(8)
	s_waitcnt lgkmcnt(0)
	s_barrier
	s_setprio 1
	s_waitcnt lgkmcnt(0)
	v_mfma_f32_16x16x32_bf16 v[124:127], v[144:147], v[186:189], v[124:127]
	v_mfma_f32_16x16x32_bf16 v[120:123], v[162:165], v[186:189], v[120:123]
	v_mfma_f32_16x16x32_bf16 v[116:119], v[144:147], v[194:197], v[116:119]
	v_mfma_f32_16x16x32_bf16 v[104:107], v[162:165], v[194:197], v[104:107]
	v_mfma_f32_16x16x32_bf16 v[92:95], v[144:147], v[208:211], v[92:95]
	v_mfma_f32_16x16x32_bf16 v[88:91], v[162:165], v[208:211], v[88:91]
	v_mfma_f32_16x16x32_bf16 v[76:79], v[144:147], v[216:219], v[76:79]
	v_mfma_f32_16x16x32_bf16 v[72:75], v[162:165], v[216:219], v[72:75]
	v_mfma_f32_16x16x32_bf16 v[124:127], v[158:161], v[190:193], v[124:127]
	v_mfma_f32_16x16x32_bf16 v[120:123], v[166:169], v[190:193], v[120:123]
	v_mfma_f32_16x16x32_bf16 v[116:119], v[158:161], v[204:207], v[116:119]
	v_mfma_f32_16x16x32_bf16 v[104:107], v[166:169], v[204:207], v[104:107]
	v_mfma_f32_16x16x32_bf16 v[92:95], v[158:161], v[212:215], v[92:95]
	v_mfma_f32_16x16x32_bf16 v[88:91], v[166:169], v[212:215], v[88:91]
	v_mfma_f32_16x16x32_bf16 v[76:79], v[158:161], v[220:223], v[76:79]
	v_mfma_f32_16x16x32_bf16 v[72:75], v[166:169], v[220:223], v[72:75]
	v_mfma_f32_16x16x32_bf16 v[112:115], v[170:173], v[186:189], v[112:115]
	v_mfma_f32_16x16x32_bf16 v[108:111], v[178:181], v[186:189], v[108:111]
	v_mfma_f32_16x16x32_bf16 v[100:103], v[170:173], v[194:197], v[100:103]
	v_mfma_f32_16x16x32_bf16 v[96:99], v[178:181], v[194:197], v[96:99]
	v_mfma_f32_16x16x32_bf16 v[84:87], v[170:173], v[208:211], v[84:87]
	v_mfma_f32_16x16x32_bf16 v[80:83], v[178:181], v[208:211], v[80:83]
	v_mfma_f32_16x16x32_bf16 v[68:71], v[170:173], v[216:219], v[68:71]
	v_mfma_f32_16x16x32_bf16 v[64:67], v[178:181], v[216:219], v[64:67]
	v_mfma_f32_16x16x32_bf16 v[112:115], v[174:177], v[190:193], v[112:115]
	v_mfma_f32_16x16x32_bf16 v[108:111], v[182:185], v[190:193], v[108:111]
	v_mfma_f32_16x16x32_bf16 v[100:103], v[174:177], v[204:207], v[100:103]
	v_mfma_f32_16x16x32_bf16 v[96:99], v[182:185], v[204:207], v[96:99]
	v_mfma_f32_16x16x32_bf16 v[84:87], v[174:177], v[212:215], v[84:87]
	v_mfma_f32_16x16x32_bf16 v[80:83], v[182:185], v[212:215], v[80:83]
	v_mfma_f32_16x16x32_bf16 v[68:71], v[174:177], v[220:223], v[68:71]
	v_mfma_f32_16x16x32_bf16 v[64:67], v[182:185], v[220:223], v[64:67]
	s_setprio 0
	s_barrier
; #define PG8_STAGE(bufoff, gbase, voff) do { _Pragma("unroll") for (int _i = 0; _i < 2; ++_i) \
;         __builtin_amdgcn_global_load_lds((const unsigned*)((const char*)(gbase) + (voff)[_i]), (PG8_LAS unsigned*)(lds + (bufoff) + ldsw + _i * 8192), 16, 0, 0); } while (0)
; #define PG8_LDA(dst, b, h) do { _Pragma("unroll") for (int m = 0; m < 4; ++m) _Pragma("unroll") for (int k = 0; k < 2; ++k) dst[m][k] = *(const PG8_LAS bf16x8*)(lds + PG8_SA(b, h) + aoff + m * 2048 + k * 1024); } while (0)
; #define PG8_MMA(ai, bj, At, Bt) do { __builtin_amdgcn_s_setprio(1); _Pragma("unroll") for (int m = 0; m < 4; ++m) _Pragma("unroll") for (int n = 0; n < 2; ++n) _Pragma("unroll") for (int k = 0; k < 2; ++k) \
;         acc[ai][bj][m][n] = __builtin_amdgcn_mfma_f32_16x16x32_bf16(Bt[n][k], At[m][k], acc[ai][bj][m][n], 0, 0, 0); __builtin_amdgcn_s_setprio(0); } while (0)
; #define PG8_WAIT_V(n) asm volatile("s_waitcnt vmcnt(" #n ")" ::: "memory")
; #define PG8_WAIT_L(n) asm volatile("s_waitcnt lgkmcnt(" #n ")" ::: "memory")
; #define PG8_BAR __builtin_amdgcn_s_barrier()
; #define PG8_SCHED __builtin_amdgcn_sched_barrier(0)
; template <class Epi, class Sched, bool ALIGN_EPI = false, bool SP2 = false>
; __device__ __forceinline__ void gemm_phase(PG8_LAS unsigned char* lds, const Gemm g, const Sched& S, const Epi& E) {
;     ...
;             PG8_LDA(At, 1, 1); PG8_STAGE(PG8_SB(1, 0), b3, voffB); PG8_STAGE(PG8_SB(1, 1), b3 + hstep, voffB); PG8_STAGE(PG8_SA(1, 0), a3, voffA);
;             PG8_WAIT_V(8); PG8_WAIT_L(0); PG8_BAR; PG8_MMA(1, 0, At, B0); PG8_MMA(1, 1, At, B1); PG8_BAR; PG8_SCHED;
;     ...
;         }
;         if constexpr (ALIGN_EPI) { if (wr == 0) PG8_BAR; }
	s_add_i32 s24, s45, s26
	v_lshl_add_u64 v[148:149], v[148:149], 0, s[4:5]
	s_mov_b32 m0, s24
	ds_read_b128 v[186:189], v155 offset:49152
	ds_read_b128 v[190:193], v155 offset:50176
	ds_read_b128 v[194:197], v155 offset:51200
	ds_read_b128 v[204:207], v155 offset:52224
	ds_read_b128 v[208:211], v155 offset:53248
	ds_read_b128 v[212:215], v155 offset:54272
	ds_read_b128 v[216:219], v155 offset:55296
	ds_read_b128 v[220:223], v155 offset:56320
	global_load_lds_dwordx4 v[148:149], off
	s_add_i32 m0, s24, 0x2000
	s_add_u32 s22, s22, 0x40080
	v_lshl_add_u64 v[148:149], v[198:199], 0, s[4:5]
	s_addc_u32 s23, s23, 0
	s_add_i32 s24, s46, s26
	global_load_lds_dwordx4 v[148:149], off
	v_lshl_add_u64 v[148:149], s[22:23], 0, v[132:133]
	s_mov_b32 m0, s24
	s_nop 0
	global_load_lds_dwordx4 v[148:149], off
	v_lshl_add_u64 v[148:149], s[22:23], 0, v[128:129]
	s_add_i32 m0, s24, 0x2000
	s_nop 0
	global_load_lds_dwordx4 v[148:149], off
	v_lshl_add_u64 v[148:149], v[224:225], 0, s[4:5]
	s_mov_b32 m0, s34
	s_nop 0
	global_load_lds_dwordx4 v[148:149], off
	v_lshl_add_u64 v[148:149], v[226:227], 0, s[4:5]
	s_mov_b32 m0, s35
	s_nop 0
	global_load_lds_dwordx4 v[148:149], off
	s_waitcnt vmcnt(8)
	s_waitcnt lgkmcnt(0)
	s_barrier
	s_setprio 1
	s_waitcnt lgkmcnt(0)
	v_mfma_f32_16x16x32_bf16 v[60:63], v[144:147], v[186:189], v[60:63]
	v_mfma_f32_16x16x32_bf16 v[56:59], v[162:165], v[186:189], v[56:59]
	v_mfma_f32_16x16x32_bf16 v[44:47], v[144:147], v[194:197], v[44:47]
	v_mfma_f32_16x16x32_bf16 v[40:43], v[162:165], v[194:197], v[40:43]
	v_mfma_f32_16x16x32_bf16 v[28:31], v[144:147], v[208:211], v[28:31]
	v_mfma_f32_16x16x32_bf16 v[24:27], v[162:165], v[208:211], v[24:27]
	v_mfma_f32_16x16x32_bf16 v[12:15], v[144:147], v[216:219], v[12:15]
	v_mfma_f32_16x16x32_bf16 v[8:11], v[162:165], v[216:219], v[8:11]
	v_mfma_f32_16x16x32_bf16 v[60:63], v[158:161], v[190:193], v[60:63]
	v_mfma_f32_16x16x32_bf16 v[56:59], v[166:169], v[190:193], v[56:59]
	v_mfma_f32_16x16x32_bf16 v[44:47], v[158:161], v[204:207], v[44:47]
	v_mfma_f32_16x16x32_bf16 v[40:43], v[166:169], v[204:207], v[40:43]
	v_mfma_f32_16x16x32_bf16 v[28:31], v[158:161], v[212:215], v[28:31]
	v_mfma_f32_16x16x32_bf16 v[24:27], v[166:169], v[212:215], v[24:27]
	v_mfma_f32_16x16x32_bf16 v[12:15], v[158:161], v[220:223], v[12:15]
	v_mfma_f32_16x16x32_bf16 v[8:11], v[166:169], v[220:223], v[8:11]
	v_mfma_f32_16x16x32_bf16 v[52:55], v[170:173], v[186:189], v[52:55]
	v_mfma_f32_16x16x32_bf16 v[48:51], v[178:181], v[186:189], v[48:51]
	v_mfma_f32_16x16x32_bf16 v[36:39], v[170:173], v[194:197], v[36:39]
	v_mfma_f32_16x16x32_bf16 v[32:35], v[178:181], v[194:197], v[32:35]
	v_mfma_f32_16x16x32_bf16 v[20:23], v[170:173], v[208:211], v[20:23]
	v_mfma_f32_16x16x32_bf16 v[16:19], v[178:181], v[208:211], v[16:19]
	v_mfma_f32_16x16x32_bf16 v[4:7], v[170:173], v[216:219], v[4:7]
	v_mfma_f32_16x16x32_bf16 v[0:3], v[178:181], v[216:219], v[0:3]
	v_mfma_f32_16x16x32_bf16 v[52:55], v[174:177], v[190:193], v[52:55]
	v_mfma_f32_16x16x32_bf16 v[48:51], v[182:185], v[190:193], v[48:51]
	v_mfma_f32_16x16x32_bf16 v[36:39], v[174:177], v[204:207], v[36:39]
	v_mfma_f32_16x16x32_bf16 v[32:35], v[182:185], v[204:207], v[32:35]
	v_mfma_f32_16x16x32_bf16 v[20:23], v[174:177], v[212:215], v[20:23]
	v_mfma_f32_16x16x32_bf16 v[16:19], v[182:185], v[212:215], v[16:19]
	v_mfma_f32_16x16x32_bf16 v[4:7], v[174:177], v[220:223], v[4:7]
	v_mfma_f32_16x16x32_bf16 v[0:3], v[182:185], v[220:223], v[0:3]
	s_setprio 0
	s_barrier
	s_add_i32 s44, s44, 2
	s_add_u32 s20, s20, 0x100
	s_addc_u32 s21, s21, 0
	s_add_u32 s42, s42, 0x100
	s_addc_u32 s43, s43, 0
	s_cmp_gt_u32 s44, 13
	s_cbranch_scc0 .LBB0_1253
	s_and_b64 vcc, exec, s[6:7]
	s_cbranch_vccz .LBB0_1256
	s_barrier

; #define PG8_STAGE(bufoff, gbase, voff) do { _Pragma("unroll") for (int _i = 0; _i < 2; ++_i) \
;         __builtin_amdgcn_global_load_lds((const unsigned*)((const char*)(gbase) + (voff)[_i]), (PG8_LAS unsigned*)(lds + (bufoff) + ldsw + _i * 8192), 16, 0, 0); } while (0)
; #define PG8_LDA(dst, b, h) do { _Pragma("unroll") for (int m = 0; m < 4; ++m) _Pragma("unroll") for (int k = 0; k < 2; ++k) dst[m][k] = *(const PG8_LAS bf16x8*)(lds + PG8_SA(b, h) + aoff + m * 2048 + k * 1024); } while (0)
; #define PG8_LDB(dst, b, h) do { _Pragma("unroll") for (int n = 0; n < 2; ++n) _Pragma("unroll") for (int k = 0; k < 2; ++k) dst[n][k] = *(const PG8_LAS bf16x8*)(lds + PG8_SB(b, h) + boff + n * 2048 + k * 1024); } while (0)
; #define PG8_MMA(ai, bj, At, Bt) do { __builtin_amdgcn_s_setprio(1); _Pragma("unroll") for (int m = 0; m < 4; ++m) _Pragma("unroll") for (int n = 0; n < 2; ++n) _Pragma("unroll") for (int k = 0; k < 2; ++k) \
;         acc[ai][bj][m][n] = __builtin_amdgcn_mfma_f32_16x16x32_bf16(Bt[n][k], At[m][k], acc[ai][bj][m][n], 0, 0, 0); __builtin_amdgcn_s_setprio(0); } while (0)
; #define PG8_WAIT_V(n) asm volatile("s_waitcnt vmcnt(" #n ")" ::: "memory")
; #define PG8_WAIT_L(n) asm volatile("s_waitcnt lgkmcnt(" #n ")" ::: "memory")
; template <class Epi, class Sched, bool ALIGN_EPI = false, bool SP2 = false>
; __device__ __forceinline__ void gemm_phase(PG8_LAS unsigned char* lds, const Gemm g, const Sched& S, const Epi& E) {
;     ...
;             const bool last = (t == nt - 2);
;             const char* a1 = cA + (size_t)(t + 1) * kstep;
;             const char* a2 = last ? nA : cA + (size_t)(t + 2) * kstep; const char* b2 = last ? nB : cB + (size_t)(t + 2) * kstep;
;             const char* a3 = a2 + kstep; const char* b3 = b2 + kstep;
;             if (last && has_next) S.a_ready(nxt);
;             if constexpr (SP2) {
;             PG8_LDB(B0, 0, 0); PG8_LDB(B1, 0, 1); PG8_SCHED; PG8_LDA(At, 0, 0); PG8_STAGE(PG8_SA(1, 1), a1 + hstep, voffA);
;             PG8_WAIT_V(8); PG8_WAIT_L(0); PG8_BAR; PG8_MMA(0, 0, At, B0); PG8_MMA(0, 1, At, B1); PG8_BAR; PG8_SCHED;
;             PG8_LDA(At, 0, 1); PG8_STAGE(PG8_SB(0, 0), b2, voffB); PG8_STAGE(PG8_SB(0, 1), b2 + hstep, voffB); PG8_STAGE(PG8_SA(0, 0), a2, voffA);
;             PG8_WAIT_V(8); PG8_WAIT_L(0); PG8_BAR; PG8_MMA(1, 0, At, B0); PG8_MMA(1, 1, At, B1); PG8_BAR; PG8_SCHED;
.LBB0_1335:
	ds_read_b128 v[128:131], v189
	ds_read_b128 v[132:135], v189 offset:1024
	ds_read_b128 v[136:139], v189 offset:2048
	ds_read_b128 v[140:143], v189 offset:3072
	ds_read_b128 v[144:147], v190
	ds_read_b128 v[148:151], v190 offset:1024
	ds_read_b128 v[168:171], v190 offset:2048
	ds_read_b128 v[172:175], v190 offset:3072
	s_add_u32 s20, s18, 0x100
	s_addc_u32 s21, s19, 0
	s_cmp_eq_u32 s43, 40
	s_cselect_b32 s25, s11, s21
	s_cselect_b32 s24, s10, s20
	s_cselect_b32 s23, s17, s42
	s_cselect_b32 s22, s16, s41
	v_lshl_add_u64 v[184:185], s[18:19], 0, v[160:161]
	s_add_i32 m0, s27, 0xc000
	ds_read_b128 v[176:179], v191
	ds_read_b128 v[180:183], v191 offset:1024
	ds_read_b128 v[192:195], v191 offset:2048
	ds_read_b128 v[196:199], v191 offset:3072
	ds_read_b128 v[204:207], v191 offset:4096
	ds_read_b128 v[208:211], v191 offset:5120
	ds_read_b128 v[212:215], v191 offset:6144
	ds_read_b128 v[216:219], v191 offset:7168
	global_load_lds_dwordx4 v[184:185], off
	v_lshl_add_u64 v[184:185], s[18:19], 0, v[162:163]
	s_add_i32 m0, s27, 0xe000
	s_nop 0
	global_load_lds_dwordx4 v[184:185], off
	s_waitcnt vmcnt(8)
	s_waitcnt lgkmcnt(0)
	s_barrier
	s_setprio 1
	s_waitcnt lgkmcnt(0)
	v_mfma_f32_16x16x32_bf16 v[124:127], v[128:131], v[176:179], v[124:127]
	v_mfma_f32_16x16x32_bf16 v[120:123], v[136:139], v[176:179], v[120:123]
	v_mfma_f32_16x16x32_bf16 v[108:111], v[128:131], v[192:195], v[108:111]
	v_mfma_f32_16x16x32_bf16 v[104:107], v[136:139], v[192:195], v[104:107]
	v_mfma_f32_16x16x32_bf16 v[92:95], v[128:131], v[204:207], v[92:95]
	v_mfma_f32_16x16x32_bf16 v[88:91], v[136:139], v[204:207], v[88:91]
	v_mfma_f32_16x16x32_bf16 v[76:79], v[128:131], v[212:215], v[76:79]
	v_mfma_f32_16x16x32_bf16 v[72:75], v[136:139], v[212:215], v[72:75]
	v_mfma_f32_16x16x32_bf16 v[124:127], v[132:135], v[180:183], v[124:127]
	v_mfma_f32_16x16x32_bf16 v[120:123], v[140:143], v[180:183], v[120:123]
	v_mfma_f32_16x16x32_bf16 v[108:111], v[132:135], v[196:199], v[108:111]
	v_mfma_f32_16x16x32_bf16 v[104:107], v[140:143], v[196:199], v[104:107]
	v_mfma_f32_16x16x32_bf16 v[92:95], v[132:135], v[208:211], v[92:95]
	v_mfma_f32_16x16x32_bf16 v[88:91], v[140:143], v[208:211], v[88:91]
	v_mfma_f32_16x16x32_bf16 v[76:79], v[132:135], v[216:219], v[76:79]
	v_mfma_f32_16x16x32_bf16 v[72:75], v[140:143], v[216:219], v[72:75]
	v_mfma_f32_16x16x32_bf16 v[116:119], v[144:147], v[176:179], v[116:119]
	v_mfma_f32_16x16x32_bf16 v[112:115], v[168:171], v[176:179], v[112:115]
	v_mfma_f32_16x16x32_bf16 v[100:103], v[144:147], v[192:195], v[100:103]
	v_mfma_f32_16x16x32_bf16 v[96:99], v[168:171], v[192:195], v[96:99]
	v_mfma_f32_16x16x32_bf16 v[84:87], v[144:147], v[204:207], v[84:87]
	v_mfma_f32_16x16x32_bf16 v[80:83], v[168:171], v[204:207], v[80:83]
	v_mfma_f32_16x16x32_bf16 v[68:71], v[144:147], v[212:215], v[68:71]
	v_mfma_f32_16x16x32_bf16 v[64:67], v[168:171], v[212:215], v[64:67]
	v_mfma_f32_16x16x32_bf16 v[116:119], v[148:151], v[180:183], v[116:119]
	v_mfma_f32_16x16x32_bf16 v[112:115], v[172:175], v[180:183], v[112:115]
	v_mfma_f32_16x16x32_bf16 v[100:103], v[148:151], v[196:199], v[100:103]
	v_mfma_f32_16x16x32_bf16 v[96:99], v[172:175], v[196:199], v[96:99]
	v_mfma_f32_16x16x32_bf16 v[84:87], v[148:151], v[208:211], v[84:87]
	v_mfma_f32_16x16x32_bf16 v[80:83], v[172:175], v[208:211], v[80:83]
	v_mfma_f32_16x16x32_bf16 v[68:71], v[148:151], v[216:219], v[68:71]
	v_mfma_f32_16x16x32_bf16 v[64:67], v[172:175], v[216:219], v[64:67]
	s_setprio 0
	s_barrier
	s_add_i32 s18, s35, s26
	v_lshl_add_u64 v[184:185], s[22:23], 0, v[154:155]
	s_mov_b32 m0, s18
	ds_read_b128 v[176:179], v191 offset:16384
	ds_read_b128 v[180:183], v191 offset:17408
	ds_read_b128 v[192:195], v191 offset:18432
	ds_read_b128 v[196:199], v191 offset:19456
	ds_read_b128 v[204:207], v191 offset:20480
	ds_read_b128 v[208:211], v191 offset:21504
	ds_read_b128 v[212:215], v191 offset:22528
	ds_read_b128 v[216:219], v191 offset:23552
	global_load_lds_dwordx4 v[184:185], off
	s_add_i32 m0, s18, 0x2000
	s_add_u32 s18, s22, 0xb0000
	v_lshl_add_u64 v[220:221], s[22:23], 0, v[158:159]
	s_addc_u32 s19, s23, 0
	s_add_i32 s44, s36, s26
	global_load_lds_dwordx4 v[220:221], off
	v_lshl_add_u64 v[222:223], s[18:19], 0, v[154:155]
	s_mov_b32 m0, s44
	v_lshl_add_u64 v[224:225], s[24:25], 0, v[156:157]
	global_load_lds_dwordx4 v[222:223], off
	v_lshl_add_u64 v[222:223], s[18:19], 0, v[158:159]
	s_add_i32 m0, s44, 0x2000
	s_nop 0
	global_load_lds_dwordx4 v[222:223], off
	v_lshl_add_u64 v[222:223], s[24:25], 0, v[152:153]
	s_mov_b32 m0, s27
	s_nop 0
	global_load_lds_dwordx4 v[222:223], off
	s_mov_b32 m0, s28
	s_nop 0
	global_load_lds_dwordx4 v[224:225], off
	s_waitcnt vmcnt(8)
	s_waitcnt lgkmcnt(0)
	s_barrier
; #define PG8_STAGE(bufoff, gbase, voff) do { _Pragma("unroll") for (int _i = 0; _i < 2; ++_i) \
;         __builtin_amdgcn_global_load_lds((const unsigned*)((const char*)(gbase) + (voff)[_i]), (PG8_LAS unsigned*)(lds + (bufoff) + ldsw + _i * 8192), 16, 0, 0); } while (0)
; #define PG8_LDA(dst, b, h) do { _Pragma("unroll") for (int m = 0; m < 4; ++m) _Pragma("unroll") for (int k = 0; k < 2; ++k) dst[m][k] = *(const PG8_LAS bf16x8*)(lds + PG8_SA(b, h) + aoff + m * 2048 + k * 1024); } while (0)
; #define PG8_LDB(dst, b, h) do { _Pragma("unroll") for (int n = 0; n < 2; ++n) _Pragma("unroll") for (int k = 0; k < 2; ++k) dst[n][k] = *(const PG8_LAS bf16x8*)(lds + PG8_SB(b, h) + boff + n * 2048 + k * 1024); } while (0)
; #define PG8_MMA(ai, bj, At, Bt) do { __builtin_amdgcn_s_setprio(1); _Pragma("unroll") for (int m = 0; m < 4; ++m) _Pragma("unroll") for (int n = 0; n < 2; ++n) _Pragma("unroll") for (int k = 0; k < 2; ++k) \
;         acc[ai][bj][m][n] = __builtin_amdgcn_mfma_f32_16x16x32_bf16(Bt[n][k], At[m][k], acc[ai][bj][m][n], 0, 0, 0); __builtin_amdgcn_s_setprio(0); } while (0)
; #define PG8_WAIT_V(n) asm volatile("s_waitcnt vmcnt(" #n ")" ::: "memory")
; #define PG8_WAIT_L(n) asm volatile("s_waitcnt lgkmcnt(" #n ")" ::: "memory")
; #define PG8_BAR __builtin_amdgcn_s_barrier()
; #define PG8_SCHED __builtin_amdgcn_sched_barrier(0)
; template <class Epi, class Sched, bool ALIGN_EPI = false, bool SP2 = false>
; __device__ __forceinline__ void gemm_phase(PG8_LAS unsigned char* lds, const Gemm g, const Sched& S, const Epi& E) {
;     ...
;             PG8_WAIT_V(8); PG8_WAIT_L(0); PG8_BAR; PG8_MMA(1, 0, At, B0); PG8_MMA(1, 1, At, B1); PG8_BAR; PG8_SCHED;
;             PG8_LDB(B0, 1, 0); PG8_LDB(B1, 1, 1); PG8_SCHED; PG8_LDA(At, 1, 0); PG8_STAGE(PG8_SA(0, 1), a2 + hstep, voffA);
;             PG8_WAIT_V(8); PG8_WAIT_L(0); PG8_BAR; PG8_MMA(0, 0, At, B0); PG8_MMA(0, 1, At, B1); PG8_BAR; PG8_SCHED;
	s_setprio 1
	s_waitcnt lgkmcnt(0)
	v_mfma_f32_16x16x32_bf16 v[60:63], v[128:131], v[176:179], v[60:63]
	v_mfma_f32_16x16x32_bf16 v[56:59], v[136:139], v[176:179], v[56:59]
	v_mfma_f32_16x16x32_bf16 v[44:47], v[128:131], v[192:195], v[44:47]
	v_mfma_f32_16x16x32_bf16 v[40:43], v[136:139], v[192:195], v[40:43]
	v_mfma_f32_16x16x32_bf16 v[28:31], v[128:131], v[204:207], v[28:31]
	v_mfma_f32_16x16x32_bf16 v[24:27], v[136:139], v[204:207], v[24:27]
	v_mfma_f32_16x16x32_bf16 v[12:15], v[128:131], v[212:215], v[12:15]
	v_mfma_f32_16x16x32_bf16 v[8:11], v[136:139], v[212:215], v[8:11]
	v_mfma_f32_16x16x32_bf16 v[60:63], v[132:135], v[180:183], v[60:63]
	v_mfma_f32_16x16x32_bf16 v[56:59], v[140:143], v[180:183], v[56:59]
	v_mfma_f32_16x16x32_bf16 v[44:47], v[132:135], v[196:199], v[44:47]
	v_mfma_f32_16x16x32_bf16 v[40:43], v[140:143], v[196:199], v[40:43]
	v_mfma_f32_16x16x32_bf16 v[28:31], v[132:135], v[208:211], v[28:31]
	v_mfma_f32_16x16x32_bf16 v[24:27], v[140:143], v[208:211], v[24:27]
	v_mfma_f32_16x16x32_bf16 v[12:15], v[132:135], v[216:219], v[12:15]
	v_mfma_f32_16x16x32_bf16 v[8:11], v[140:143], v[216:219], v[8:11]
	v_mfma_f32_16x16x32_bf16 v[52:55], v[144:147], v[176:179], v[52:55]
	v_mfma_f32_16x16x32_bf16 v[48:51], v[168:171], v[176:179], v[48:51]
	v_mfma_f32_16x16x32_bf16 v[36:39], v[144:147], v[192:195], v[36:39]
	v_mfma_f32_16x16x32_bf16 v[32:35], v[168:171], v[192:195], v[32:35]
	v_mfma_f32_16x16x32_bf16 v[20:23], v[144:147], v[204:207], v[20:23]
	v_mfma_f32_16x16x32_bf16 v[16:19], v[168:171], v[204:207], v[16:19]
	v_mfma_f32_16x16x32_bf16 v[4:7], v[144:147], v[212:215], v[4:7]
	v_mfma_f32_16x16x32_bf16 v[0:3], v[168:171], v[212:215], v[0:3]
	v_mfma_f32_16x16x32_bf16 v[52:55], v[148:151], v[180:183], v[52:55]
	v_mfma_f32_16x16x32_bf16 v[48:51], v[172:175], v[180:183], v[48:51]
	v_mfma_f32_16x16x32_bf16 v[36:39], v[148:151], v[196:199], v[36:39]
	v_mfma_f32_16x16x32_bf16 v[32:35], v[172:175], v[196:199], v[32:35]
	v_mfma_f32_16x16x32_bf16 v[20:23], v[148:151], v[208:211], v[20:23]
	v_mfma_f32_16x16x32_bf16 v[16:19], v[172:175], v[208:211], v[16:19]
	v_mfma_f32_16x16x32_bf16 v[4:7], v[148:151], v[216:219], v[4:7]
	v_mfma_f32_16x16x32_bf16 v[0:3], v[172:175], v[216:219], v[0:3]
	s_setprio 0
	s_barrier
	s_add_i32 s44, 0, 0x18000
	s_add_i32 s45, 0, 0x1c000
	v_add_u32_e32 v140, s44, v187
	v_add_u32_e32 v172, s45, v187
	ds_read_b128 v[128:131], v140
	ds_read_b128 v[132:135], v140 offset:1024
	ds_read_b128 v[136:139], v140 offset:2048
	ds_read_b128 v[140:143], v140 offset:3072
	ds_read_b128 v[144:147], v172
	ds_read_b128 v[148:151], v172 offset:1024
	ds_read_b128 v[168:171], v172 offset:2048
	ds_read_b128 v[172:175], v172 offset:3072
	s_add_u32 s18, s24, 0xb0000
	s_addc_u32 s19, s25, 0
	s_mov_b32 m0, s29
	v_lshl_add_u64 v[226:227], s[18:19], 0, v[152:153]
	ds_read_b128 v[176:179], v191 offset:32768
	ds_read_b128 v[180:183], v191 offset:33792
	ds_read_b128 v[192:195], v191 offset:34816
	ds_read_b128 v[196:199], v191 offset:35840
	ds_read_b128 v[204:207], v191 offset:36864
	ds_read_b128 v[208:211], v191 offset:37888
	ds_read_b128 v[212:215], v191 offset:38912
	ds_read_b128 v[216:219], v191 offset:39936
	global_load_lds_dwordx4 v[226:227], off
	v_lshl_add_u64 v[226:227], s[18:19], 0, v[156:157]
	s_mov_b32 m0, s30
	s_nop 0
	global_load_lds_dwordx4 v[226:227], off
	s_waitcnt vmcnt(8)
	s_waitcnt lgkmcnt(0)
	s_barrier
	s_setprio 1
	s_waitcnt lgkmcnt(0)
	v_mfma_f32_16x16x32_bf16 v[124:127], v[128:131], v[176:179], v[124:127]
	v_mfma_f32_16x16x32_bf16 v[120:123], v[136:139], v[176:179], v[120:123]
	v_mfma_f32_16x16x32_bf16 v[108:111], v[128:131], v[192:195], v[108:111]
	v_mfma_f32_16x16x32_bf16 v[104:107], v[136:139], v[192:195], v[104:107]
	v_mfma_f32_16x16x32_bf16 v[92:95], v[128:131], v[204:207], v[92:95]
	v_mfma_f32_16x16x32_bf16 v[88:91], v[136:139], v[204:207], v[88:91]
	v_mfma_f32_16x16x32_bf16 v[76:79], v[128:131], v[212:215], v[76:79]
	v_mfma_f32_16x16x32_bf16 v[72:75], v[136:139], v[212:215], v[72:75]
	v_mfma_f32_16x16x32_bf16 v[124:127], v[132:135], v[180:183], v[124:127]
	v_mfma_f32_16x16x32_bf16 v[120:123], v[140:143], v[180:183], v[120:123]
	v_mfma_f32_16x16x32_bf16 v[108:111], v[132:135], v[196:199], v[108:111]
	v_mfma_f32_16x16x32_bf16 v[104:107], v[140:143], v[196:199], v[104:107]
	v_mfma_f32_16x16x32_bf16 v[92:95], v[132:135], v[208:211], v[92:95]
	v_mfma_f32_16x16x32_bf16 v[88:91], v[140:143], v[208:211], v[88:91]
	v_mfma_f32_16x16x32_bf16 v[76:79], v[132:135], v[216:219], v[76:79]
	v_mfma_f32_16x16x32_bf16 v[72:75], v[140:143], v[216:219], v[72:75]
	v_mfma_f32_16x16x32_bf16 v[116:119], v[144:147], v[176:179], v[116:119]
	v_mfma_f32_16x16x32_bf16 v[112:115], v[168:171], v[176:179], v[112:115]
	v_mfma_f32_16x16x32_bf16 v[100:103], v[144:147], v[192:195], v[100:103]
	v_mfma_f32_16x16x32_bf16 v[96:99], v[168:171], v[192:195], v[96:99]
	v_mfma_f32_16x16x32_bf16 v[84:87], v[144:147], v[204:207], v[84:87]
	v_mfma_f32_16x16x32_bf16 v[80:83], v[168:171], v[204:207], v[80:83]
	v_mfma_f32_16x16x32_bf16 v[68:71], v[144:147], v[212:215], v[68:71]
	v_mfma_f32_16x16x32_bf16 v[64:67], v[168:171], v[212:215], v[64:67]
	v_mfma_f32_16x16x32_bf16 v[116:119], v[148:151], v[180:183], v[116:119]
	v_mfma_f32_16x16x32_bf16 v[112:115], v[172:175], v[180:183], v[112:115]
	v_mfma_f32_16x16x32_bf16 v[100:103], v[148:151], v[196:199], v[100:103]
	v_mfma_f32_16x16x32_bf16 v[96:99], v[172:175], v[196:199], v[96:99]
	v_mfma_f32_16x16x32_bf16 v[84:87], v[148:151], v[208:211], v[84:87]
	v_mfma_f32_16x16x32_bf16 v[80:83], v[172:175], v[208:211], v[80:83]
	v_mfma_f32_16x16x32_bf16 v[68:71], v[148:151], v[216:219], v[68:71]
	v_mfma_f32_16x16x32_bf16 v[64:67], v[172:175], v[216:219], v[64:67]
	s_setprio 0
	s_barrier
; #define PG8_STAGE(bufoff, gbase, voff) do { _Pragma("unroll") for (int _i = 0; _i < 2; ++_i) \
;         __builtin_amdgcn_global_load_lds((const unsigned*)((const char*)(gbase) + (voff)[_i]), (PG8_LAS unsigned*)(lds + (bufoff) + ldsw + _i * 8192), 16, 0, 0); } while (0)
; #define PG8_LDA(dst, b, h) do { _Pragma("unroll") for (int m = 0; m < 4; ++m) _Pragma("unroll") for (int k = 0; k < 2; ++k) dst[m][k] = *(const PG8_LAS bf16x8*)(lds + PG8_SA(b, h) + aoff + m * 2048 + k * 1024); } while (0)
; #define PG8_MMA(ai, bj, At, Bt) do { __builtin_amdgcn_s_setprio(1); _Pragma("unroll") for (int m = 0; m < 4; ++m) _Pragma("unroll") for (int n = 0; n < 2; ++n) _Pragma("unroll") for (int k = 0; k < 2; ++k) \
;         acc[ai][bj][m][n] = __builtin_amdgcn_mfma_f32_16x16x32_bf16(Bt[n][k], At[m][k], acc[ai][bj][m][n], 0, 0, 0); __builtin_amdgcn_s_setprio(0); } while (0)
; #define PG8_WAIT_V(n) asm volatile("s_waitcnt vmcnt(" #n ")" ::: "memory")
; #define PG8_WAIT_L(n) asm volatile("s_waitcnt lgkmcnt(" #n ")" ::: "memory")
; #define PG8_BAR __builtin_amdgcn_s_barrier()
; #define PG8_SCHED __builtin_amdgcn_sched_barrier(0)
; template <class Epi, class Sched, bool ALIGN_EPI = false, bool SP2 = false>
; __device__ __forceinline__ void gemm_phase(PG8_LAS unsigned char* lds, const Gemm g, const Sched& S, const Epi& E) {
;     ...
;             PG8_LDA(At, 1, 1); PG8_STAGE(PG8_SB(1, 0), b3, voffB); PG8_STAGE(PG8_SB(1, 1), b3 + hstep, voffB); PG8_STAGE(PG8_SA(1, 0), a3, voffA);
;             PG8_WAIT_V(8); PG8_WAIT_L(0); PG8_BAR; PG8_MMA(1, 0, At, B0); PG8_MMA(1, 1, At, B1); PG8_BAR; PG8_SCHED;
	s_add_i32 s18, s44, s26
	v_lshl_add_u64 v[184:185], v[184:185], 0, s[12:13]
	s_mov_b32 m0, s18
	ds_read_b128 v[176:179], v191 offset:49152
	ds_read_b128 v[180:183], v191 offset:50176
	ds_read_b128 v[192:195], v191 offset:51200
	ds_read_b128 v[196:199], v191 offset:52224
	ds_read_b128 v[204:207], v191 offset:53248
	ds_read_b128 v[208:211], v191 offset:54272
	ds_read_b128 v[212:215], v191 offset:55296
	ds_read_b128 v[216:219], v191 offset:56320
	global_load_lds_dwordx4 v[184:185], off
	s_add_i32 m0, s18, 0x2000
	s_add_u32 s18, s22, 0xb0080
	v_lshl_add_u64 v[184:185], v[220:221], 0, s[12:13]
	s_addc_u32 s19, s23, 0
	s_add_i32 s22, s45, s26
	global_load_lds_dwordx4 v[184:185], off
	v_lshl_add_u64 v[184:185], s[18:19], 0, v[154:155]
	s_mov_b32 m0, s22
	s_nop 0
	global_load_lds_dwordx4 v[184:185], off
	v_lshl_add_u64 v[184:185], s[18:19], 0, v[158:159]
	s_add_i32 m0, s22, 0x2000
	s_nop 0
	global_load_lds_dwordx4 v[184:185], off
	v_lshl_add_u64 v[184:185], v[222:223], 0, s[12:13]
	s_mov_b32 m0, s33
	s_nop 0
	global_load_lds_dwordx4 v[184:185], off
	v_lshl_add_u64 v[184:185], v[224:225], 0, s[12:13]
	s_mov_b32 m0, s34
	s_nop 0
	global_load_lds_dwordx4 v[184:185], off
	s_waitcnt vmcnt(8)
	s_waitcnt lgkmcnt(0)
	s_barrier
	s_setprio 1
	s_waitcnt lgkmcnt(0)
	v_mfma_f32_16x16x32_bf16 v[60:63], v[128:131], v[176:179], v[60:63]
	v_mfma_f32_16x16x32_bf16 v[56:59], v[136:139], v[176:179], v[56:59]
	v_mfma_f32_16x16x32_bf16 v[44:47], v[128:131], v[192:195], v[44:47]
	v_mfma_f32_16x16x32_bf16 v[40:43], v[136:139], v[192:195], v[40:43]
	v_mfma_f32_16x16x32_bf16 v[28:31], v[128:131], v[204:207], v[28:31]
	v_mfma_f32_16x16x32_bf16 v[24:27], v[136:139], v[204:207], v[24:27]
	v_mfma_f32_16x16x32_bf16 v[12:15], v[128:131], v[212:215], v[12:15]
	v_mfma_f32_16x16x32_bf16 v[8:11], v[136:139], v[212:215], v[8:11]
	v_mfma_f32_16x16x32_bf16 v[60:63], v[132:135], v[180:183], v[60:63]
	v_mfma_f32_16x16x32_bf16 v[56:59], v[140:143], v[180:183], v[56:59]
	v_mfma_f32_16x16x32_bf16 v[44:47], v[132:135], v[196:199], v[44:47]
	v_mfma_f32_16x16x32_bf16 v[40:43], v[140:143], v[196:199], v[40:43]
	v_mfma_f32_16x16x32_bf16 v[28:31], v[132:135], v[208:211], v[28:31]
	v_mfma_f32_16x16x32_bf16 v[24:27], v[140:143], v[208:211], v[24:27]
	v_mfma_f32_16x16x32_bf16 v[12:15], v[132:135], v[216:219], v[12:15]
	v_mfma_f32_16x16x32_bf16 v[8:11], v[140:143], v[216:219], v[8:11]
	v_mfma_f32_16x16x32_bf16 v[52:55], v[144:147], v[176:179], v[52:55]
	v_mfma_f32_16x16x32_bf16 v[48:51], v[168:171], v[176:179], v[48:51]
	v_mfma_f32_16x16x32_bf16 v[36:39], v[144:147], v[192:195], v[36:39]
	v_mfma_f32_16x16x32_bf16 v[32:35], v[168:171], v[192:195], v[32:35]
	v_mfma_f32_16x16x32_bf16 v[20:23], v[144:147], v[204:207], v[20:23]
	v_mfma_f32_16x16x32_bf16 v[16:19], v[168:171], v[204:207], v[16:19]
	v_mfma_f32_16x16x32_bf16 v[4:7], v[144:147], v[212:215], v[4:7]
	v_mfma_f32_16x16x32_bf16 v[0:3], v[168:171], v[212:215], v[0:3]
	v_mfma_f32_16x16x32_bf16 v[52:55], v[148:151], v[180:183], v[52:55]
	v_mfma_f32_16x16x32_bf16 v[48:51], v[172:175], v[180:183], v[48:51]
	v_mfma_f32_16x16x32_bf16 v[36:39], v[148:151], v[196:199], v[36:39]
	v_mfma_f32_16x16x32_bf16 v[32:35], v[172:175], v[196:199], v[32:35]
	v_mfma_f32_16x16x32_bf16 v[20:23], v[148:151], v[208:211], v[20:23]
	v_mfma_f32_16x16x32_bf16 v[16:19], v[172:175], v[208:211], v[16:19]
	v_mfma_f32_16x16x32_bf16 v[4:7], v[148:151], v[216:219], v[4:7]
	v_mfma_f32_16x16x32_bf16 v[0:3], v[172:175], v[216:219], v[0:3]
	s_setprio 0
	s_barrier
	s_add_i32 s43, s43, 2
	s_add_u32 s41, s41, 0x100
	s_addc_u32 s42, s42, 0
	s_cmp_gt_u32 s43, 41
	s_mov_b64 s[18:19], s[20:21]
	s_cbranch_scc0 .LBB0_1335
	s_and_b64 vcc, exec, s[14:15]
	s_cbranch_vccz .LBB0_1338
	s_barrier
